# merged-phase K-loops + peeled first trip per unit (accumulators start from C=0, 128 zero-init v_movs per unit removed)
# speedup vs baseline: 1.0241x; 1.0090x over previous
; #define PG8_STAGE(bufoff, gbase, voff) do { _Pragma("unroll") for (int _i = 0; _i < 2; ++_i) \
;         __builtin_amdgcn_global_load_lds((const unsigned*)((const char*)(gbase) + (voff)[_i]), (PG8_LAS unsigned*)(lds + (bufoff) + ldsw + _i * 8192), 16, 0, 0); } while (0)
; #define PG8_LDA(dst, b, h) do { _Pragma("unroll") for (int m = 0; m < 4; ++m) _Pragma("unroll") for (int k = 0; k < 2; ++k) dst[m][k] = *(const PG8_LAS bf16x8*)(lds + PG8_SA(b, h) + aoff + m * 2048 + k * 1024); } while (0)
; #define PG8_LDB(dst, b, h) do { _Pragma("unroll") for (int n = 0; n < 2; ++n) _Pragma("unroll") for (int k = 0; k < 2; ++k) dst[n][k] = *(const PG8_LAS bf16x8*)(lds + PG8_SB(b, h) + boff + n * 2048 + k * 1024); } while (0)
; #define PG8_MMA(ai, bj, At, Bt) do { __builtin_amdgcn_s_setprio(1); _Pragma("unroll") for (int m = 0; m < 4; ++m) _Pragma("unroll") for (int n = 0; n < 2; ++n) _Pragma("unroll") for (int k = 0; k < 2; ++k) \
;         acc[ai][bj][m][n] = __builtin_amdgcn_mfma_f32_16x16x32_bf16(Bt[n][k], At[m][k], acc[ai][bj][m][n], 0, 0, 0); __builtin_amdgcn_s_setprio(0); } while (0)
; template <class Epi, class Sched>
; __device__ __forceinline__ void gemm_phase(PG8_LAS unsigned char* lds, const Gemm g, const Sched& S, const Epi& E) {
;     ...
;     for (;;) {
;         const bool has_next = S.next(ui + 1, nxt);
;         const char* nA = has_next ? (const char*)g.A + (size_t)nxt.pm * tstep : cA; const char* nB = has_next ? (const char*)g.Bt + (size_t)nxt.pn * tstep : cB;
;         for (int t = 0; t < nt; t += 2) {
;             const bool last = (t == nt - 2);
;             const char* a1 = cA + (size_t)(t + 1) * kstep;
;             const char* a2 = last ? nA : cA + (size_t)(t + 2) * kstep; const char* b2 = last ? nB : cB + (size_t)(t + 2) * kstep;
;             const char* a3 = a2 + kstep; const char* b3 = b2 + kstep;
;             if (last && has_next) S.a_ready(nxt);
;             PG8_LDB(B0, 0, 0); PG8_SCHED; PG8_LDA(At, 0, 0); PG8_STAGE(PG8_SA(1, 1), a1 + hstep, voffA);
;             PG8_WAIT_L(8); PG8_BAR; PG8_WAIT_L(0); PG8_MMA(0, 0, At, B0); PG8_BAR; PG8_SCHED;
;             PG8_LDB(B1, 0, 1); PG8_STAGE(PG8_SB(0, 0), b2, voffB);
;             PG8_BAR; PG8_WAIT_L(0); PG8_MMA(0, 1, At, B1); PG8_BAR;
;             PG8_LDA(At, 0, 1); PG8_STAGE(PG8_SA(0, 0), a2, voffA);
;             PG8_BAR; PG8_WAIT_L(0); PG8_MMA(1, 0, At, B0); PG8_BAR; PG8_SCHED;
.LBB0_194:
	s_ashr_i32 s17, s16, 31
	v_cmp_lt_i64_e32 vcc, s[18:19], v[140:141]
	s_lshl_b64 s[18:19], s[16:17], 19
	s_add_u32 s18, s38, s18
	s_addc_u32 s19, s39, s19
	s_and_b64 s[24:25], vcc, exec
	s_cselect_b32 s17, s19, s29
	s_cselect_b32 s54, s18, s28
	s_ashr_i32 s15, s14, 31
	s_lshl_b64 s[24:25], s[14:15], 19
	s_add_u32 s24, s90, s24
	s_addc_u32 s25, s91, s25
	s_and_b64 s[34:35], vcc, exec
	s_cselect_b32 s15, s25, s31
	s_cselect_b32 s55, s24, s30
	s_add_u32 s28, s28, 0x40080
	s_addc_u32 s29, s29, 0
	s_add_u32 s56, s30, 0x100
	s_addc_u32 s57, s31, 0
	s_mov_b32 s58, -2
	ds_read_b128 v[144:147], v151
	ds_read_b128 v[156:159], v151 offset:1024
	ds_read_b128 v[160:163], v151 offset:2048
	ds_read_b128 v[166:169], v151 offset:3072
	s_add_u32 s30, s28, 0xfffc0080
	s_addc_u32 s31, s29, -1
	s_cmp_eq_u32 s58, 12
	s_cselect_b32 s35, s17, s31
	s_cselect_b32 s34, s54, s30
	s_cselect_b32 s31, s15, s57
	s_cselect_b32 s30, s55, s56
	v_lshl_add_u64 v[174:175], s[28:29], 0, v[136:137]
	s_add_i32 m0, s27, 0xc000
	ds_read_b128 v[170:173], v153
	ds_read_b128 v[182:185], v153 offset:1024
	ds_read_b128 v[190:193], v153 offset:2048
	ds_read_b128 v[194:197], v153 offset:3072
	ds_read_b128 v[198:201], v153 offset:4096
	ds_read_b128 v[202:205], v153 offset:5120
	ds_read_b128 v[206:209], v153 offset:6144
	ds_read_b128 v[210:213], v153 offset:7168
	global_load_lds_dwordx4 v[174:175], off
	v_lshl_add_u64 v[174:175], s[28:29], 0, v[138:139]
	s_add_i32 m0, s27, 0xe000
	s_nop 0
	global_load_lds_dwordx4 v[174:175], off
	s_waitcnt lgkmcnt(8)
	ds_read_b128 v[214:217], v154
	ds_read_b128 v[218:221], v154 offset:1024
	ds_read_b128 v[222:225], v154 offset:2048
	ds_read_b128 v[226:229], v154 offset:3072
	s_waitcnt vmcnt(8) lgkmcnt(0)
	s_barrier
	v_mfma_f32_16x16x32_bf16 v[124:127], v[144:147], v[170:173], 0
	v_mfma_f32_16x16x32_bf16 v[120:123], v[160:163], v[170:173], 0
	v_mfma_f32_16x16x32_bf16 v[108:111], v[144:147], v[190:193], 0
	v_mfma_f32_16x16x32_bf16 v[104:107], v[160:163], v[190:193], 0
	v_mfma_f32_16x16x32_bf16 v[92:95], v[144:147], v[198:201], 0
	v_mfma_f32_16x16x32_bf16 v[88:91], v[160:163], v[198:201], 0
	v_mfma_f32_16x16x32_bf16 v[76:79], v[144:147], v[206:209], 0
	v_mfma_f32_16x16x32_bf16 v[72:75], v[160:163], v[206:209], 0
	v_mfma_f32_16x16x32_bf16 v[124:127], v[156:159], v[182:185], v[124:127]
	v_mfma_f32_16x16x32_bf16 v[120:123], v[166:169], v[182:185], v[120:123]
	v_mfma_f32_16x16x32_bf16 v[108:111], v[156:159], v[194:197], v[108:111]
	v_mfma_f32_16x16x32_bf16 v[104:107], v[166:169], v[194:197], v[104:107]
	v_mfma_f32_16x16x32_bf16 v[92:95], v[156:159], v[202:205], v[92:95]
	v_mfma_f32_16x16x32_bf16 v[88:91], v[166:169], v[202:205], v[88:91]
	v_mfma_f32_16x16x32_bf16 v[76:79], v[156:159], v[210:213], v[76:79]
	v_mfma_f32_16x16x32_bf16 v[72:75], v[166:169], v[210:213], v[72:75]
	v_mfma_f32_16x16x32_bf16 v[116:119], v[214:217], v[170:173], 0
	v_mfma_f32_16x16x32_bf16 v[112:115], v[222:225], v[170:173], 0
	v_mfma_f32_16x16x32_bf16 v[100:103], v[214:217], v[190:193], 0
	v_mfma_f32_16x16x32_bf16 v[96:99], v[222:225], v[190:193], 0
	v_mfma_f32_16x16x32_bf16 v[84:87], v[214:217], v[198:201], 0
	v_mfma_f32_16x16x32_bf16 v[80:83], v[222:225], v[198:201], 0
	v_mfma_f32_16x16x32_bf16 v[68:71], v[214:217], v[206:209], 0
	v_mfma_f32_16x16x32_bf16 v[64:67], v[222:225], v[206:209], 0
	v_mfma_f32_16x16x32_bf16 v[116:119], v[218:221], v[182:185], v[116:119]
	v_mfma_f32_16x16x32_bf16 v[112:115], v[226:229], v[182:185], v[112:115]
	v_mfma_f32_16x16x32_bf16 v[100:103], v[218:221], v[194:197], v[100:103]
	v_mfma_f32_16x16x32_bf16 v[96:99], v[226:229], v[194:197], v[96:99]
	v_mfma_f32_16x16x32_bf16 v[84:87], v[218:221], v[202:205], v[84:87]
	v_mfma_f32_16x16x32_bf16 v[80:83], v[226:229], v[202:205], v[80:83]
	v_mfma_f32_16x16x32_bf16 v[68:71], v[218:221], v[210:213], v[68:71]
	v_mfma_f32_16x16x32_bf16 v[64:67], v[226:229], v[210:213], v[64:67]
	s_barrier
	ds_read_b128 v[170:173], v153 offset:16384
	ds_read_b128 v[182:185], v153 offset:17408
	ds_read_b128 v[190:193], v153 offset:18432
	ds_read_b128 v[194:197], v153 offset:19456
	ds_read_b128 v[198:201], v153 offset:20480
	ds_read_b128 v[202:205], v153 offset:21504
	ds_read_b128 v[206:209], v153 offset:22528
	ds_read_b128 v[210:213], v153 offset:23552
	s_add_i32 s59, s50, s40
	v_lshl_add_u64 v[174:175], s[30:31], 0, v[132:133]
	s_mov_b32 m0, s59
	s_nop 0
	global_load_lds_dwordx4 v[174:175], off
	v_lshl_add_u64 v[178:179], s[30:31], 0, v[128:129]
	s_add_i32 m0, s59, 0x2000
	s_nop 0
	global_load_lds_dwordx4 v[178:179], off
	s_nop 1
	s_mov_b32 m0, s27
	v_lshl_add_u64 v[186:187], s[34:35], 0, v[134:135]
	global_load_lds_dwordx4 v[186:187], off
	v_lshl_add_u64 v[230:231], s[34:35], 0, v[130:131]
	s_mov_b32 m0, s43
	s_nop 0
	global_load_lds_dwordx4 v[230:231], off
	s_add_u32 s60, s30, 0x40000
	s_addc_u32 s61, s31, 0
	s_add_i32 s59, s51, s40
	v_lshl_add_u64 v[246:247], s[60:61], 0, v[132:133]
	s_mov_b32 m0, s59
	s_nop 0
	global_load_lds_dwordx4 v[246:247], off
	v_lshl_add_u64 v[246:247], s[60:61], 0, v[128:129]
	s_add_i32 m0, s59, 0x2000
	s_nop 0
	global_load_lds_dwordx4 v[246:247], off
	s_waitcnt vmcnt(8) lgkmcnt(0)
	s_barrier
; #define PG8_STAGE(bufoff, gbase, voff) do { _Pragma("unroll") for (int _i = 0; _i < 2; ++_i) \
;         __builtin_amdgcn_global_load_lds((const unsigned*)((const char*)(gbase) + (voff)[_i]), (PG8_LAS unsigned*)(lds + (bufoff) + ldsw + _i * 8192), 16, 0, 0); } while (0)
; #define PG8_LDA(dst, b, h) do { _Pragma("unroll") for (int m = 0; m < 4; ++m) _Pragma("unroll") for (int k = 0; k < 2; ++k) dst[m][k] = *(const PG8_LAS bf16x8*)(lds + PG8_SA(b, h) + aoff + m * 2048 + k * 1024); } while (0)
; #define PG8_LDB(dst, b, h) do { _Pragma("unroll") for (int n = 0; n < 2; ++n) _Pragma("unroll") for (int k = 0; k < 2; ++k) dst[n][k] = *(const PG8_LAS bf16x8*)(lds + PG8_SB(b, h) + boff + n * 2048 + k * 1024); } while (0)
; #define PG8_MMA(ai, bj, At, Bt) do { __builtin_amdgcn_s_setprio(1); _Pragma("unroll") for (int m = 0; m < 4; ++m) _Pragma("unroll") for (int n = 0; n < 2; ++n) _Pragma("unroll") for (int k = 0; k < 2; ++k) \
;         acc[ai][bj][m][n] = __builtin_amdgcn_mfma_f32_16x16x32_bf16(Bt[n][k], At[m][k], acc[ai][bj][m][n], 0, 0, 0); __builtin_amdgcn_s_setprio(0); } while (0)
; #define PG8_WAIT_V(n) asm volatile("s_waitcnt vmcnt(" #n ")" ::: "memory")
; #define PG8_WAIT_L(n) asm volatile("s_waitcnt lgkmcnt(" #n ")" ::: "memory")
; #define PG8_BAR __builtin_amdgcn_s_barrier()
; #define PG8_SCHED __builtin_amdgcn_sched_barrier(0)
; template <class Epi, class Sched>
; __device__ __forceinline__ void gemm_phase(PG8_LAS unsigned char* lds, const Gemm g, const Sched& S, const Epi& E) {
;     ...
;             PG8_BAR; PG8_WAIT_L(0); PG8_MMA(1, 0, At, B0); PG8_BAR; PG8_SCHED;
;             PG8_STAGE(PG8_SB(0, 1), b2 + hstep, voffB);
;             PG8_WAIT_V(6); PG8_BAR; PG8_MMA(1, 1, At, B1); PG8_BAR;
;             PG8_LDB(B0, 1, 0); PG8_SCHED; PG8_LDA(At, 1, 0); PG8_STAGE(PG8_SA(0, 1), a2 + hstep, voffA);
;             PG8_WAIT_L(8); PG8_BAR; PG8_WAIT_L(0); PG8_MMA(0, 0, At, B0); PG8_BAR; PG8_SCHED;
;             PG8_LDB(B1, 1, 1); PG8_STAGE(PG8_SB(1, 0), b3, voffB);
;             PG8_BAR; PG8_WAIT_L(0); PG8_MMA(0, 1, At, B1); PG8_BAR;
;             PG8_LDA(At, 1, 1); PG8_STAGE(PG8_SA(1, 0), a3, voffA);
;             PG8_BAR; PG8_WAIT_L(0); PG8_MMA(1, 0, At, B0); PG8_BAR; PG8_SCHED;
	v_mfma_f32_16x16x32_bf16 v[60:63], v[144:147], v[170:173], 0
	v_mfma_f32_16x16x32_bf16 v[56:59], v[160:163], v[170:173], 0
	v_mfma_f32_16x16x32_bf16 v[44:47], v[144:147], v[190:193], 0
	v_mfma_f32_16x16x32_bf16 v[40:43], v[160:163], v[190:193], 0
	v_mfma_f32_16x16x32_bf16 v[28:31], v[144:147], v[198:201], 0
	v_mfma_f32_16x16x32_bf16 v[24:27], v[160:163], v[198:201], 0
	v_mfma_f32_16x16x32_bf16 v[12:15], v[144:147], v[206:209], 0
	v_mfma_f32_16x16x32_bf16 v[8:11], v[160:163], v[206:209], 0
	v_mfma_f32_16x16x32_bf16 v[60:63], v[156:159], v[182:185], v[60:63]
	v_mfma_f32_16x16x32_bf16 v[56:59], v[166:169], v[182:185], v[56:59]
	v_mfma_f32_16x16x32_bf16 v[44:47], v[156:159], v[194:197], v[44:47]
	v_mfma_f32_16x16x32_bf16 v[40:43], v[166:169], v[194:197], v[40:43]
	v_mfma_f32_16x16x32_bf16 v[28:31], v[156:159], v[202:205], v[28:31]
	v_mfma_f32_16x16x32_bf16 v[24:27], v[166:169], v[202:205], v[24:27]
	v_mfma_f32_16x16x32_bf16 v[12:15], v[156:159], v[210:213], v[12:15]
	v_mfma_f32_16x16x32_bf16 v[8:11], v[166:169], v[210:213], v[8:11]
	v_mfma_f32_16x16x32_bf16 v[52:55], v[214:217], v[170:173], 0
	v_mfma_f32_16x16x32_bf16 v[48:51], v[222:225], v[170:173], 0
	v_mfma_f32_16x16x32_bf16 v[36:39], v[214:217], v[190:193], 0
	v_mfma_f32_16x16x32_bf16 v[32:35], v[222:225], v[190:193], 0
	v_mfma_f32_16x16x32_bf16 v[20:23], v[214:217], v[198:201], 0
	v_mfma_f32_16x16x32_bf16 v[16:19], v[222:225], v[198:201], 0
	v_mfma_f32_16x16x32_bf16 v[4:7], v[214:217], v[206:209], 0
	v_mfma_f32_16x16x32_bf16 v[0:3], v[222:225], v[206:209], 0
	v_mfma_f32_16x16x32_bf16 v[52:55], v[218:221], v[182:185], v[52:55]
	v_mfma_f32_16x16x32_bf16 v[48:51], v[226:229], v[182:185], v[48:51]
	v_mfma_f32_16x16x32_bf16 v[36:39], v[218:221], v[194:197], v[36:39]
	v_mfma_f32_16x16x32_bf16 v[32:35], v[226:229], v[194:197], v[32:35]
	v_mfma_f32_16x16x32_bf16 v[20:23], v[218:221], v[202:205], v[20:23]
	v_mfma_f32_16x16x32_bf16 v[16:19], v[226:229], v[202:205], v[16:19]
	v_mfma_f32_16x16x32_bf16 v[4:7], v[218:221], v[210:213], v[4:7]
	v_mfma_f32_16x16x32_bf16 v[0:3], v[226:229], v[210:213], v[0:3]
	s_barrier
	s_add_i32 s59, 0, 0x18000
	v_add_u32_e32 v155, s59, v149
	ds_read_b128 v[144:147], v155
	ds_read_b128 v[156:159], v155 offset:1024
	ds_read_b128 v[160:163], v155 offset:2048
	ds_read_b128 v[166:169], v155 offset:3072
	s_add_u32 s34, s34, 0x40000
	s_addc_u32 s35, s35, 0
	s_mov_b32 m0, s44
	v_lshl_add_u64 v[214:215], s[34:35], 0, v[134:135]
	ds_read_b128 v[170:173], v153 offset:32768
	ds_read_b128 v[182:185], v153 offset:33792
	ds_read_b128 v[190:193], v153 offset:34816
	ds_read_b128 v[194:197], v153 offset:35840
	ds_read_b128 v[198:201], v153 offset:36864
	ds_read_b128 v[202:205], v153 offset:37888
	ds_read_b128 v[206:209], v153 offset:38912
	ds_read_b128 v[210:213], v153 offset:39936
	global_load_lds_dwordx4 v[214:215], off
	v_lshl_add_u64 v[214:215], s[34:35], 0, v[130:131]
	s_mov_b32 m0, s45
	s_nop 0
	global_load_lds_dwordx4 v[214:215], off
	s_add_i32 s34, 0, 0x1c000
	v_add_u32_e32 v155, s34, v149
	s_waitcnt lgkmcnt(8)
	ds_read_b128 v[214:217], v155
	ds_read_b128 v[218:221], v155 offset:1024
	ds_read_b128 v[222:225], v155 offset:2048
	ds_read_b128 v[226:229], v155 offset:3072
	s_waitcnt vmcnt(8) lgkmcnt(0)
	s_barrier
	v_mfma_f32_16x16x32_bf16 v[124:127], v[144:147], v[170:173], v[124:127]
	v_mfma_f32_16x16x32_bf16 v[120:123], v[160:163], v[170:173], v[120:123]
	v_mfma_f32_16x16x32_bf16 v[108:111], v[144:147], v[190:193], v[108:111]
	v_mfma_f32_16x16x32_bf16 v[104:107], v[160:163], v[190:193], v[104:107]
	v_mfma_f32_16x16x32_bf16 v[92:95], v[144:147], v[198:201], v[92:95]
	v_mfma_f32_16x16x32_bf16 v[88:91], v[160:163], v[198:201], v[88:91]
	v_mfma_f32_16x16x32_bf16 v[76:79], v[144:147], v[206:209], v[76:79]
	v_mfma_f32_16x16x32_bf16 v[72:75], v[160:163], v[206:209], v[72:75]
	v_mfma_f32_16x16x32_bf16 v[124:127], v[156:159], v[182:185], v[124:127]
	v_mfma_f32_16x16x32_bf16 v[120:123], v[166:169], v[182:185], v[120:123]
	v_mfma_f32_16x16x32_bf16 v[108:111], v[156:159], v[194:197], v[108:111]
	v_mfma_f32_16x16x32_bf16 v[104:107], v[166:169], v[194:197], v[104:107]
	v_mfma_f32_16x16x32_bf16 v[92:95], v[156:159], v[202:205], v[92:95]
	v_mfma_f32_16x16x32_bf16 v[88:91], v[166:169], v[202:205], v[88:91]
	v_mfma_f32_16x16x32_bf16 v[76:79], v[156:159], v[210:213], v[76:79]
	v_mfma_f32_16x16x32_bf16 v[72:75], v[166:169], v[210:213], v[72:75]
	v_mfma_f32_16x16x32_bf16 v[116:119], v[214:217], v[170:173], v[116:119]
	v_mfma_f32_16x16x32_bf16 v[112:115], v[222:225], v[170:173], v[112:115]
	v_mfma_f32_16x16x32_bf16 v[100:103], v[214:217], v[190:193], v[100:103]
	v_mfma_f32_16x16x32_bf16 v[96:99], v[222:225], v[190:193], v[96:99]
	v_mfma_f32_16x16x32_bf16 v[84:87], v[214:217], v[198:201], v[84:87]
	v_mfma_f32_16x16x32_bf16 v[80:83], v[222:225], v[198:201], v[80:83]
	v_mfma_f32_16x16x32_bf16 v[68:71], v[214:217], v[206:209], v[68:71]
	v_mfma_f32_16x16x32_bf16 v[64:67], v[222:225], v[206:209], v[64:67]
	v_mfma_f32_16x16x32_bf16 v[116:119], v[218:221], v[182:185], v[116:119]
	v_mfma_f32_16x16x32_bf16 v[112:115], v[226:229], v[182:185], v[112:115]
	v_mfma_f32_16x16x32_bf16 v[100:103], v[218:221], v[194:197], v[100:103]
	v_mfma_f32_16x16x32_bf16 v[96:99], v[226:229], v[194:197], v[96:99]
	v_mfma_f32_16x16x32_bf16 v[84:87], v[218:221], v[202:205], v[84:87]
	v_mfma_f32_16x16x32_bf16 v[80:83], v[226:229], v[202:205], v[80:83]
	v_mfma_f32_16x16x32_bf16 v[68:71], v[218:221], v[210:213], v[68:71]
	v_mfma_f32_16x16x32_bf16 v[64:67], v[226:229], v[210:213], v[64:67]
	s_barrier
; #define PG8_STAGE(bufoff, gbase, voff) do { _Pragma("unroll") for (int _i = 0; _i < 2; ++_i) \
;         __builtin_amdgcn_global_load_lds((const unsigned*)((const char*)(gbase) + (voff)[_i]), (PG8_LAS unsigned*)(lds + (bufoff) + ldsw + _i * 8192), 16, 0, 0); } while (0)
; #define PG8_LDA(dst, b, h) do { _Pragma("unroll") for (int m = 0; m < 4; ++m) _Pragma("unroll") for (int k = 0; k < 2; ++k) dst[m][k] = *(const PG8_LAS bf16x8*)(lds + PG8_SA(b, h) + aoff + m * 2048 + k * 1024); } while (0)
; #define PG8_MMA(ai, bj, At, Bt) do { __builtin_amdgcn_s_setprio(1); _Pragma("unroll") for (int m = 0; m < 4; ++m) _Pragma("unroll") for (int n = 0; n < 2; ++n) _Pragma("unroll") for (int k = 0; k < 2; ++k) \
;         acc[ai][bj][m][n] = __builtin_amdgcn_mfma_f32_16x16x32_bf16(Bt[n][k], At[m][k], acc[ai][bj][m][n], 0, 0, 0); __builtin_amdgcn_s_setprio(0); } while (0)
; #define PG8_WAIT_V(n) asm volatile("s_waitcnt vmcnt(" #n ")" ::: "memory")
; #define PG8_WAIT_L(n) asm volatile("s_waitcnt lgkmcnt(" #n ")" ::: "memory")
; #define PG8_BAR __builtin_amdgcn_s_barrier()
; #define PG8_SCHED __builtin_amdgcn_sched_barrier(0)
; template <class Epi, class Sched>
; __device__ __forceinline__ void gemm_phase(PG8_LAS unsigned char* lds, const Gemm g, const Sched& S, const Epi& E) {
;     ...
;             PG8_LDA(At, 1, 1); PG8_STAGE(PG8_SA(1, 0), a3, voffA);
;             PG8_BAR; PG8_WAIT_L(0); PG8_MMA(1, 0, At, B0); PG8_BAR; PG8_SCHED;
;             PG8_STAGE(PG8_SB(1, 1), b3 + hstep, voffB);
;             PG8_WAIT_V(6); PG8_BAR; PG8_MMA(1, 1, At, B1); PG8_BAR;
;         }
	ds_read_b128 v[170:173], v153 offset:49152
	ds_read_b128 v[182:185], v153 offset:50176
	ds_read_b128 v[190:193], v153 offset:51200
	ds_read_b128 v[194:197], v153 offset:52224
	ds_read_b128 v[198:201], v153 offset:53248
	ds_read_b128 v[202:205], v153 offset:54272
	ds_read_b128 v[206:209], v153 offset:55296
	ds_read_b128 v[210:213], v153 offset:56320
	s_add_i32 s35, s59, s40
	v_lshl_add_u64 v[174:175], v[174:175], 0, s[10:11]
	s_mov_b32 m0, s35
	s_nop 0
	global_load_lds_dwordx4 v[174:175], off
	v_lshl_add_u64 v[174:175], v[178:179], 0, s[10:11]
	s_add_i32 m0, s35, 0x2000
	s_nop 0
	global_load_lds_dwordx4 v[174:175], off
	s_nop 1
	s_mov_b32 m0, s47
	v_lshl_add_u64 v[174:175], v[186:187], 0, s[10:11]
	global_load_lds_dwordx4 v[174:175], off
	v_lshl_add_u64 v[174:175], v[230:231], 0, s[10:11]
	s_mov_b32 m0, s48
	s_nop 0
	global_load_lds_dwordx4 v[174:175], off
	s_add_u32 s30, s30, 0x40080
	s_addc_u32 s31, s31, 0
	s_add_i32 s34, s34, s40
	v_lshl_add_u64 v[246:247], s[30:31], 0, v[132:133]
	s_mov_b32 m0, s34
	s_nop 0
	global_load_lds_dwordx4 v[246:247], off
	v_lshl_add_u64 v[246:247], s[30:31], 0, v[128:129]
	s_add_i32 m0, s34, 0x2000
	s_nop 0
	global_load_lds_dwordx4 v[246:247], off
	s_waitcnt vmcnt(8) lgkmcnt(0)
	s_barrier
	v_mfma_f32_16x16x32_bf16 v[60:63], v[144:147], v[170:173], v[60:63]
	v_mfma_f32_16x16x32_bf16 v[56:59], v[160:163], v[170:173], v[56:59]
	v_mfma_f32_16x16x32_bf16 v[44:47], v[144:147], v[190:193], v[44:47]
	v_mfma_f32_16x16x32_bf16 v[40:43], v[160:163], v[190:193], v[40:43]
	v_mfma_f32_16x16x32_bf16 v[28:31], v[144:147], v[198:201], v[28:31]
	v_mfma_f32_16x16x32_bf16 v[24:27], v[160:163], v[198:201], v[24:27]
	v_mfma_f32_16x16x32_bf16 v[12:15], v[144:147], v[206:209], v[12:15]
	v_mfma_f32_16x16x32_bf16 v[8:11], v[160:163], v[206:209], v[8:11]
	v_mfma_f32_16x16x32_bf16 v[60:63], v[156:159], v[182:185], v[60:63]
	v_mfma_f32_16x16x32_bf16 v[56:59], v[166:169], v[182:185], v[56:59]
	v_mfma_f32_16x16x32_bf16 v[44:47], v[156:159], v[194:197], v[44:47]
	v_mfma_f32_16x16x32_bf16 v[40:43], v[166:169], v[194:197], v[40:43]
	v_mfma_f32_16x16x32_bf16 v[28:31], v[156:159], v[202:205], v[28:31]
	v_mfma_f32_16x16x32_bf16 v[24:27], v[166:169], v[202:205], v[24:27]
	v_mfma_f32_16x16x32_bf16 v[12:15], v[156:159], v[210:213], v[12:15]
	v_mfma_f32_16x16x32_bf16 v[8:11], v[166:169], v[210:213], v[8:11]
	v_mfma_f32_16x16x32_bf16 v[52:55], v[214:217], v[170:173], v[52:55]
	v_mfma_f32_16x16x32_bf16 v[48:51], v[222:225], v[170:173], v[48:51]
	v_mfma_f32_16x16x32_bf16 v[36:39], v[214:217], v[190:193], v[36:39]
	v_mfma_f32_16x16x32_bf16 v[32:35], v[222:225], v[190:193], v[32:35]
	v_mfma_f32_16x16x32_bf16 v[20:23], v[214:217], v[198:201], v[20:23]
	v_mfma_f32_16x16x32_bf16 v[16:19], v[222:225], v[198:201], v[16:19]
	v_mfma_f32_16x16x32_bf16 v[4:7], v[214:217], v[206:209], v[4:7]
	v_mfma_f32_16x16x32_bf16 v[0:3], v[222:225], v[206:209], v[0:3]
	v_mfma_f32_16x16x32_bf16 v[52:55], v[218:221], v[182:185], v[52:55]
	v_mfma_f32_16x16x32_bf16 v[48:51], v[226:229], v[182:185], v[48:51]
	v_mfma_f32_16x16x32_bf16 v[36:39], v[218:221], v[194:197], v[36:39]
	v_mfma_f32_16x16x32_bf16 v[32:35], v[226:229], v[194:197], v[32:35]
	v_mfma_f32_16x16x32_bf16 v[20:23], v[218:221], v[202:205], v[20:23]
	v_mfma_f32_16x16x32_bf16 v[16:19], v[226:229], v[202:205], v[16:19]
	v_mfma_f32_16x16x32_bf16 v[4:7], v[218:221], v[210:213], v[4:7]
	v_mfma_f32_16x16x32_bf16 v[0:3], v[226:229], v[210:213], v[0:3]
	s_barrier
	s_add_i32 s58, s58, 2
	s_add_u32 s28, s28, 0x100
	s_addc_u32 s29, s29, 0
	s_add_u32 s56, s56, 0x100
	s_addc_u32 s57, s57, 0
	s_cmp_gt_u32 s58, 13

; #define PG8_STAGE(bufoff, gbase, voff) do { _Pragma("unroll") for (int _i = 0; _i < 2; ++_i) \
;         __builtin_amdgcn_global_load_lds((const unsigned*)((const char*)(gbase) + (voff)[_i]), (PG8_LAS unsigned*)(lds + (bufoff) + ldsw + _i * 8192), 16, 0, 0); } while (0)
; #define PG8_LDA(dst, b, h) do { _Pragma("unroll") for (int m = 0; m < 4; ++m) _Pragma("unroll") for (int k = 0; k < 2; ++k) dst[m][k] = *(const PG8_LAS bf16x8*)(lds + PG8_SA(b, h) + aoff + m * 2048 + k * 1024); } while (0)
; #define PG8_LDB(dst, b, h) do { _Pragma("unroll") for (int n = 0; n < 2; ++n) _Pragma("unroll") for (int k = 0; k < 2; ++k) dst[n][k] = *(const PG8_LAS bf16x8*)(lds + PG8_SB(b, h) + boff + n * 2048 + k * 1024); } while (0)
; #define PG8_WAIT_V(n) asm volatile("s_waitcnt vmcnt(" #n ")" ::: "memory")
; #define PG8_WAIT_L(n) asm volatile("s_waitcnt lgkmcnt(" #n ")" ::: "memory")
; #define PG8_BAR __builtin_amdgcn_s_barrier()
; #define PG8_SCHED __builtin_amdgcn_sched_barrier(0)
; template <class Epi, class Sched>
; __device__ __forceinline__ void gemm_phase(PG8_LAS unsigned char* lds, const Gemm g, const Sched& S, const Epi& E) {
;     ...
;             const bool last = (t == nt - 2);
;             const char* a1 = cA + (size_t)(t + 1) * kstep;
;             const char* a2 = last ? nA : cA + (size_t)(t + 2) * kstep; const char* b2 = last ? nB : cB + (size_t)(t + 2) * kstep;
;             const char* a3 = a2 + kstep; const char* b3 = b2 + kstep;
;             if (last && has_next) S.a_ready(nxt);
;             PG8_LDB(B0, 0, 0); PG8_SCHED; PG8_LDA(At, 0, 0); PG8_STAGE(PG8_SA(1, 1), a1 + hstep, voffA);
;             PG8_WAIT_L(8); PG8_BAR; PG8_WAIT_L(0); PG8_MMA(0, 0, At, B0); PG8_BAR; PG8_SCHED;
;             PG8_LDB(B1, 0, 1); PG8_STAGE(PG8_SB(0, 0), b2, voffB);
;             PG8_BAR; PG8_WAIT_L(0); PG8_MMA(0, 1, At, B1); PG8_BAR;
;             PG8_LDA(At, 0, 1); PG8_STAGE(PG8_SA(0, 0), a2, voffA);
;             PG8_BAR; PG8_WAIT_L(0); PG8_MMA(1, 0, At, B0); PG8_BAR; PG8_SCHED;
;             PG8_STAGE(PG8_SB(0, 1), b2 + hstep, voffB);
;             PG8_WAIT_V(6); PG8_BAR; PG8_MMA(1, 1, At, B1); PG8_BAR;
;     ...
;         for (int a = 0; a < 2; ++a)
; #pragma unroll
;             for (int b = 0; b < 2; ++b)
; #pragma unroll
;                 for (int m = 0; m < 4; ++m)
; #pragma unroll
;                     for (int n = 0; n < 2; ++n) acc[a][b][m][n] = (f32x4){0.f, 0.f, 0.f, 0.f};
.LBB0_285:
	s_add_u32 s55, s24, 0x100
	s_addc_u32 s56, s25, 0
	s_mov_b32 s57, -2
	ds_read_b128 v[154:157], v149
	ds_read_b128 v[158:161], v149 offset:1024
	ds_read_b128 v[166:169], v149 offset:2048
	ds_read_b128 v[170:173], v149 offset:3072
	s_add_u32 s24, s22, 0x100
	s_addc_u32 s25, s23, 0
	s_cmp_eq_u32 s57, 40
	s_cselect_b32 s29, s1, s25
	s_cselect_b32 s28, s0, s24
	s_cselect_b32 s27, s5, s56
	s_cselect_b32 s26, s4, s55
	v_lshl_add_u64 v[144:145], s[22:23], 0, v[136:137]
	s_add_i32 m0, s38, 0xc000
	ds_read_b128 v[182:185], v150
	ds_read_b128 v[190:193], v150 offset:1024
	ds_read_b128 v[194:197], v150 offset:2048
	ds_read_b128 v[198:201], v150 offset:3072
	ds_read_b128 v[202:205], v150 offset:4096
	ds_read_b128 v[206:209], v150 offset:5120
	ds_read_b128 v[210:213], v150 offset:6144
	ds_read_b128 v[214:217], v150 offset:7168
	global_load_lds_dwordx4 v[144:145], off
	v_lshl_add_u64 v[144:145], s[22:23], 0, v[138:139]
	s_add_i32 m0, s38, 0xe000
	s_nop 0
	global_load_lds_dwordx4 v[144:145], off
	s_waitcnt lgkmcnt(8)
	ds_read_b128 v[218:221], v151
	ds_read_b128 v[222:225], v151 offset:1024
	ds_read_b128 v[226:229], v151 offset:2048
	ds_read_b128 v[230:233], v151 offset:3072
	s_waitcnt vmcnt(8) lgkmcnt(0)
	s_barrier
	v_mfma_f32_16x16x32_bf16 v[124:127], v[154:157], v[182:185], 0
	v_mfma_f32_16x16x32_bf16 v[120:123], v[166:169], v[182:185], 0
	v_mfma_f32_16x16x32_bf16 v[108:111], v[154:157], v[194:197], 0
	v_mfma_f32_16x16x32_bf16 v[104:107], v[166:169], v[194:197], 0
	v_mfma_f32_16x16x32_bf16 v[92:95], v[154:157], v[202:205], 0
	v_mfma_f32_16x16x32_bf16 v[88:91], v[166:169], v[202:205], 0
	v_mfma_f32_16x16x32_bf16 v[76:79], v[154:157], v[210:213], 0
	v_mfma_f32_16x16x32_bf16 v[72:75], v[166:169], v[210:213], 0
	v_mfma_f32_16x16x32_bf16 v[124:127], v[158:161], v[190:193], v[124:127]
	v_mfma_f32_16x16x32_bf16 v[120:123], v[170:173], v[190:193], v[120:123]
	v_mfma_f32_16x16x32_bf16 v[108:111], v[158:161], v[198:201], v[108:111]
	v_mfma_f32_16x16x32_bf16 v[104:107], v[170:173], v[198:201], v[104:107]
	v_mfma_f32_16x16x32_bf16 v[92:95], v[158:161], v[206:209], v[92:95]
	v_mfma_f32_16x16x32_bf16 v[88:91], v[170:173], v[206:209], v[88:91]
	v_mfma_f32_16x16x32_bf16 v[76:79], v[158:161], v[214:217], v[76:79]
	v_mfma_f32_16x16x32_bf16 v[72:75], v[170:173], v[214:217], v[72:75]
	v_mfma_f32_16x16x32_bf16 v[116:119], v[218:221], v[182:185], 0
	v_mfma_f32_16x16x32_bf16 v[112:115], v[226:229], v[182:185], 0
	v_mfma_f32_16x16x32_bf16 v[100:103], v[218:221], v[194:197], 0
	v_mfma_f32_16x16x32_bf16 v[96:99], v[226:229], v[194:197], 0
	v_mfma_f32_16x16x32_bf16 v[84:87], v[218:221], v[202:205], 0
	v_mfma_f32_16x16x32_bf16 v[80:83], v[226:229], v[202:205], 0
	v_mfma_f32_16x16x32_bf16 v[68:71], v[218:221], v[210:213], 0
	v_mfma_f32_16x16x32_bf16 v[64:67], v[226:229], v[210:213], 0
	v_mfma_f32_16x16x32_bf16 v[116:119], v[222:225], v[190:193], v[116:119]
	v_mfma_f32_16x16x32_bf16 v[112:115], v[230:233], v[190:193], v[112:115]
	v_mfma_f32_16x16x32_bf16 v[100:103], v[222:225], v[198:201], v[100:103]
	v_mfma_f32_16x16x32_bf16 v[96:99], v[230:233], v[198:201], v[96:99]
	v_mfma_f32_16x16x32_bf16 v[84:87], v[222:225], v[206:209], v[84:87]
	v_mfma_f32_16x16x32_bf16 v[80:83], v[230:233], v[206:209], v[80:83]
	v_mfma_f32_16x16x32_bf16 v[68:71], v[222:225], v[214:217], v[68:71]
	v_mfma_f32_16x16x32_bf16 v[64:67], v[230:233], v[214:217], v[64:67]
	s_barrier
	ds_read_b128 v[182:185], v150 offset:16384
	ds_read_b128 v[190:193], v150 offset:17408
	ds_read_b128 v[194:197], v150 offset:18432
	ds_read_b128 v[198:201], v150 offset:19456
	ds_read_b128 v[202:205], v150 offset:20480
	ds_read_b128 v[206:209], v150 offset:21504
	ds_read_b128 v[210:213], v150 offset:22528
	ds_read_b128 v[214:217], v150 offset:23552
	s_add_i32 s22, s46, s37
	v_lshl_add_u64 v[144:145], s[26:27], 0, v[130:131]
	s_mov_b32 m0, s22
	s_nop 0
	global_load_lds_dwordx4 v[144:145], off
	v_lshl_add_u64 v[162:163], s[26:27], 0, v[134:135]
	s_add_i32 m0, s22, 0x2000
	s_nop 0
	global_load_lds_dwordx4 v[162:163], off
	s_nop 1
	s_mov_b32 m0, s38
	v_lshl_add_u64 v[174:175], s[28:29], 0, v[128:129]
	global_load_lds_dwordx4 v[174:175], off
	v_lshl_add_u64 v[178:179], s[28:29], 0, v[132:133]
	s_mov_b32 m0, s39
	s_nop 0
	global_load_lds_dwordx4 v[178:179], off
	s_add_u32 s22, s26, 0xb0000
	s_addc_u32 s23, s27, 0
	s_add_i32 s58, s47, s37
	v_lshl_add_u64 v[246:247], s[22:23], 0, v[130:131]
	s_mov_b32 m0, s58
	s_nop 0
	global_load_lds_dwordx4 v[246:247], off
	v_lshl_add_u64 v[246:247], s[22:23], 0, v[134:135]
	s_add_i32 m0, s58, 0x2000
	s_nop 0
	global_load_lds_dwordx4 v[246:247], off
	s_waitcnt vmcnt(8) lgkmcnt(0)
	s_barrier
; #define PG8_STAGE(bufoff, gbase, voff) do { _Pragma("unroll") for (int _i = 0; _i < 2; ++_i) \
;         __builtin_amdgcn_global_load_lds((const unsigned*)((const char*)(gbase) + (voff)[_i]), (PG8_LAS unsigned*)(lds + (bufoff) + ldsw + _i * 8192), 16, 0, 0); } while (0)
; #define PG8_LDA(dst, b, h) do { _Pragma("unroll") for (int m = 0; m < 4; ++m) _Pragma("unroll") for (int k = 0; k < 2; ++k) dst[m][k] = *(const PG8_LAS bf16x8*)(lds + PG8_SA(b, h) + aoff + m * 2048 + k * 1024); } while (0)
; #define PG8_LDB(dst, b, h) do { _Pragma("unroll") for (int n = 0; n < 2; ++n) _Pragma("unroll") for (int k = 0; k < 2; ++k) dst[n][k] = *(const PG8_LAS bf16x8*)(lds + PG8_SB(b, h) + boff + n * 2048 + k * 1024); } while (0)
; #define PG8_MMA(ai, bj, At, Bt) do { __builtin_amdgcn_s_setprio(1); _Pragma("unroll") for (int m = 0; m < 4; ++m) _Pragma("unroll") for (int n = 0; n < 2; ++n) _Pragma("unroll") for (int k = 0; k < 2; ++k) \
;         acc[ai][bj][m][n] = __builtin_amdgcn_mfma_f32_16x16x32_bf16(Bt[n][k], At[m][k], acc[ai][bj][m][n], 0, 0, 0); __builtin_amdgcn_s_setprio(0); } while (0)
; #define PG8_WAIT_V(n) asm volatile("s_waitcnt vmcnt(" #n ")" ::: "memory")
; #define PG8_WAIT_L(n) asm volatile("s_waitcnt lgkmcnt(" #n ")" ::: "memory")
; #define PG8_BAR __builtin_amdgcn_s_barrier()
; #define PG8_SCHED __builtin_amdgcn_sched_barrier(0)
; template <class Epi, class Sched>
; __device__ __forceinline__ void gemm_phase(PG8_LAS unsigned char* lds, const Gemm g, const Sched& S, const Epi& E) {
;     ...
;             PG8_BAR; PG8_WAIT_L(0); PG8_MMA(1, 0, At, B0); PG8_BAR; PG8_SCHED;
;             PG8_STAGE(PG8_SB(0, 1), b2 + hstep, voffB);
;             PG8_WAIT_V(6); PG8_BAR; PG8_MMA(1, 1, At, B1); PG8_BAR;
;             PG8_LDB(B0, 1, 0); PG8_SCHED; PG8_LDA(At, 1, 0); PG8_STAGE(PG8_SA(0, 1), a2 + hstep, voffA);
;             PG8_WAIT_L(8); PG8_BAR; PG8_WAIT_L(0); PG8_MMA(0, 0, At, B0); PG8_BAR; PG8_SCHED;
;             PG8_LDB(B1, 1, 1); PG8_STAGE(PG8_SB(1, 0), b3, voffB);
;             PG8_BAR; PG8_WAIT_L(0); PG8_MMA(0, 1, At, B1); PG8_BAR;
	v_mfma_f32_16x16x32_bf16 v[60:63], v[154:157], v[182:185], 0
	v_mfma_f32_16x16x32_bf16 v[56:59], v[166:169], v[182:185], 0
	v_mfma_f32_16x16x32_bf16 v[48:51], v[154:157], v[194:197], 0
	v_mfma_f32_16x16x32_bf16 v[40:43], v[166:169], v[194:197], 0
	v_mfma_f32_16x16x32_bf16 v[32:35], v[154:157], v[202:205], 0
	v_mfma_f32_16x16x32_bf16 v[24:27], v[166:169], v[202:205], 0
	v_mfma_f32_16x16x32_bf16 v[16:19], v[154:157], v[210:213], 0
	v_mfma_f32_16x16x32_bf16 v[8:11], v[166:169], v[210:213], 0
	v_mfma_f32_16x16x32_bf16 v[60:63], v[158:161], v[190:193], v[60:63]
	v_mfma_f32_16x16x32_bf16 v[56:59], v[170:173], v[190:193], v[56:59]
	v_mfma_f32_16x16x32_bf16 v[48:51], v[158:161], v[198:201], v[48:51]
	v_mfma_f32_16x16x32_bf16 v[40:43], v[170:173], v[198:201], v[40:43]
	v_mfma_f32_16x16x32_bf16 v[32:35], v[158:161], v[206:209], v[32:35]
	v_mfma_f32_16x16x32_bf16 v[24:27], v[170:173], v[206:209], v[24:27]
	v_mfma_f32_16x16x32_bf16 v[16:19], v[158:161], v[214:217], v[16:19]
	v_mfma_f32_16x16x32_bf16 v[8:11], v[170:173], v[214:217], v[8:11]
	v_mfma_f32_16x16x32_bf16 v[52:55], v[218:221], v[182:185], 0
	v_mfma_f32_16x16x32_bf16 v[44:47], v[226:229], v[182:185], 0
	v_mfma_f32_16x16x32_bf16 v[36:39], v[218:221], v[194:197], 0
	v_mfma_f32_16x16x32_bf16 v[28:31], v[226:229], v[194:197], 0
	v_mfma_f32_16x16x32_bf16 v[20:23], v[218:221], v[202:205], 0
	v_mfma_f32_16x16x32_bf16 v[12:15], v[226:229], v[202:205], 0
	v_mfma_f32_16x16x32_bf16 v[4:7], v[218:221], v[210:213], 0
	v_mfma_f32_16x16x32_bf16 v[0:3], v[226:229], v[210:213], 0
	v_mfma_f32_16x16x32_bf16 v[52:55], v[222:225], v[190:193], v[52:55]
	v_mfma_f32_16x16x32_bf16 v[44:47], v[230:233], v[190:193], v[44:47]
	v_mfma_f32_16x16x32_bf16 v[36:39], v[222:225], v[198:201], v[36:39]
	v_mfma_f32_16x16x32_bf16 v[28:31], v[230:233], v[198:201], v[28:31]
	v_mfma_f32_16x16x32_bf16 v[20:23], v[222:225], v[206:209], v[20:23]
	v_mfma_f32_16x16x32_bf16 v[12:15], v[230:233], v[206:209], v[12:15]
	v_mfma_f32_16x16x32_bf16 v[4:7], v[222:225], v[214:217], v[4:7]
	v_mfma_f32_16x16x32_bf16 v[0:3], v[230:233], v[214:217], v[0:3]
	s_barrier
	s_add_i32 s58, 0, 0x18000
	v_add_u32_e32 v153, s58, v147
	ds_read_b128 v[154:157], v153
	ds_read_b128 v[158:161], v153 offset:1024
	ds_read_b128 v[166:169], v153 offset:2048
	ds_read_b128 v[170:173], v153 offset:3072
	s_add_u32 s22, s28, 0xb0000
	s_addc_u32 s23, s29, 0
	s_mov_b32 m0, s40
	v_lshl_add_u64 v[186:187], s[22:23], 0, v[128:129]
	ds_read_b128 v[182:185], v150 offset:32768
	ds_read_b128 v[190:193], v150 offset:33792
	ds_read_b128 v[194:197], v150 offset:34816
	ds_read_b128 v[198:201], v150 offset:35840
	ds_read_b128 v[202:205], v150 offset:36864
	ds_read_b128 v[206:209], v150 offset:37888
	ds_read_b128 v[210:213], v150 offset:38912
	ds_read_b128 v[214:217], v150 offset:39936
	global_load_lds_dwordx4 v[186:187], off
	v_lshl_add_u64 v[186:187], s[22:23], 0, v[132:133]
	s_mov_b32 m0, s41
	s_nop 0
	global_load_lds_dwordx4 v[186:187], off
	s_add_i32 s28, 0, 0x1c000
	v_add_u32_e32 v153, s28, v147
	s_waitcnt lgkmcnt(8)
	ds_read_b128 v[218:221], v153
	ds_read_b128 v[222:225], v153 offset:1024
	ds_read_b128 v[226:229], v153 offset:2048
	ds_read_b128 v[230:233], v153 offset:3072
	s_waitcnt vmcnt(8) lgkmcnt(0)
	s_barrier
	v_mfma_f32_16x16x32_bf16 v[124:127], v[154:157], v[182:185], v[124:127]
	v_mfma_f32_16x16x32_bf16 v[120:123], v[166:169], v[182:185], v[120:123]
	v_mfma_f32_16x16x32_bf16 v[108:111], v[154:157], v[194:197], v[108:111]
	v_mfma_f32_16x16x32_bf16 v[104:107], v[166:169], v[194:197], v[104:107]
	v_mfma_f32_16x16x32_bf16 v[92:95], v[154:157], v[202:205], v[92:95]
	v_mfma_f32_16x16x32_bf16 v[88:91], v[166:169], v[202:205], v[88:91]
	v_mfma_f32_16x16x32_bf16 v[76:79], v[154:157], v[210:213], v[76:79]
	v_mfma_f32_16x16x32_bf16 v[72:75], v[166:169], v[210:213], v[72:75]
	v_mfma_f32_16x16x32_bf16 v[124:127], v[158:161], v[190:193], v[124:127]
	v_mfma_f32_16x16x32_bf16 v[120:123], v[170:173], v[190:193], v[120:123]
	v_mfma_f32_16x16x32_bf16 v[108:111], v[158:161], v[198:201], v[108:111]
	v_mfma_f32_16x16x32_bf16 v[104:107], v[170:173], v[198:201], v[104:107]
	v_mfma_f32_16x16x32_bf16 v[92:95], v[158:161], v[206:209], v[92:95]
	v_mfma_f32_16x16x32_bf16 v[88:91], v[170:173], v[206:209], v[88:91]
	v_mfma_f32_16x16x32_bf16 v[76:79], v[158:161], v[214:217], v[76:79]
	v_mfma_f32_16x16x32_bf16 v[72:75], v[170:173], v[214:217], v[72:75]
	v_mfma_f32_16x16x32_bf16 v[116:119], v[218:221], v[182:185], v[116:119]
	v_mfma_f32_16x16x32_bf16 v[112:115], v[226:229], v[182:185], v[112:115]
	v_mfma_f32_16x16x32_bf16 v[100:103], v[218:221], v[194:197], v[100:103]
	v_mfma_f32_16x16x32_bf16 v[96:99], v[226:229], v[194:197], v[96:99]
	v_mfma_f32_16x16x32_bf16 v[84:87], v[218:221], v[202:205], v[84:87]
	v_mfma_f32_16x16x32_bf16 v[80:83], v[226:229], v[202:205], v[80:83]
	v_mfma_f32_16x16x32_bf16 v[68:71], v[218:221], v[210:213], v[68:71]
	v_mfma_f32_16x16x32_bf16 v[64:67], v[226:229], v[210:213], v[64:67]
	v_mfma_f32_16x16x32_bf16 v[116:119], v[222:225], v[190:193], v[116:119]
	v_mfma_f32_16x16x32_bf16 v[112:115], v[230:233], v[190:193], v[112:115]
	v_mfma_f32_16x16x32_bf16 v[100:103], v[222:225], v[198:201], v[100:103]
	v_mfma_f32_16x16x32_bf16 v[96:99], v[230:233], v[198:201], v[96:99]
	v_mfma_f32_16x16x32_bf16 v[84:87], v[222:225], v[206:209], v[84:87]
	v_mfma_f32_16x16x32_bf16 v[80:83], v[230:233], v[206:209], v[80:83]
	v_mfma_f32_16x16x32_bf16 v[68:71], v[222:225], v[214:217], v[68:71]
	v_mfma_f32_16x16x32_bf16 v[64:67], v[230:233], v[214:217], v[64:67]
	s_barrier
; #define PG8_STAGE(bufoff, gbase, voff) do { _Pragma("unroll") for (int _i = 0; _i < 2; ++_i) \
;         __builtin_amdgcn_global_load_lds((const unsigned*)((const char*)(gbase) + (voff)[_i]), (PG8_LAS unsigned*)(lds + (bufoff) + ldsw + _i * 8192), 16, 0, 0); } while (0)
; #define PG8_LDA(dst, b, h) do { _Pragma("unroll") for (int m = 0; m < 4; ++m) _Pragma("unroll") for (int k = 0; k < 2; ++k) dst[m][k] = *(const PG8_LAS bf16x8*)(lds + PG8_SA(b, h) + aoff + m * 2048 + k * 1024); } while (0)
; #define PG8_MMA(ai, bj, At, Bt) do { __builtin_amdgcn_s_setprio(1); _Pragma("unroll") for (int m = 0; m < 4; ++m) _Pragma("unroll") for (int n = 0; n < 2; ++n) _Pragma("unroll") for (int k = 0; k < 2; ++k) \
;         acc[ai][bj][m][n] = __builtin_amdgcn_mfma_f32_16x16x32_bf16(Bt[n][k], At[m][k], acc[ai][bj][m][n], 0, 0, 0); __builtin_amdgcn_s_setprio(0); } while (0)
; #define PG8_WAIT_V(n) asm volatile("s_waitcnt vmcnt(" #n ")" ::: "memory")
; #define PG8_WAIT_L(n) asm volatile("s_waitcnt lgkmcnt(" #n ")" ::: "memory")
; #define PG8_BAR __builtin_amdgcn_s_barrier()
; #define PG8_SCHED __builtin_amdgcn_sched_barrier(0)
; template <class Epi, class Sched>
; __device__ __forceinline__ void gemm_phase(PG8_LAS unsigned char* lds, const Gemm g, const Sched& S, const Epi& E) {
;     ...
;             PG8_LDA(At, 1, 1); PG8_STAGE(PG8_SA(1, 0), a3, voffA);
;             PG8_BAR; PG8_WAIT_L(0); PG8_MMA(1, 0, At, B0); PG8_BAR; PG8_SCHED;
;             PG8_STAGE(PG8_SB(1, 1), b3 + hstep, voffB);
;             PG8_WAIT_V(6); PG8_BAR; PG8_MMA(1, 1, At, B1); PG8_BAR;
;         }
	ds_read_b128 v[182:185], v150 offset:49152
	ds_read_b128 v[190:193], v150 offset:50176
	ds_read_b128 v[194:197], v150 offset:51200
	ds_read_b128 v[198:201], v150 offset:52224
	ds_read_b128 v[202:205], v150 offset:53248
	ds_read_b128 v[206:209], v150 offset:54272
	ds_read_b128 v[210:213], v150 offset:55296
	ds_read_b128 v[214:217], v150 offset:56320
	s_add_i32 s22, s58, s37
	v_lshl_add_u64 v[144:145], v[144:145], 0, s[14:15]
	s_mov_b32 m0, s22
	s_nop 0
	global_load_lds_dwordx4 v[144:145], off
	v_lshl_add_u64 v[144:145], v[162:163], 0, s[14:15]
	s_add_i32 m0, s22, 0x2000
	s_nop 0
	global_load_lds_dwordx4 v[144:145], off
	s_nop 1
	s_mov_b32 m0, s43
	v_lshl_add_u64 v[144:145], v[174:175], 0, s[14:15]
	global_load_lds_dwordx4 v[144:145], off
	v_lshl_add_u64 v[144:145], v[178:179], 0, s[14:15]
	s_mov_b32 m0, s44
	s_nop 0
	global_load_lds_dwordx4 v[144:145], off
	s_add_u32 s22, s26, 0xb0080
	s_addc_u32 s23, s27, 0
	s_add_i32 s26, s28, s37
	v_lshl_add_u64 v[144:145], s[22:23], 0, v[130:131]
	s_mov_b32 m0, s26
	s_nop 0
	global_load_lds_dwordx4 v[144:145], off
	v_lshl_add_u64 v[144:145], s[22:23], 0, v[134:135]
	s_add_i32 m0, s26, 0x2000
	s_nop 0
	global_load_lds_dwordx4 v[144:145], off
	s_waitcnt vmcnt(8) lgkmcnt(0)
	s_barrier
	v_mfma_f32_16x16x32_bf16 v[60:63], v[154:157], v[182:185], v[60:63]
	v_mfma_f32_16x16x32_bf16 v[56:59], v[166:169], v[182:185], v[56:59]
	v_mfma_f32_16x16x32_bf16 v[48:51], v[154:157], v[194:197], v[48:51]
	v_mfma_f32_16x16x32_bf16 v[40:43], v[166:169], v[194:197], v[40:43]
	v_mfma_f32_16x16x32_bf16 v[32:35], v[154:157], v[202:205], v[32:35]
	v_mfma_f32_16x16x32_bf16 v[24:27], v[166:169], v[202:205], v[24:27]
	v_mfma_f32_16x16x32_bf16 v[16:19], v[154:157], v[210:213], v[16:19]
	v_mfma_f32_16x16x32_bf16 v[8:11], v[166:169], v[210:213], v[8:11]
	v_mfma_f32_16x16x32_bf16 v[60:63], v[158:161], v[190:193], v[60:63]
	v_mfma_f32_16x16x32_bf16 v[56:59], v[170:173], v[190:193], v[56:59]
	v_mfma_f32_16x16x32_bf16 v[48:51], v[158:161], v[198:201], v[48:51]
	v_mfma_f32_16x16x32_bf16 v[40:43], v[170:173], v[198:201], v[40:43]
	v_mfma_f32_16x16x32_bf16 v[32:35], v[158:161], v[206:209], v[32:35]
	v_mfma_f32_16x16x32_bf16 v[24:27], v[170:173], v[206:209], v[24:27]
	v_mfma_f32_16x16x32_bf16 v[16:19], v[158:161], v[214:217], v[16:19]
	v_mfma_f32_16x16x32_bf16 v[8:11], v[170:173], v[214:217], v[8:11]
	v_mfma_f32_16x16x32_bf16 v[52:55], v[218:221], v[182:185], v[52:55]
	v_mfma_f32_16x16x32_bf16 v[44:47], v[226:229], v[182:185], v[44:47]
	v_mfma_f32_16x16x32_bf16 v[36:39], v[218:221], v[194:197], v[36:39]
	v_mfma_f32_16x16x32_bf16 v[28:31], v[226:229], v[194:197], v[28:31]
	v_mfma_f32_16x16x32_bf16 v[20:23], v[218:221], v[202:205], v[20:23]
	v_mfma_f32_16x16x32_bf16 v[12:15], v[226:229], v[202:205], v[12:15]
	v_mfma_f32_16x16x32_bf16 v[4:7], v[218:221], v[210:213], v[4:7]
	v_mfma_f32_16x16x32_bf16 v[0:3], v[226:229], v[210:213], v[0:3]
	v_mfma_f32_16x16x32_bf16 v[52:55], v[222:225], v[190:193], v[52:55]
	v_mfma_f32_16x16x32_bf16 v[44:47], v[230:233], v[190:193], v[44:47]
	v_mfma_f32_16x16x32_bf16 v[36:39], v[222:225], v[198:201], v[36:39]
	v_mfma_f32_16x16x32_bf16 v[28:31], v[230:233], v[198:201], v[28:31]
	v_mfma_f32_16x16x32_bf16 v[20:23], v[222:225], v[206:209], v[20:23]
	v_mfma_f32_16x16x32_bf16 v[12:15], v[230:233], v[206:209], v[12:15]
	v_mfma_f32_16x16x32_bf16 v[4:7], v[222:225], v[214:217], v[4:7]
	v_mfma_f32_16x16x32_bf16 v[0:3], v[230:233], v[214:217], v[0:3]
	s_barrier
	s_add_i32 s57, s57, 2
	s_add_u32 s55, s55, 0x100
	s_addc_u32 s56, s56, 0
	s_cmp_gt_u32 s57, 41
	s_mov_b64 s[22:23], s[24:25]

; #define PG8_STAGE(bufoff, gbase, voff) do { _Pragma("unroll") for (int _i = 0; _i < 2; ++_i) \
;         __builtin_amdgcn_global_load_lds((const unsigned*)((const char*)(gbase) + (voff)[_i]), (PG8_LAS unsigned*)(lds + (bufoff) + ldsw + _i * 8192), 16, 0, 0); } while (0)
; #define PG8_LDA(dst, b, h) do { _Pragma("unroll") for (int m = 0; m < 4; ++m) _Pragma("unroll") for (int k = 0; k < 2; ++k) dst[m][k] = *(const PG8_LAS bf16x8*)(lds + PG8_SA(b, h) + aoff + m * 2048 + k * 1024); } while (0)
; #define PG8_LDB(dst, b, h) do { _Pragma("unroll") for (int n = 0; n < 2; ++n) _Pragma("unroll") for (int k = 0; k < 2; ++k) dst[n][k] = *(const PG8_LAS bf16x8*)(lds + PG8_SB(b, h) + boff + n * 2048 + k * 1024); } while (0)
; template <class Epi, class Sched>
; __device__ __forceinline__ void gemm_phase(PG8_LAS unsigned char* lds, const Gemm g, const Sched& S, const Epi& E) {
;     ...
;         const bool has_next = S.next(ui + 1, nxt);
;         const char* nA = has_next ? (const char*)g.A + (size_t)nxt.pm * tstep : cA; const char* nB = has_next ? (const char*)g.Bt + (size_t)nxt.pn * tstep : cB;
;         for (int t = 0; t < nt; t += 2) {
;             const bool last = (t == nt - 2);
;             const char* a1 = cA + (size_t)(t + 1) * kstep;
;             const char* a2 = last ? nA : cA + (size_t)(t + 2) * kstep; const char* b2 = last ? nB : cB + (size_t)(t + 2) * kstep;
;             const char* a3 = a2 + kstep; const char* b3 = b2 + kstep;
;             if (last && has_next) S.a_ready(nxt);
;             PG8_LDB(B0, 0, 0); PG8_SCHED; PG8_LDA(At, 0, 0); PG8_STAGE(PG8_SA(1, 1), a1 + hstep, voffA);
;             PG8_WAIT_L(8); PG8_BAR; PG8_WAIT_L(0); PG8_MMA(0, 0, At, B0); PG8_BAR; PG8_SCHED;
;             PG8_LDB(B1, 0, 1); PG8_STAGE(PG8_SB(0, 0), b2, voffB);
;             PG8_BAR; PG8_WAIT_L(0); PG8_MMA(0, 1, At, B1); PG8_BAR;
;             PG8_LDA(At, 0, 1); PG8_STAGE(PG8_SA(0, 0), a2, voffA);
;             PG8_BAR; PG8_WAIT_L(0); PG8_MMA(1, 0, At, B0); PG8_BAR; PG8_SCHED;
;             PG8_STAGE(PG8_SB(0, 1), b2 + hstep, voffB);
;             PG8_WAIT_V(6); PG8_BAR; PG8_MMA(1, 1, At, B1); PG8_BAR;
;     ...
;         for (int a = 0; a < 2; ++a)
; #pragma unroll
;             for (int b = 0; b < 2; ++b)
; #pragma unroll
;                 for (int m = 0; m < 4; ++m)
; #pragma unroll
;                     for (int n = 0; n < 2; ++n) acc[a][b][m][n] = (f32x4){0.f, 0.f, 0.f, 0.f};
.LBB0_415:
	s_ashr_i32 s21, s20, 31
	v_cmp_lt_i64_e32 vcc, s[22:23], v[170:171]
	s_lshl_b64 s[22:23], s[20:21], 19
	s_add_u32 s22, s31, s22
	s_addc_u32 s23, s34, s23
	s_and_b64 s[24:25], vcc, exec
	s_cselect_b32 s7, s23, s1
	s_cselect_b32 s10, s22, s0
	s_ashr_i32 s19, s18, 31
	s_lshl_b64 s[24:25], s[18:19], 19
	s_add_u32 s24, s8, s24
	s_addc_u32 s25, s9, s25
	s_and_b64 s[28:29], vcc, exec
	s_cselect_b32 s19, s25, s5
	s_cselect_b32 s21, s24, s4
	s_add_u32 s0, s0, 0x40080
	s_addc_u32 s1, s1, 0
	s_add_u32 s51, s4, 0x100
	s_addc_u32 s52, s5, 0
	s_mov_b32 s53, -2
	ds_read_b128 v[24:27], v186
	ds_read_b128 v[28:31], v186 offset:1024
	ds_read_b128 v[40:43], v186 offset:2048
	ds_read_b128 v[44:47], v186 offset:3072
	s_add_u32 s4, s0, 0xfffc0080
	s_addc_u32 s5, s1, -1
	s_cmp_eq_u32 s53, 12
	s_cselect_b32 s29, s7, s5
	s_cselect_b32 s28, s10, s4
	s_cselect_b32 s5, s19, s52
	s_cselect_b32 s4, s21, s51
	v_lshl_add_u64 v[174:175], s[0:1], 0, v[166:167]
	s_add_i32 m0, s27, 0xc000
	ds_read_b128 v[144:147], v187
	ds_read_b128 v[148:151], v187 offset:1024
	ds_read_b128 v[182:185], v187 offset:2048
	ds_read_b128 v[192:195], v187 offset:3072
	ds_read_b128 v[196:199], v187 offset:4096
	ds_read_b128 v[200:203], v187 offset:5120
	ds_read_b128 v[204:207], v187 offset:6144
	ds_read_b128 v[208:211], v187 offset:7168
	global_load_lds_dwordx4 v[174:175], off
	v_lshl_add_u64 v[174:175], s[0:1], 0, v[168:169]
	s_add_i32 m0, s27, 0xe000
	s_nop 0
	global_load_lds_dwordx4 v[174:175], off
	s_waitcnt lgkmcnt(8)
	ds_read_b128 v[212:215], v189
	ds_read_b128 v[216:219], v189 offset:1024
	ds_read_b128 v[220:223], v189 offset:2048
	ds_read_b128 v[224:227], v189 offset:3072
	s_waitcnt vmcnt(8) lgkmcnt(0)
	s_barrier
	v_mfma_f32_16x16x32_bf16 v[140:143], v[24:27], v[144:147], 0
	v_mfma_f32_16x16x32_bf16 v[136:139], v[40:43], v[144:147], 0
	v_mfma_f32_16x16x32_bf16 v[124:127], v[24:27], v[182:185], 0
	v_mfma_f32_16x16x32_bf16 v[120:123], v[40:43], v[182:185], 0
	v_mfma_f32_16x16x32_bf16 v[108:111], v[24:27], v[196:199], 0
	v_mfma_f32_16x16x32_bf16 v[104:107], v[40:43], v[196:199], 0
	v_mfma_f32_16x16x32_bf16 v[92:95], v[24:27], v[204:207], 0
	v_mfma_f32_16x16x32_bf16 v[88:91], v[40:43], v[204:207], 0
	v_mfma_f32_16x16x32_bf16 v[140:143], v[28:31], v[148:151], v[140:143]
	v_mfma_f32_16x16x32_bf16 v[136:139], v[44:47], v[148:151], v[136:139]
	v_mfma_f32_16x16x32_bf16 v[124:127], v[28:31], v[192:195], v[124:127]
	v_mfma_f32_16x16x32_bf16 v[120:123], v[44:47], v[192:195], v[120:123]
	v_mfma_f32_16x16x32_bf16 v[108:111], v[28:31], v[200:203], v[108:111]
	v_mfma_f32_16x16x32_bf16 v[104:107], v[44:47], v[200:203], v[104:107]
	v_mfma_f32_16x16x32_bf16 v[92:95], v[28:31], v[208:211], v[92:95]
	v_mfma_f32_16x16x32_bf16 v[88:91], v[44:47], v[208:211], v[88:91]
	v_mfma_f32_16x16x32_bf16 v[132:135], v[212:215], v[144:147], 0
	v_mfma_f32_16x16x32_bf16 v[128:131], v[220:223], v[144:147], 0
	v_mfma_f32_16x16x32_bf16 v[116:119], v[212:215], v[182:185], 0
	v_mfma_f32_16x16x32_bf16 v[112:115], v[220:223], v[182:185], 0
	v_mfma_f32_16x16x32_bf16 v[100:103], v[212:215], v[196:199], 0
	v_mfma_f32_16x16x32_bf16 v[96:99], v[220:223], v[196:199], 0
	v_mfma_f32_16x16x32_bf16 v[84:87], v[212:215], v[204:207], 0
	v_mfma_f32_16x16x32_bf16 v[80:83], v[220:223], v[204:207], 0
	v_mfma_f32_16x16x32_bf16 v[132:135], v[216:219], v[148:151], v[132:135]
	v_mfma_f32_16x16x32_bf16 v[128:131], v[224:227], v[148:151], v[128:131]
	v_mfma_f32_16x16x32_bf16 v[116:119], v[216:219], v[192:195], v[116:119]
	v_mfma_f32_16x16x32_bf16 v[112:115], v[224:227], v[192:195], v[112:115]
	v_mfma_f32_16x16x32_bf16 v[100:103], v[216:219], v[200:203], v[100:103]
	v_mfma_f32_16x16x32_bf16 v[96:99], v[224:227], v[200:203], v[96:99]
	v_mfma_f32_16x16x32_bf16 v[84:87], v[216:219], v[208:211], v[84:87]
	v_mfma_f32_16x16x32_bf16 v[80:83], v[224:227], v[208:211], v[80:83]
	s_barrier
	ds_read_b128 v[144:147], v187 offset:16384
	ds_read_b128 v[148:151], v187 offset:17408
	ds_read_b128 v[182:185], v187 offset:18432
	ds_read_b128 v[192:195], v187 offset:19456
	ds_read_b128 v[196:199], v187 offset:20480
	ds_read_b128 v[200:203], v187 offset:21504
	ds_read_b128 v[204:207], v187 offset:22528
	ds_read_b128 v[208:211], v187 offset:23552
	s_add_i32 s54, s43, s35
	v_lshl_add_u64 v[174:175], s[4:5], 0, v[156:157]
	s_mov_b32 m0, s54
	s_nop 0
	global_load_lds_dwordx4 v[174:175], off
	v_lshl_add_u64 v[228:229], s[4:5], 0, v[160:161]
	s_add_i32 m0, s54, 0x2000
	s_nop 0
	global_load_lds_dwordx4 v[228:229], off
	s_nop 1
	s_mov_b32 m0, s27
	v_lshl_add_u64 v[230:231], s[28:29], 0, v[154:155]
	global_load_lds_dwordx4 v[230:231], off
	v_lshl_add_u64 v[232:233], s[28:29], 0, v[158:159]
	s_mov_b32 m0, s36
	s_nop 0
	global_load_lds_dwordx4 v[232:233], off
	s_add_u32 s54, s4, 0x40000
	s_addc_u32 s55, s5, 0
	s_add_i32 s56, s44, s35
	v_lshl_add_u64 v[246:247], s[54:55], 0, v[156:157]
	s_mov_b32 m0, s56
	s_nop 0
	global_load_lds_dwordx4 v[246:247], off
	v_lshl_add_u64 v[246:247], s[54:55], 0, v[160:161]
	s_add_i32 m0, s56, 0x2000
	s_nop 0
	global_load_lds_dwordx4 v[246:247], off
	s_waitcnt vmcnt(8) lgkmcnt(0)
	s_barrier
; #define PG8_STAGE(bufoff, gbase, voff) do { _Pragma("unroll") for (int _i = 0; _i < 2; ++_i) \
;         __builtin_amdgcn_global_load_lds((const unsigned*)((const char*)(gbase) + (voff)[_i]), (PG8_LAS unsigned*)(lds + (bufoff) + ldsw + _i * 8192), 16, 0, 0); } while (0)
; #define PG8_LDA(dst, b, h) do { _Pragma("unroll") for (int m = 0; m < 4; ++m) _Pragma("unroll") for (int k = 0; k < 2; ++k) dst[m][k] = *(const PG8_LAS bf16x8*)(lds + PG8_SA(b, h) + aoff + m * 2048 + k * 1024); } while (0)
; #define PG8_LDB(dst, b, h) do { _Pragma("unroll") for (int n = 0; n < 2; ++n) _Pragma("unroll") for (int k = 0; k < 2; ++k) dst[n][k] = *(const PG8_LAS bf16x8*)(lds + PG8_SB(b, h) + boff + n * 2048 + k * 1024); } while (0)
; #define PG8_MMA(ai, bj, At, Bt) do { __builtin_amdgcn_s_setprio(1); _Pragma("unroll") for (int m = 0; m < 4; ++m) _Pragma("unroll") for (int n = 0; n < 2; ++n) _Pragma("unroll") for (int k = 0; k < 2; ++k) \
;         acc[ai][bj][m][n] = __builtin_amdgcn_mfma_f32_16x16x32_bf16(Bt[n][k], At[m][k], acc[ai][bj][m][n], 0, 0, 0); __builtin_amdgcn_s_setprio(0); } while (0)
; #define PG8_WAIT_V(n) asm volatile("s_waitcnt vmcnt(" #n ")" ::: "memory")
; #define PG8_WAIT_L(n) asm volatile("s_waitcnt lgkmcnt(" #n ")" ::: "memory")
; #define PG8_BAR __builtin_amdgcn_s_barrier()
; #define PG8_SCHED __builtin_amdgcn_sched_barrier(0)
; template <class Epi, class Sched>
; __device__ __forceinline__ void gemm_phase(PG8_LAS unsigned char* lds, const Gemm g, const Sched& S, const Epi& E) {
;     ...
;             PG8_BAR; PG8_WAIT_L(0); PG8_MMA(1, 0, At, B0); PG8_BAR; PG8_SCHED;
;             PG8_STAGE(PG8_SB(0, 1), b2 + hstep, voffB);
;             PG8_WAIT_V(6); PG8_BAR; PG8_MMA(1, 1, At, B1); PG8_BAR;
;             PG8_LDB(B0, 1, 0); PG8_SCHED; PG8_LDA(At, 1, 0); PG8_STAGE(PG8_SA(0, 1), a2 + hstep, voffA);
;             PG8_WAIT_L(8); PG8_BAR; PG8_WAIT_L(0); PG8_MMA(0, 0, At, B0); PG8_BAR; PG8_SCHED;
;             PG8_LDB(B1, 1, 1); PG8_STAGE(PG8_SB(1, 0), b3, voffB);
;             PG8_BAR; PG8_WAIT_L(0); PG8_MMA(0, 1, At, B1); PG8_BAR;
	v_mfma_f32_16x16x32_bf16 v[76:79], v[24:27], v[144:147], 0
	v_mfma_f32_16x16x32_bf16 v[72:75], v[40:43], v[144:147], 0
	v_mfma_f32_16x16x32_bf16 v[60:63], v[24:27], v[182:185], 0
	v_mfma_f32_16x16x32_bf16 v[56:59], v[40:43], v[182:185], 0
	v_mfma_f32_16x16x32_bf16 v[36:39], v[24:27], v[196:199], 0
	v_mfma_f32_16x16x32_bf16 v[32:35], v[40:43], v[196:199], 0
	v_mfma_f32_16x16x32_bf16 v[12:15], v[24:27], v[204:207], 0
	v_mfma_f32_16x16x32_bf16 v[8:11], v[40:43], v[204:207], 0
	v_mfma_f32_16x16x32_bf16 v[76:79], v[28:31], v[148:151], v[76:79]
	v_mfma_f32_16x16x32_bf16 v[72:75], v[44:47], v[148:151], v[72:75]
	v_mfma_f32_16x16x32_bf16 v[60:63], v[28:31], v[192:195], v[60:63]
	v_mfma_f32_16x16x32_bf16 v[56:59], v[44:47], v[192:195], v[56:59]
	v_mfma_f32_16x16x32_bf16 v[36:39], v[28:31], v[200:203], v[36:39]
	v_mfma_f32_16x16x32_bf16 v[32:35], v[44:47], v[200:203], v[32:35]
	v_mfma_f32_16x16x32_bf16 v[12:15], v[28:31], v[208:211], v[12:15]
	v_mfma_f32_16x16x32_bf16 v[8:11], v[44:47], v[208:211], v[8:11]
	v_mfma_f32_16x16x32_bf16 v[20:23], v[212:215], v[196:199], 0
	v_mfma_f32_16x16x32_bf16 v[16:19], v[220:223], v[196:199], 0
	v_mfma_f32_16x16x32_bf16 v[4:7], v[212:215], v[204:207], 0
	v_mfma_f32_16x16x32_bf16 v[0:3], v[220:223], v[204:207], 0
	v_mfma_f32_16x16x32_bf16 v[24:27], v[212:215], v[144:147], 0
	v_mfma_f32_16x16x32_bf16 v[28:31], v[220:223], v[144:147], 0
	v_mfma_f32_16x16x32_bf16 v[40:43], v[212:215], v[182:185], 0
	v_mfma_f32_16x16x32_bf16 v[44:47], v[220:223], v[182:185], 0
	v_mfma_f32_16x16x32_bf16 v[20:23], v[216:219], v[200:203], v[20:23]
	v_mfma_f32_16x16x32_bf16 v[16:19], v[224:227], v[200:203], v[16:19]
	v_mfma_f32_16x16x32_bf16 v[4:7], v[216:219], v[208:211], v[4:7]
	v_mfma_f32_16x16x32_bf16 v[0:3], v[224:227], v[208:211], v[0:3]
	v_mfma_f32_16x16x32_bf16 v[24:27], v[216:219], v[148:151], v[24:27]
	v_mfma_f32_16x16x32_bf16 v[28:31], v[224:227], v[148:151], v[28:31]
	v_mfma_f32_16x16x32_bf16 v[40:43], v[216:219], v[192:195], v[40:43]
	v_mfma_f32_16x16x32_bf16 v[44:47], v[224:227], v[192:195], v[44:47]
	s_barrier
	s_add_i32 s54, 0, 0x18000
	v_add_u32_e32 v68, s54, v179
	ds_read_b128 v[48:51], v68
	ds_read_b128 v[52:55], v68 offset:1024
	ds_read_b128 v[64:67], v68 offset:2048
	ds_read_b128 v[68:71], v68 offset:3072
	s_add_u32 s28, s28, 0x40000
	s_addc_u32 s29, s29, 0
	s_mov_b32 m0, s37
	v_lshl_add_u64 v[212:213], s[28:29], 0, v[154:155]
	ds_read_b128 v[144:147], v187 offset:32768
	ds_read_b128 v[148:151], v187 offset:33792
	ds_read_b128 v[182:185], v187 offset:34816
	ds_read_b128 v[192:195], v187 offset:35840
	ds_read_b128 v[196:199], v187 offset:36864
	ds_read_b128 v[200:203], v187 offset:37888
	ds_read_b128 v[204:207], v187 offset:38912
	ds_read_b128 v[208:211], v187 offset:39936
	global_load_lds_dwordx4 v[212:213], off
	v_lshl_add_u64 v[212:213], s[28:29], 0, v[158:159]
	s_mov_b32 m0, s38
	s_nop 0
	global_load_lds_dwordx4 v[212:213], off
	s_add_i32 s28, 0, 0x1c000
	v_add_u32_e32 v162, s28, v179
	s_waitcnt lgkmcnt(8)
	ds_read_b128 v[212:215], v162
	ds_read_b128 v[216:219], v162 offset:1024
	ds_read_b128 v[220:223], v162 offset:2048
	ds_read_b128 v[224:227], v162 offset:3072
	s_waitcnt vmcnt(8) lgkmcnt(0)
	s_barrier
	v_mfma_f32_16x16x32_bf16 v[140:143], v[48:51], v[144:147], v[140:143]
	v_mfma_f32_16x16x32_bf16 v[136:139], v[64:67], v[144:147], v[136:139]
	v_mfma_f32_16x16x32_bf16 v[124:127], v[48:51], v[182:185], v[124:127]
	v_mfma_f32_16x16x32_bf16 v[120:123], v[64:67], v[182:185], v[120:123]
	v_mfma_f32_16x16x32_bf16 v[108:111], v[48:51], v[196:199], v[108:111]
	v_mfma_f32_16x16x32_bf16 v[104:107], v[64:67], v[196:199], v[104:107]
	v_mfma_f32_16x16x32_bf16 v[92:95], v[48:51], v[204:207], v[92:95]
	v_mfma_f32_16x16x32_bf16 v[88:91], v[64:67], v[204:207], v[88:91]
	v_mfma_f32_16x16x32_bf16 v[140:143], v[52:55], v[148:151], v[140:143]
	v_mfma_f32_16x16x32_bf16 v[136:139], v[68:71], v[148:151], v[136:139]
	v_mfma_f32_16x16x32_bf16 v[124:127], v[52:55], v[192:195], v[124:127]
	v_mfma_f32_16x16x32_bf16 v[120:123], v[68:71], v[192:195], v[120:123]
	v_mfma_f32_16x16x32_bf16 v[108:111], v[52:55], v[200:203], v[108:111]
	v_mfma_f32_16x16x32_bf16 v[104:107], v[68:71], v[200:203], v[104:107]
	v_mfma_f32_16x16x32_bf16 v[92:95], v[52:55], v[208:211], v[92:95]
	v_mfma_f32_16x16x32_bf16 v[88:91], v[68:71], v[208:211], v[88:91]
	v_mfma_f32_16x16x32_bf16 v[132:135], v[212:215], v[144:147], v[132:135]
	v_mfma_f32_16x16x32_bf16 v[128:131], v[220:223], v[144:147], v[128:131]
	v_mfma_f32_16x16x32_bf16 v[116:119], v[212:215], v[182:185], v[116:119]
	v_mfma_f32_16x16x32_bf16 v[112:115], v[220:223], v[182:185], v[112:115]
	v_mfma_f32_16x16x32_bf16 v[100:103], v[212:215], v[196:199], v[100:103]
	v_mfma_f32_16x16x32_bf16 v[96:99], v[220:223], v[196:199], v[96:99]
	v_mfma_f32_16x16x32_bf16 v[84:87], v[212:215], v[204:207], v[84:87]
	v_mfma_f32_16x16x32_bf16 v[80:83], v[220:223], v[204:207], v[80:83]
	v_mfma_f32_16x16x32_bf16 v[132:135], v[216:219], v[148:151], v[132:135]
	v_mfma_f32_16x16x32_bf16 v[128:131], v[224:227], v[148:151], v[128:131]
	v_mfma_f32_16x16x32_bf16 v[116:119], v[216:219], v[192:195], v[116:119]
	v_mfma_f32_16x16x32_bf16 v[112:115], v[224:227], v[192:195], v[112:115]
	v_mfma_f32_16x16x32_bf16 v[100:103], v[216:219], v[200:203], v[100:103]
	v_mfma_f32_16x16x32_bf16 v[96:99], v[224:227], v[200:203], v[96:99]
	v_mfma_f32_16x16x32_bf16 v[84:87], v[216:219], v[208:211], v[84:87]
	v_mfma_f32_16x16x32_bf16 v[80:83], v[224:227], v[208:211], v[80:83]
	s_barrier
; #define PG8_STAGE(bufoff, gbase, voff) do { _Pragma("unroll") for (int _i = 0; _i < 2; ++_i) \
;         __builtin_amdgcn_global_load_lds((const unsigned*)((const char*)(gbase) + (voff)[_i]), (PG8_LAS unsigned*)(lds + (bufoff) + ldsw + _i * 8192), 16, 0, 0); } while (0)
; #define PG8_LDA(dst, b, h) do { _Pragma("unroll") for (int m = 0; m < 4; ++m) _Pragma("unroll") for (int k = 0; k < 2; ++k) dst[m][k] = *(const PG8_LAS bf16x8*)(lds + PG8_SA(b, h) + aoff + m * 2048 + k * 1024); } while (0)
; #define PG8_MMA(ai, bj, At, Bt) do { __builtin_amdgcn_s_setprio(1); _Pragma("unroll") for (int m = 0; m < 4; ++m) _Pragma("unroll") for (int n = 0; n < 2; ++n) _Pragma("unroll") for (int k = 0; k < 2; ++k) \
;         acc[ai][bj][m][n] = __builtin_amdgcn_mfma_f32_16x16x32_bf16(Bt[n][k], At[m][k], acc[ai][bj][m][n], 0, 0, 0); __builtin_amdgcn_s_setprio(0); } while (0)
; #define PG8_WAIT_V(n) asm volatile("s_waitcnt vmcnt(" #n ")" ::: "memory")
; #define PG8_WAIT_L(n) asm volatile("s_waitcnt lgkmcnt(" #n ")" ::: "memory")
; #define PG8_BAR __builtin_amdgcn_s_barrier()
; #define PG8_SCHED __builtin_amdgcn_sched_barrier(0)
; template <class Epi, class Sched>
; __device__ __forceinline__ void gemm_phase(PG8_LAS unsigned char* lds, const Gemm g, const Sched& S, const Epi& E) {
;     ...
;             PG8_LDA(At, 1, 1); PG8_STAGE(PG8_SA(1, 0), a3, voffA);
;             PG8_BAR; PG8_WAIT_L(0); PG8_MMA(1, 0, At, B0); PG8_BAR; PG8_SCHED;
;             PG8_STAGE(PG8_SB(1, 1), b3 + hstep, voffB);
;             PG8_WAIT_V(6); PG8_BAR; PG8_MMA(1, 1, At, B1); PG8_BAR;
;         }
	ds_read_b128 v[144:147], v187 offset:49152
	ds_read_b128 v[148:151], v187 offset:50176
	ds_read_b128 v[182:185], v187 offset:51200
	ds_read_b128 v[192:195], v187 offset:52224
	ds_read_b128 v[196:199], v187 offset:53248
	ds_read_b128 v[200:203], v187 offset:54272
	ds_read_b128 v[204:207], v187 offset:55296
	ds_read_b128 v[208:211], v187 offset:56320
	s_add_i32 s29, s54, s35
	v_lshl_add_u64 v[174:175], v[174:175], 0, s[14:15]
	s_mov_b32 m0, s29
	s_nop 0
	global_load_lds_dwordx4 v[174:175], off
	v_lshl_add_u64 v[174:175], v[228:229], 0, s[14:15]
	s_add_i32 m0, s29, 0x2000
	s_nop 0
	global_load_lds_dwordx4 v[174:175], off
	s_nop 1
	s_mov_b32 m0, s39
	v_lshl_add_u64 v[174:175], v[230:231], 0, s[14:15]
	global_load_lds_dwordx4 v[174:175], off
	v_lshl_add_u64 v[174:175], v[232:233], 0, s[14:15]
	s_mov_b32 m0, s40
	s_nop 0
	global_load_lds_dwordx4 v[174:175], off
	s_add_u32 s4, s4, 0x40080
	s_addc_u32 s5, s5, 0
	s_add_i32 s28, s28, s35
	v_lshl_add_u64 v[246:247], s[4:5], 0, v[156:157]
	s_mov_b32 m0, s28
	s_nop 0
	global_load_lds_dwordx4 v[246:247], off
	v_lshl_add_u64 v[246:247], s[4:5], 0, v[160:161]
	s_add_i32 m0, s28, 0x2000
	s_nop 0
	global_load_lds_dwordx4 v[246:247], off
	s_waitcnt vmcnt(8) lgkmcnt(0)
	s_barrier
	v_mfma_f32_16x16x32_bf16 v[76:79], v[48:51], v[144:147], v[76:79]
	v_mfma_f32_16x16x32_bf16 v[72:75], v[64:67], v[144:147], v[72:75]
	v_mfma_f32_16x16x32_bf16 v[60:63], v[48:51], v[182:185], v[60:63]
	v_mfma_f32_16x16x32_bf16 v[56:59], v[64:67], v[182:185], v[56:59]
	v_mfma_f32_16x16x32_bf16 v[36:39], v[48:51], v[196:199], v[36:39]
	v_mfma_f32_16x16x32_bf16 v[32:35], v[64:67], v[196:199], v[32:35]
	v_mfma_f32_16x16x32_bf16 v[12:15], v[48:51], v[204:207], v[12:15]
	v_mfma_f32_16x16x32_bf16 v[8:11], v[64:67], v[204:207], v[8:11]
	v_mfma_f32_16x16x32_bf16 v[76:79], v[52:55], v[148:151], v[76:79]
	v_mfma_f32_16x16x32_bf16 v[72:75], v[68:71], v[148:151], v[72:75]
	v_mfma_f32_16x16x32_bf16 v[60:63], v[52:55], v[192:195], v[60:63]
	v_mfma_f32_16x16x32_bf16 v[56:59], v[68:71], v[192:195], v[56:59]
	v_mfma_f32_16x16x32_bf16 v[36:39], v[52:55], v[200:203], v[36:39]
	v_mfma_f32_16x16x32_bf16 v[32:35], v[68:71], v[200:203], v[32:35]
	v_mfma_f32_16x16x32_bf16 v[12:15], v[52:55], v[208:211], v[12:15]
	v_mfma_f32_16x16x32_bf16 v[8:11], v[68:71], v[208:211], v[8:11]
	v_mfma_f32_16x16x32_bf16 v[24:27], v[212:215], v[144:147], v[24:27]
	v_mfma_f32_16x16x32_bf16 v[68:71], v[216:219], v[148:151], v[24:27]
	v_mfma_f32_16x16x32_bf16 v[24:27], v[220:223], v[144:147], v[28:31]
	v_mfma_f32_16x16x32_bf16 v[64:67], v[224:227], v[148:151], v[24:27]
	v_mfma_f32_16x16x32_bf16 v[24:27], v[212:215], v[182:185], v[40:43]
	v_mfma_f32_16x16x32_bf16 v[52:55], v[216:219], v[192:195], v[24:27]
	v_mfma_f32_16x16x32_bf16 v[24:27], v[220:223], v[182:185], v[44:47]
	v_mfma_f32_16x16x32_bf16 v[20:23], v[212:215], v[196:199], v[20:23]
	v_mfma_f32_16x16x32_bf16 v[16:19], v[220:223], v[196:199], v[16:19]
	v_mfma_f32_16x16x32_bf16 v[4:7], v[212:215], v[204:207], v[4:7]
	v_mfma_f32_16x16x32_bf16 v[0:3], v[220:223], v[204:207], v[0:3]
	v_mfma_f32_16x16x32_bf16 v[48:51], v[224:227], v[192:195], v[24:27]
	v_mfma_f32_16x16x32_bf16 v[20:23], v[216:219], v[200:203], v[20:23]
	v_mfma_f32_16x16x32_bf16 v[16:19], v[224:227], v[200:203], v[16:19]
	v_mfma_f32_16x16x32_bf16 v[4:7], v[216:219], v[208:211], v[4:7]
	v_mfma_f32_16x16x32_bf16 v[0:3], v[224:227], v[208:211], v[0:3]
	s_barrier
	s_add_i32 s53, s53, 2
	s_add_u32 s0, s0, 0x100
	s_addc_u32 s1, s1, 0
	s_add_u32 s51, s51, 0x100
	s_addc_u32 s52, s52, 0
	s_cmp_gt_u32 s53, 13

; #define PG8_STAGE(bufoff, gbase, voff) do { _Pragma("unroll") for (int _i = 0; _i < 2; ++_i) \
;         __builtin_amdgcn_global_load_lds((const unsigned*)((const char*)(gbase) + (voff)[_i]), (PG8_LAS unsigned*)(lds + (bufoff) + ldsw + _i * 8192), 16, 0, 0); } while (0)
; #define PG8_LDA(dst, b, h) do { _Pragma("unroll") for (int m = 0; m < 4; ++m) _Pragma("unroll") for (int k = 0; k < 2; ++k) dst[m][k] = *(const PG8_LAS bf16x8*)(lds + PG8_SA(b, h) + aoff + m * 2048 + k * 1024); } while (0)
; #define PG8_LDB(dst, b, h) do { _Pragma("unroll") for (int n = 0; n < 2; ++n) _Pragma("unroll") for (int k = 0; k < 2; ++k) dst[n][k] = *(const PG8_LAS bf16x8*)(lds + PG8_SB(b, h) + boff + n * 2048 + k * 1024); } while (0)
; template <class Epi, class Sched>
; __device__ __forceinline__ void gemm_phase(PG8_LAS unsigned char* lds, const Gemm g, const Sched& S, const Epi& E) {
;     ...
;         const bool has_next = S.next(ui + 1, nxt);
;         const char* nA = has_next ? (const char*)g.A + (size_t)nxt.pm * tstep : cA; const char* nB = has_next ? (const char*)g.Bt + (size_t)nxt.pn * tstep : cB;
;         for (int t = 0; t < nt; t += 2) {
;             const bool last = (t == nt - 2);
;             const char* a1 = cA + (size_t)(t + 1) * kstep;
;             const char* a2 = last ? nA : cA + (size_t)(t + 2) * kstep; const char* b2 = last ? nB : cB + (size_t)(t + 2) * kstep;
;             const char* a3 = a2 + kstep; const char* b3 = b2 + kstep;
;             if (last && has_next) S.a_ready(nxt);
;             PG8_LDB(B0, 0, 0); PG8_SCHED; PG8_LDA(At, 0, 0); PG8_STAGE(PG8_SA(1, 1), a1 + hstep, voffA);
;             PG8_WAIT_L(8); PG8_BAR; PG8_WAIT_L(0); PG8_MMA(0, 0, At, B0); PG8_BAR; PG8_SCHED;
;             PG8_LDB(B1, 0, 1); PG8_STAGE(PG8_SB(0, 0), b2, voffB);
;             PG8_BAR; PG8_WAIT_L(0); PG8_MMA(0, 1, At, B1); PG8_BAR;
;             PG8_LDA(At, 0, 1); PG8_STAGE(PG8_SA(0, 0), a2, voffA);
;             PG8_BAR; PG8_WAIT_L(0); PG8_MMA(1, 0, At, B0); PG8_BAR; PG8_SCHED;
;             PG8_STAGE(PG8_SB(0, 1), b2 + hstep, voffB);
;             PG8_WAIT_V(6); PG8_BAR; PG8_MMA(1, 1, At, B1); PG8_BAR;
;     ...
;         for (int a = 0; a < 2; ++a)
; #pragma unroll
;             for (int b = 0; b < 2; ++b)
; #pragma unroll
;                 for (int m = 0; m < 4; ++m)
; #pragma unroll
;                     for (int n = 0; n < 2; ++n) acc[a][b][m][n] = (f32x4){0.f, 0.f, 0.f, 0.f};
.LBB0_723:
	s_ashr_i32 s11, s10, 31
	v_cmp_lt_i64_e32 vcc, s[12:13], v[140:141]
	s_lshl_b64 s[12:13], s[10:11], 19
	s_add_u32 s12, s26, s12
	s_addc_u32 s13, s27, s13
	s_and_b64 s[14:15], vcc, exec
	s_cselect_b32 s5, s13, s19
	s_cselect_b32 s11, s12, s18
	s_ashr_i32 s9, s8, 31
	s_lshl_b64 s[14:15], s[8:9], 19
	s_add_u32 s14, s28, s14
	s_addc_u32 s15, s29, s15
	s_and_b64 s[22:23], vcc, exec
	s_cselect_b32 s9, s15, s21
	s_cselect_b32 s45, s14, s20
	s_add_u32 s18, s18, 0x40080
	s_addc_u32 s19, s19, 0
	s_add_u32 s46, s20, 0x100
	s_addc_u32 s47, s21, 0
	s_mov_b32 s48, -2
	ds_read_b128 v[144:147], v151
	ds_read_b128 v[156:159], v151 offset:1024
	ds_read_b128 v[160:163], v151 offset:2048
	ds_read_b128 v[166:169], v151 offset:3072
	s_add_u32 s20, s18, 0xfffc0080
	s_addc_u32 s21, s19, -1
	s_cmp_eq_u32 s48, 12
	s_cselect_b32 s23, s5, s21
	s_cselect_b32 s22, s11, s20
	s_cselect_b32 s21, s9, s47
	s_cselect_b32 s20, s45, s46
	v_lshl_add_u64 v[174:175], s[18:19], 0, v[136:137]
	s_add_i32 m0, s17, 0xc000
	ds_read_b128 v[170:173], v153
	ds_read_b128 v[182:185], v153 offset:1024
	ds_read_b128 v[190:193], v153 offset:2048
	ds_read_b128 v[194:197], v153 offset:3072
	ds_read_b128 v[198:201], v153 offset:4096
	ds_read_b128 v[202:205], v153 offset:5120
	ds_read_b128 v[206:209], v153 offset:6144
	ds_read_b128 v[210:213], v153 offset:7168
	global_load_lds_dwordx4 v[174:175], off
	v_lshl_add_u64 v[174:175], s[18:19], 0, v[138:139]
	s_add_i32 m0, s17, 0xe000
	s_nop 0
	global_load_lds_dwordx4 v[174:175], off
	s_waitcnt lgkmcnt(8)
	ds_read_b128 v[214:217], v154
	ds_read_b128 v[218:221], v154 offset:1024
	ds_read_b128 v[222:225], v154 offset:2048
	ds_read_b128 v[226:229], v154 offset:3072
	s_waitcnt vmcnt(8) lgkmcnt(0)
	s_barrier
	v_mfma_f32_16x16x32_bf16 v[124:127], v[144:147], v[170:173], 0
	v_mfma_f32_16x16x32_bf16 v[120:123], v[160:163], v[170:173], 0
	v_mfma_f32_16x16x32_bf16 v[108:111], v[144:147], v[190:193], 0
	v_mfma_f32_16x16x32_bf16 v[104:107], v[160:163], v[190:193], 0
	v_mfma_f32_16x16x32_bf16 v[92:95], v[144:147], v[198:201], 0
	v_mfma_f32_16x16x32_bf16 v[88:91], v[160:163], v[198:201], 0
	v_mfma_f32_16x16x32_bf16 v[76:79], v[144:147], v[206:209], 0
	v_mfma_f32_16x16x32_bf16 v[72:75], v[160:163], v[206:209], 0
	v_mfma_f32_16x16x32_bf16 v[124:127], v[156:159], v[182:185], v[124:127]
	v_mfma_f32_16x16x32_bf16 v[120:123], v[166:169], v[182:185], v[120:123]
	v_mfma_f32_16x16x32_bf16 v[108:111], v[156:159], v[194:197], v[108:111]
	v_mfma_f32_16x16x32_bf16 v[104:107], v[166:169], v[194:197], v[104:107]
	v_mfma_f32_16x16x32_bf16 v[92:95], v[156:159], v[202:205], v[92:95]
	v_mfma_f32_16x16x32_bf16 v[88:91], v[166:169], v[202:205], v[88:91]
	v_mfma_f32_16x16x32_bf16 v[76:79], v[156:159], v[210:213], v[76:79]
	v_mfma_f32_16x16x32_bf16 v[72:75], v[166:169], v[210:213], v[72:75]
	v_mfma_f32_16x16x32_bf16 v[116:119], v[214:217], v[170:173], 0
	v_mfma_f32_16x16x32_bf16 v[112:115], v[222:225], v[170:173], 0
	v_mfma_f32_16x16x32_bf16 v[100:103], v[214:217], v[190:193], 0
	v_mfma_f32_16x16x32_bf16 v[96:99], v[222:225], v[190:193], 0
	v_mfma_f32_16x16x32_bf16 v[84:87], v[214:217], v[198:201], 0
	v_mfma_f32_16x16x32_bf16 v[80:83], v[222:225], v[198:201], 0
	v_mfma_f32_16x16x32_bf16 v[68:71], v[214:217], v[206:209], 0
	v_mfma_f32_16x16x32_bf16 v[64:67], v[222:225], v[206:209], 0
	v_mfma_f32_16x16x32_bf16 v[116:119], v[218:221], v[182:185], v[116:119]
	v_mfma_f32_16x16x32_bf16 v[112:115], v[226:229], v[182:185], v[112:115]
	v_mfma_f32_16x16x32_bf16 v[100:103], v[218:221], v[194:197], v[100:103]
	v_mfma_f32_16x16x32_bf16 v[96:99], v[226:229], v[194:197], v[96:99]
	v_mfma_f32_16x16x32_bf16 v[84:87], v[218:221], v[202:205], v[84:87]
	v_mfma_f32_16x16x32_bf16 v[80:83], v[226:229], v[202:205], v[80:83]
	v_mfma_f32_16x16x32_bf16 v[68:71], v[218:221], v[210:213], v[68:71]
	v_mfma_f32_16x16x32_bf16 v[64:67], v[226:229], v[210:213], v[64:67]
	s_barrier
	ds_read_b128 v[170:173], v153 offset:16384
	ds_read_b128 v[182:185], v153 offset:17408
	ds_read_b128 v[190:193], v153 offset:18432
	ds_read_b128 v[194:197], v153 offset:19456
	ds_read_b128 v[198:201], v153 offset:20480
	ds_read_b128 v[202:205], v153 offset:21504
	ds_read_b128 v[206:209], v153 offset:22528
	ds_read_b128 v[210:213], v153 offset:23552
	s_add_i32 s49, s42, s30
	v_lshl_add_u64 v[174:175], s[20:21], 0, v[130:131]
	s_mov_b32 m0, s49
	s_nop 0
	global_load_lds_dwordx4 v[174:175], off
	v_lshl_add_u64 v[186:187], s[20:21], 0, v[134:135]
	s_add_i32 m0, s49, 0x2000
	s_nop 0
	global_load_lds_dwordx4 v[186:187], off
	s_nop 1
	s_mov_b32 m0, s17
	v_lshl_add_u64 v[230:231], s[22:23], 0, v[128:129]
	global_load_lds_dwordx4 v[230:231], off
	v_lshl_add_u64 v[232:233], s[22:23], 0, v[132:133]
	s_mov_b32 m0, s31
	s_nop 0
	global_load_lds_dwordx4 v[232:233], off
	s_add_u32 s50, s20, 0x40000
	s_addc_u32 s51, s21, 0
	s_add_i32 s49, s43, s30
	v_lshl_add_u64 v[246:247], s[50:51], 0, v[130:131]
	s_mov_b32 m0, s49
	s_nop 0
	global_load_lds_dwordx4 v[246:247], off
	v_lshl_add_u64 v[246:247], s[50:51], 0, v[134:135]
	s_add_i32 m0, s49, 0x2000
	s_nop 0
	global_load_lds_dwordx4 v[246:247], off
	s_waitcnt vmcnt(8) lgkmcnt(0)
	s_barrier
; #define PG8_STAGE(bufoff, gbase, voff) do { _Pragma("unroll") for (int _i = 0; _i < 2; ++_i) \
;         __builtin_amdgcn_global_load_lds((const unsigned*)((const char*)(gbase) + (voff)[_i]), (PG8_LAS unsigned*)(lds + (bufoff) + ldsw + _i * 8192), 16, 0, 0); } while (0)
; #define PG8_LDA(dst, b, h) do { _Pragma("unroll") for (int m = 0; m < 4; ++m) _Pragma("unroll") for (int k = 0; k < 2; ++k) dst[m][k] = *(const PG8_LAS bf16x8*)(lds + PG8_SA(b, h) + aoff + m * 2048 + k * 1024); } while (0)
; #define PG8_LDB(dst, b, h) do { _Pragma("unroll") for (int n = 0; n < 2; ++n) _Pragma("unroll") for (int k = 0; k < 2; ++k) dst[n][k] = *(const PG8_LAS bf16x8*)(lds + PG8_SB(b, h) + boff + n * 2048 + k * 1024); } while (0)
; #define PG8_MMA(ai, bj, At, Bt) do { __builtin_amdgcn_s_setprio(1); _Pragma("unroll") for (int m = 0; m < 4; ++m) _Pragma("unroll") for (int n = 0; n < 2; ++n) _Pragma("unroll") for (int k = 0; k < 2; ++k) \
;         acc[ai][bj][m][n] = __builtin_amdgcn_mfma_f32_16x16x32_bf16(Bt[n][k], At[m][k], acc[ai][bj][m][n], 0, 0, 0); __builtin_amdgcn_s_setprio(0); } while (0)
; #define PG8_WAIT_V(n) asm volatile("s_waitcnt vmcnt(" #n ")" ::: "memory")
; #define PG8_WAIT_L(n) asm volatile("s_waitcnt lgkmcnt(" #n ")" ::: "memory")
; #define PG8_BAR __builtin_amdgcn_s_barrier()
; #define PG8_SCHED __builtin_amdgcn_sched_barrier(0)
; template <class Epi, class Sched>
; __device__ __forceinline__ void gemm_phase(PG8_LAS unsigned char* lds, const Gemm g, const Sched& S, const Epi& E) {
;     ...
;             PG8_BAR; PG8_WAIT_L(0); PG8_MMA(1, 0, At, B0); PG8_BAR; PG8_SCHED;
;             PG8_STAGE(PG8_SB(0, 1), b2 + hstep, voffB);
;             PG8_WAIT_V(6); PG8_BAR; PG8_MMA(1, 1, At, B1); PG8_BAR;
;             PG8_LDB(B0, 1, 0); PG8_SCHED; PG8_LDA(At, 1, 0); PG8_STAGE(PG8_SA(0, 1), a2 + hstep, voffA);
;             PG8_WAIT_L(8); PG8_BAR; PG8_WAIT_L(0); PG8_MMA(0, 0, At, B0); PG8_BAR; PG8_SCHED;
;             PG8_LDB(B1, 1, 1); PG8_STAGE(PG8_SB(1, 0), b3, voffB);
;             PG8_BAR; PG8_WAIT_L(0); PG8_MMA(0, 1, At, B1); PG8_BAR;
	v_mfma_f32_16x16x32_bf16 v[60:63], v[144:147], v[170:173], 0
	v_mfma_f32_16x16x32_bf16 v[56:59], v[160:163], v[170:173], 0
	v_mfma_f32_16x16x32_bf16 v[44:47], v[144:147], v[190:193], 0
	v_mfma_f32_16x16x32_bf16 v[40:43], v[160:163], v[190:193], 0
	v_mfma_f32_16x16x32_bf16 v[28:31], v[144:147], v[198:201], 0
	v_mfma_f32_16x16x32_bf16 v[24:27], v[160:163], v[198:201], 0
	v_mfma_f32_16x16x32_bf16 v[12:15], v[144:147], v[206:209], 0
	v_mfma_f32_16x16x32_bf16 v[8:11], v[160:163], v[206:209], 0
	v_mfma_f32_16x16x32_bf16 v[60:63], v[156:159], v[182:185], v[60:63]
	v_mfma_f32_16x16x32_bf16 v[56:59], v[166:169], v[182:185], v[56:59]
	v_mfma_f32_16x16x32_bf16 v[44:47], v[156:159], v[194:197], v[44:47]
	v_mfma_f32_16x16x32_bf16 v[40:43], v[166:169], v[194:197], v[40:43]
	v_mfma_f32_16x16x32_bf16 v[28:31], v[156:159], v[202:205], v[28:31]
	v_mfma_f32_16x16x32_bf16 v[24:27], v[166:169], v[202:205], v[24:27]
	v_mfma_f32_16x16x32_bf16 v[12:15], v[156:159], v[210:213], v[12:15]
	v_mfma_f32_16x16x32_bf16 v[8:11], v[166:169], v[210:213], v[8:11]
	v_mfma_f32_16x16x32_bf16 v[52:55], v[214:217], v[170:173], 0
	v_mfma_f32_16x16x32_bf16 v[48:51], v[222:225], v[170:173], 0
	v_mfma_f32_16x16x32_bf16 v[36:39], v[214:217], v[190:193], 0
	v_mfma_f32_16x16x32_bf16 v[32:35], v[222:225], v[190:193], 0
	v_mfma_f32_16x16x32_bf16 v[20:23], v[214:217], v[198:201], 0
	v_mfma_f32_16x16x32_bf16 v[16:19], v[222:225], v[198:201], 0
	v_mfma_f32_16x16x32_bf16 v[4:7], v[214:217], v[206:209], 0
	v_mfma_f32_16x16x32_bf16 v[0:3], v[222:225], v[206:209], 0
	v_mfma_f32_16x16x32_bf16 v[52:55], v[218:221], v[182:185], v[52:55]
	v_mfma_f32_16x16x32_bf16 v[48:51], v[226:229], v[182:185], v[48:51]
	v_mfma_f32_16x16x32_bf16 v[36:39], v[218:221], v[194:197], v[36:39]
	v_mfma_f32_16x16x32_bf16 v[32:35], v[226:229], v[194:197], v[32:35]
	v_mfma_f32_16x16x32_bf16 v[20:23], v[218:221], v[202:205], v[20:23]
	v_mfma_f32_16x16x32_bf16 v[16:19], v[226:229], v[202:205], v[16:19]
	v_mfma_f32_16x16x32_bf16 v[4:7], v[218:221], v[210:213], v[4:7]
	v_mfma_f32_16x16x32_bf16 v[0:3], v[226:229], v[210:213], v[0:3]
	s_barrier
	s_add_i32 s49, 0, 0x18000
	v_add_u32_e32 v155, s49, v149
	ds_read_b128 v[144:147], v155
	ds_read_b128 v[156:159], v155 offset:1024
	ds_read_b128 v[160:163], v155 offset:2048
	ds_read_b128 v[166:169], v155 offset:3072
	s_add_u32 s22, s22, 0x40000
	s_addc_u32 s23, s23, 0
	s_mov_b32 m0, s34
	v_lshl_add_u64 v[214:215], s[22:23], 0, v[128:129]
	ds_read_b128 v[170:173], v153 offset:32768
	ds_read_b128 v[182:185], v153 offset:33792
	ds_read_b128 v[190:193], v153 offset:34816
	ds_read_b128 v[194:197], v153 offset:35840
	ds_read_b128 v[198:201], v153 offset:36864
	ds_read_b128 v[202:205], v153 offset:37888
	ds_read_b128 v[206:209], v153 offset:38912
	ds_read_b128 v[210:213], v153 offset:39936
	global_load_lds_dwordx4 v[214:215], off
	v_lshl_add_u64 v[214:215], s[22:23], 0, v[132:133]
	s_mov_b32 m0, s35
	s_nop 0
	global_load_lds_dwordx4 v[214:215], off
	s_add_i32 s22, 0, 0x1c000
	v_add_u32_e32 v155, s22, v149
	s_waitcnt lgkmcnt(8)
	ds_read_b128 v[214:217], v155
	ds_read_b128 v[218:221], v155 offset:1024
	ds_read_b128 v[222:225], v155 offset:2048
	ds_read_b128 v[226:229], v155 offset:3072
	s_waitcnt vmcnt(8) lgkmcnt(0)
	s_barrier
	v_mfma_f32_16x16x32_bf16 v[124:127], v[144:147], v[170:173], v[124:127]
	v_mfma_f32_16x16x32_bf16 v[120:123], v[160:163], v[170:173], v[120:123]
	v_mfma_f32_16x16x32_bf16 v[108:111], v[144:147], v[190:193], v[108:111]
	v_mfma_f32_16x16x32_bf16 v[104:107], v[160:163], v[190:193], v[104:107]
	v_mfma_f32_16x16x32_bf16 v[92:95], v[144:147], v[198:201], v[92:95]
	v_mfma_f32_16x16x32_bf16 v[88:91], v[160:163], v[198:201], v[88:91]
	v_mfma_f32_16x16x32_bf16 v[76:79], v[144:147], v[206:209], v[76:79]
	v_mfma_f32_16x16x32_bf16 v[72:75], v[160:163], v[206:209], v[72:75]
	v_mfma_f32_16x16x32_bf16 v[124:127], v[156:159], v[182:185], v[124:127]
	v_mfma_f32_16x16x32_bf16 v[120:123], v[166:169], v[182:185], v[120:123]
	v_mfma_f32_16x16x32_bf16 v[108:111], v[156:159], v[194:197], v[108:111]
	v_mfma_f32_16x16x32_bf16 v[104:107], v[166:169], v[194:197], v[104:107]
	v_mfma_f32_16x16x32_bf16 v[92:95], v[156:159], v[202:205], v[92:95]
	v_mfma_f32_16x16x32_bf16 v[88:91], v[166:169], v[202:205], v[88:91]
	v_mfma_f32_16x16x32_bf16 v[76:79], v[156:159], v[210:213], v[76:79]
	v_mfma_f32_16x16x32_bf16 v[72:75], v[166:169], v[210:213], v[72:75]
	v_mfma_f32_16x16x32_bf16 v[116:119], v[214:217], v[170:173], v[116:119]
	v_mfma_f32_16x16x32_bf16 v[112:115], v[222:225], v[170:173], v[112:115]
	v_mfma_f32_16x16x32_bf16 v[100:103], v[214:217], v[190:193], v[100:103]
	v_mfma_f32_16x16x32_bf16 v[96:99], v[222:225], v[190:193], v[96:99]
	v_mfma_f32_16x16x32_bf16 v[84:87], v[214:217], v[198:201], v[84:87]
	v_mfma_f32_16x16x32_bf16 v[80:83], v[222:225], v[198:201], v[80:83]
	v_mfma_f32_16x16x32_bf16 v[68:71], v[214:217], v[206:209], v[68:71]
	v_mfma_f32_16x16x32_bf16 v[64:67], v[222:225], v[206:209], v[64:67]
	v_mfma_f32_16x16x32_bf16 v[116:119], v[218:221], v[182:185], v[116:119]
	v_mfma_f32_16x16x32_bf16 v[112:115], v[226:229], v[182:185], v[112:115]
	v_mfma_f32_16x16x32_bf16 v[100:103], v[218:221], v[194:197], v[100:103]
	v_mfma_f32_16x16x32_bf16 v[96:99], v[226:229], v[194:197], v[96:99]
	v_mfma_f32_16x16x32_bf16 v[84:87], v[218:221], v[202:205], v[84:87]
	v_mfma_f32_16x16x32_bf16 v[80:83], v[226:229], v[202:205], v[80:83]
	v_mfma_f32_16x16x32_bf16 v[68:71], v[218:221], v[210:213], v[68:71]
	v_mfma_f32_16x16x32_bf16 v[64:67], v[226:229], v[210:213], v[64:67]
	s_barrier
; #define PG8_STAGE(bufoff, gbase, voff) do { _Pragma("unroll") for (int _i = 0; _i < 2; ++_i) \
;         __builtin_amdgcn_global_load_lds((const unsigned*)((const char*)(gbase) + (voff)[_i]), (PG8_LAS unsigned*)(lds + (bufoff) + ldsw + _i * 8192), 16, 0, 0); } while (0)
; #define PG8_LDA(dst, b, h) do { _Pragma("unroll") for (int m = 0; m < 4; ++m) _Pragma("unroll") for (int k = 0; k < 2; ++k) dst[m][k] = *(const PG8_LAS bf16x8*)(lds + PG8_SA(b, h) + aoff + m * 2048 + k * 1024); } while (0)
; #define PG8_MMA(ai, bj, At, Bt) do { __builtin_amdgcn_s_setprio(1); _Pragma("unroll") for (int m = 0; m < 4; ++m) _Pragma("unroll") for (int n = 0; n < 2; ++n) _Pragma("unroll") for (int k = 0; k < 2; ++k) \
;         acc[ai][bj][m][n] = __builtin_amdgcn_mfma_f32_16x16x32_bf16(Bt[n][k], At[m][k], acc[ai][bj][m][n], 0, 0, 0); __builtin_amdgcn_s_setprio(0); } while (0)
; #define PG8_WAIT_V(n) asm volatile("s_waitcnt vmcnt(" #n ")" ::: "memory")
; #define PG8_WAIT_L(n) asm volatile("s_waitcnt lgkmcnt(" #n ")" ::: "memory")
; #define PG8_BAR __builtin_amdgcn_s_barrier()
; #define PG8_SCHED __builtin_amdgcn_sched_barrier(0)
; template <class Epi, class Sched>
; __device__ __forceinline__ void gemm_phase(PG8_LAS unsigned char* lds, const Gemm g, const Sched& S, const Epi& E) {
;     ...
;             PG8_LDA(At, 1, 1); PG8_STAGE(PG8_SA(1, 0), a3, voffA);
;             PG8_BAR; PG8_WAIT_L(0); PG8_MMA(1, 0, At, B0); PG8_BAR; PG8_SCHED;
;             PG8_STAGE(PG8_SB(1, 1), b3 + hstep, voffB);
;             PG8_WAIT_V(6); PG8_BAR; PG8_MMA(1, 1, At, B1); PG8_BAR;
;         }
	ds_read_b128 v[170:173], v153 offset:49152
	ds_read_b128 v[182:185], v153 offset:50176
	ds_read_b128 v[190:193], v153 offset:51200
	ds_read_b128 v[194:197], v153 offset:52224
	ds_read_b128 v[198:201], v153 offset:53248
	ds_read_b128 v[202:205], v153 offset:54272
	ds_read_b128 v[206:209], v153 offset:55296
	ds_read_b128 v[210:213], v153 offset:56320
	s_add_i32 s23, s49, s30
	v_lshl_add_u64 v[174:175], v[174:175], 0, s[6:7]
	s_mov_b32 m0, s23
	s_nop 0
	global_load_lds_dwordx4 v[174:175], off
	v_lshl_add_u64 v[174:175], v[186:187], 0, s[6:7]
	s_add_i32 m0, s23, 0x2000
	s_nop 0
	global_load_lds_dwordx4 v[174:175], off
	s_nop 1
	s_mov_b32 m0, s37
	v_lshl_add_u64 v[174:175], v[230:231], 0, s[6:7]
	global_load_lds_dwordx4 v[174:175], off
	v_lshl_add_u64 v[174:175], v[232:233], 0, s[6:7]
	s_mov_b32 m0, s38
	s_nop 0
	global_load_lds_dwordx4 v[174:175], off
	s_add_u32 s20, s20, 0x40080
	s_addc_u32 s21, s21, 0
	s_add_i32 s22, s22, s30
	v_lshl_add_u64 v[246:247], s[20:21], 0, v[130:131]
	s_mov_b32 m0, s22
	s_nop 0
	global_load_lds_dwordx4 v[246:247], off
	v_lshl_add_u64 v[246:247], s[20:21], 0, v[134:135]
	s_add_i32 m0, s22, 0x2000
	s_nop 0
	global_load_lds_dwordx4 v[246:247], off
	s_waitcnt vmcnt(8) lgkmcnt(0)
	s_barrier
	v_mfma_f32_16x16x32_bf16 v[60:63], v[144:147], v[170:173], v[60:63]
	v_mfma_f32_16x16x32_bf16 v[56:59], v[160:163], v[170:173], v[56:59]
	v_mfma_f32_16x16x32_bf16 v[44:47], v[144:147], v[190:193], v[44:47]
	v_mfma_f32_16x16x32_bf16 v[40:43], v[160:163], v[190:193], v[40:43]
	v_mfma_f32_16x16x32_bf16 v[28:31], v[144:147], v[198:201], v[28:31]
	v_mfma_f32_16x16x32_bf16 v[24:27], v[160:163], v[198:201], v[24:27]
	v_mfma_f32_16x16x32_bf16 v[12:15], v[144:147], v[206:209], v[12:15]
	v_mfma_f32_16x16x32_bf16 v[8:11], v[160:163], v[206:209], v[8:11]
	v_mfma_f32_16x16x32_bf16 v[60:63], v[156:159], v[182:185], v[60:63]
	v_mfma_f32_16x16x32_bf16 v[56:59], v[166:169], v[182:185], v[56:59]
	v_mfma_f32_16x16x32_bf16 v[44:47], v[156:159], v[194:197], v[44:47]
	v_mfma_f32_16x16x32_bf16 v[40:43], v[166:169], v[194:197], v[40:43]
	v_mfma_f32_16x16x32_bf16 v[28:31], v[156:159], v[202:205], v[28:31]
	v_mfma_f32_16x16x32_bf16 v[24:27], v[166:169], v[202:205], v[24:27]
	v_mfma_f32_16x16x32_bf16 v[12:15], v[156:159], v[210:213], v[12:15]
	v_mfma_f32_16x16x32_bf16 v[8:11], v[166:169], v[210:213], v[8:11]
	v_mfma_f32_16x16x32_bf16 v[52:55], v[214:217], v[170:173], v[52:55]
	v_mfma_f32_16x16x32_bf16 v[48:51], v[222:225], v[170:173], v[48:51]
	v_mfma_f32_16x16x32_bf16 v[36:39], v[214:217], v[190:193], v[36:39]
	v_mfma_f32_16x16x32_bf16 v[32:35], v[222:225], v[190:193], v[32:35]
	v_mfma_f32_16x16x32_bf16 v[20:23], v[214:217], v[198:201], v[20:23]
	v_mfma_f32_16x16x32_bf16 v[16:19], v[222:225], v[198:201], v[16:19]
	v_mfma_f32_16x16x32_bf16 v[4:7], v[214:217], v[206:209], v[4:7]
	v_mfma_f32_16x16x32_bf16 v[0:3], v[222:225], v[206:209], v[0:3]
	v_mfma_f32_16x16x32_bf16 v[52:55], v[218:221], v[182:185], v[52:55]
	v_mfma_f32_16x16x32_bf16 v[48:51], v[226:229], v[182:185], v[48:51]
	v_mfma_f32_16x16x32_bf16 v[36:39], v[218:221], v[194:197], v[36:39]
	v_mfma_f32_16x16x32_bf16 v[32:35], v[226:229], v[194:197], v[32:35]
	v_mfma_f32_16x16x32_bf16 v[20:23], v[218:221], v[202:205], v[20:23]
	v_mfma_f32_16x16x32_bf16 v[16:19], v[226:229], v[202:205], v[16:19]
	v_mfma_f32_16x16x32_bf16 v[4:7], v[218:221], v[210:213], v[4:7]
	v_mfma_f32_16x16x32_bf16 v[0:3], v[226:229], v[210:213], v[0:3]
	s_barrier
	s_add_i32 s48, s48, 2
	s_add_u32 s18, s18, 0x100
	s_addc_u32 s19, s19, 0
	s_add_u32 s46, s46, 0x100
	s_addc_u32 s47, s47, 0
	s_cmp_gt_u32 s48, 13

; #define PG8_STAGE(bufoff, gbase, voff) do { _Pragma("unroll") for (int _i = 0; _i < 2; ++_i) \
;         __builtin_amdgcn_global_load_lds((const unsigned*)((const char*)(gbase) + (voff)[_i]), (PG8_LAS unsigned*)(lds + (bufoff) + ldsw + _i * 8192), 16, 0, 0); } while (0)
; #define PG8_LDA(dst, b, h) do { _Pragma("unroll") for (int m = 0; m < 4; ++m) _Pragma("unroll") for (int k = 0; k < 2; ++k) dst[m][k] = *(const PG8_LAS bf16x8*)(lds + PG8_SA(b, h) + aoff + m * 2048 + k * 1024); } while (0)
; #define PG8_LDB(dst, b, h) do { _Pragma("unroll") for (int n = 0; n < 2; ++n) _Pragma("unroll") for (int k = 0; k < 2; ++k) dst[n][k] = *(const PG8_LAS bf16x8*)(lds + PG8_SB(b, h) + boff + n * 2048 + k * 1024); } while (0)
; template <class Epi, class Sched>
; __device__ __forceinline__ void gemm_phase(PG8_LAS unsigned char* lds, const Gemm g, const Sched& S, const Epi& E) {
;     ...
;         const bool has_next = S.next(ui + 1, nxt);
;         const char* nA = has_next ? (const char*)g.A + (size_t)nxt.pm * tstep : cA; const char* nB = has_next ? (const char*)g.Bt + (size_t)nxt.pn * tstep : cB;
;         for (int t = 0; t < nt; t += 2) {
;             const bool last = (t == nt - 2);
;             const char* a1 = cA + (size_t)(t + 1) * kstep;
;             const char* a2 = last ? nA : cA + (size_t)(t + 2) * kstep; const char* b2 = last ? nB : cB + (size_t)(t + 2) * kstep;
;             const char* a3 = a2 + kstep; const char* b3 = b2 + kstep;
;             if (last && has_next) S.a_ready(nxt);
;             PG8_LDB(B0, 0, 0); PG8_SCHED; PG8_LDA(At, 0, 0); PG8_STAGE(PG8_SA(1, 1), a1 + hstep, voffA);
;             PG8_WAIT_L(8); PG8_BAR; PG8_WAIT_L(0); PG8_MMA(0, 0, At, B0); PG8_BAR; PG8_SCHED;
;             PG8_LDB(B1, 0, 1); PG8_STAGE(PG8_SB(0, 0), b2, voffB);
;             PG8_BAR; PG8_WAIT_L(0); PG8_MMA(0, 1, At, B1); PG8_BAR;
;             PG8_LDA(At, 0, 1); PG8_STAGE(PG8_SA(0, 0), a2, voffA);
;             PG8_BAR; PG8_WAIT_L(0); PG8_MMA(1, 0, At, B0); PG8_BAR; PG8_SCHED;
;             PG8_STAGE(PG8_SB(0, 1), b2 + hstep, voffB);
;             PG8_WAIT_V(6); PG8_BAR; PG8_MMA(1, 1, At, B1); PG8_BAR;
;     ...
;         for (int a = 0; a < 2; ++a)
; #pragma unroll
;             for (int b = 0; b < 2; ++b)
; #pragma unroll
;                 for (int m = 0; m < 4; ++m)
; #pragma unroll
;                     for (int n = 0; n < 2; ++n) acc[a][b][m][n] = (f32x4){0.f, 0.f, 0.f, 0.f};
.LBB0_990:
	s_ashr_i32 s11, s10, 31
	v_cmp_lt_i64_e32 vcc, s[12:13], v[140:141]
	s_lshl_b64 s[12:13], s[10:11], 19
	s_add_u32 s12, s27, s12
	s_addc_u32 s13, s28, s13
	s_and_b64 s[14:15], vcc, exec
	s_cselect_b32 s11, s13, s19
	s_cselect_b32 s43, s12, s18
	s_ashr_i32 s9, s8, 31
	s_lshl_b64 s[14:15], s[8:9], 19
	s_add_u32 s14, s96, s14
	s_addc_u32 s15, s97, s15
	s_and_b64 s[22:23], vcc, exec
	s_cselect_b32 s9, s15, s21
	s_cselect_b32 s44, s14, s20
	s_add_u32 s18, s18, 0x40080
	s_addc_u32 s19, s19, 0
	s_add_u32 s45, s20, 0x100
	s_addc_u32 s46, s21, 0
	s_mov_b32 s47, -2
	ds_read_b128 v[144:147], v153
	ds_read_b128 v[156:159], v153 offset:1024
	ds_read_b128 v[160:163], v153 offset:2048
	ds_read_b128 v[164:167], v153 offset:3072
	s_add_u32 s20, s18, 0xfffc0080
	s_addc_u32 s21, s19, -1
	s_cmp_eq_u32 s47, 12
	s_cselect_b32 s23, s11, s21
	s_cselect_b32 s22, s43, s20
	s_cselect_b32 s21, s9, s46
	s_cselect_b32 s20, s44, s45
	v_lshl_add_u64 v[148:149], s[18:19], 0, v[136:137]
	s_add_i32 m0, s17, 0xc000
	ds_read_b128 v[168:171], v154
	ds_read_b128 v[172:175], v154 offset:1024
	ds_read_b128 v[182:185], v154 offset:2048
	ds_read_b128 v[190:193], v154 offset:3072
	ds_read_b128 v[194:197], v154 offset:4096
	ds_read_b128 v[198:201], v154 offset:5120
	ds_read_b128 v[202:205], v154 offset:6144
	ds_read_b128 v[206:209], v154 offset:7168
	global_load_lds_dwordx4 v[148:149], off
	v_lshl_add_u64 v[148:149], s[18:19], 0, v[138:139]
	s_add_i32 m0, s17, 0xe000
	s_nop 0
	global_load_lds_dwordx4 v[148:149], off
	s_waitcnt lgkmcnt(8)
	ds_read_b128 v[210:213], v155
	ds_read_b128 v[214:217], v155 offset:1024
	ds_read_b128 v[218:221], v155 offset:2048
	ds_read_b128 v[222:225], v155 offset:3072
	s_waitcnt vmcnt(8) lgkmcnt(0)
	s_barrier
	v_mfma_f32_16x16x32_bf16 v[124:127], v[144:147], v[168:171], 0
	v_mfma_f32_16x16x32_bf16 v[120:123], v[160:163], v[168:171], 0
	v_mfma_f32_16x16x32_bf16 v[112:115], v[144:147], v[182:185], 0
	v_mfma_f32_16x16x32_bf16 v[104:107], v[160:163], v[182:185], 0
	v_mfma_f32_16x16x32_bf16 v[96:99], v[144:147], v[194:197], 0
	v_mfma_f32_16x16x32_bf16 v[88:91], v[160:163], v[194:197], 0
	v_mfma_f32_16x16x32_bf16 v[80:83], v[144:147], v[202:205], 0
	v_mfma_f32_16x16x32_bf16 v[72:75], v[160:163], v[202:205], 0
	v_mfma_f32_16x16x32_bf16 v[124:127], v[156:159], v[172:175], v[124:127]
	v_mfma_f32_16x16x32_bf16 v[120:123], v[164:167], v[172:175], v[120:123]
	v_mfma_f32_16x16x32_bf16 v[112:115], v[156:159], v[190:193], v[112:115]
	v_mfma_f32_16x16x32_bf16 v[104:107], v[164:167], v[190:193], v[104:107]
	v_mfma_f32_16x16x32_bf16 v[96:99], v[156:159], v[198:201], v[96:99]
	v_mfma_f32_16x16x32_bf16 v[88:91], v[164:167], v[198:201], v[88:91]
	v_mfma_f32_16x16x32_bf16 v[80:83], v[156:159], v[206:209], v[80:83]
	v_mfma_f32_16x16x32_bf16 v[72:75], v[164:167], v[206:209], v[72:75]
	v_mfma_f32_16x16x32_bf16 v[116:119], v[210:213], v[168:171], 0
	v_mfma_f32_16x16x32_bf16 v[108:111], v[218:221], v[168:171], 0
	v_mfma_f32_16x16x32_bf16 v[100:103], v[210:213], v[182:185], 0
	v_mfma_f32_16x16x32_bf16 v[92:95], v[218:221], v[182:185], 0
	v_mfma_f32_16x16x32_bf16 v[84:87], v[210:213], v[194:197], 0
	v_mfma_f32_16x16x32_bf16 v[76:79], v[218:221], v[194:197], 0
	v_mfma_f32_16x16x32_bf16 v[68:71], v[210:213], v[202:205], 0
	v_mfma_f32_16x16x32_bf16 v[64:67], v[218:221], v[202:205], 0
	v_mfma_f32_16x16x32_bf16 v[116:119], v[214:217], v[172:175], v[116:119]
	v_mfma_f32_16x16x32_bf16 v[108:111], v[222:225], v[172:175], v[108:111]
	v_mfma_f32_16x16x32_bf16 v[100:103], v[214:217], v[190:193], v[100:103]
	v_mfma_f32_16x16x32_bf16 v[92:95], v[222:225], v[190:193], v[92:95]
	v_mfma_f32_16x16x32_bf16 v[84:87], v[214:217], v[198:201], v[84:87]
	v_mfma_f32_16x16x32_bf16 v[76:79], v[222:225], v[198:201], v[76:79]
	v_mfma_f32_16x16x32_bf16 v[68:71], v[214:217], v[206:209], v[68:71]
	v_mfma_f32_16x16x32_bf16 v[64:67], v[222:225], v[206:209], v[64:67]
	s_barrier
	ds_read_b128 v[168:171], v154 offset:16384
	ds_read_b128 v[172:175], v154 offset:17408
	ds_read_b128 v[182:185], v154 offset:18432
	ds_read_b128 v[190:193], v154 offset:19456
	ds_read_b128 v[194:197], v154 offset:20480
	ds_read_b128 v[198:201], v154 offset:21504
	ds_read_b128 v[202:205], v154 offset:22528
	ds_read_b128 v[206:209], v154 offset:23552
	s_add_i32 s48, s39, s29
	v_lshl_add_u64 v[148:149], s[20:21], 0, v[130:131]
	s_mov_b32 m0, s48
	s_nop 0
	global_load_lds_dwordx4 v[148:149], off
	v_lshl_add_u64 v[186:187], s[20:21], 0, v[134:135]
	s_add_i32 m0, s48, 0x2000
	s_nop 0
	global_load_lds_dwordx4 v[186:187], off
	s_nop 1
	s_mov_b32 m0, s17
	v_lshl_add_u64 v[226:227], s[22:23], 0, v[128:129]
	global_load_lds_dwordx4 v[226:227], off
	v_lshl_add_u64 v[228:229], s[22:23], 0, v[132:133]
	s_mov_b32 m0, s30
	s_nop 0
	global_load_lds_dwordx4 v[228:229], off
	s_add_u32 s48, s20, 0x40000
	s_addc_u32 s49, s21, 0
	s_add_i32 s50, s40, s29
	v_lshl_add_u64 v[246:247], s[48:49], 0, v[130:131]
	s_mov_b32 m0, s50
	s_nop 0
	global_load_lds_dwordx4 v[246:247], off
	v_lshl_add_u64 v[246:247], s[48:49], 0, v[134:135]
	s_add_i32 m0, s50, 0x2000
	s_nop 0
	global_load_lds_dwordx4 v[246:247], off
	s_waitcnt vmcnt(8) lgkmcnt(0)
	s_barrier
; #define PG8_STAGE(bufoff, gbase, voff) do { _Pragma("unroll") for (int _i = 0; _i < 2; ++_i) \
;         __builtin_amdgcn_global_load_lds((const unsigned*)((const char*)(gbase) + (voff)[_i]), (PG8_LAS unsigned*)(lds + (bufoff) + ldsw + _i * 8192), 16, 0, 0); } while (0)
; #define PG8_LDA(dst, b, h) do { _Pragma("unroll") for (int m = 0; m < 4; ++m) _Pragma("unroll") for (int k = 0; k < 2; ++k) dst[m][k] = *(const PG8_LAS bf16x8*)(lds + PG8_SA(b, h) + aoff + m * 2048 + k * 1024); } while (0)
; #define PG8_LDB(dst, b, h) do { _Pragma("unroll") for (int n = 0; n < 2; ++n) _Pragma("unroll") for (int k = 0; k < 2; ++k) dst[n][k] = *(const PG8_LAS bf16x8*)(lds + PG8_SB(b, h) + boff + n * 2048 + k * 1024); } while (0)
; #define PG8_MMA(ai, bj, At, Bt) do { __builtin_amdgcn_s_setprio(1); _Pragma("unroll") for (int m = 0; m < 4; ++m) _Pragma("unroll") for (int n = 0; n < 2; ++n) _Pragma("unroll") for (int k = 0; k < 2; ++k) \
;         acc[ai][bj][m][n] = __builtin_amdgcn_mfma_f32_16x16x32_bf16(Bt[n][k], At[m][k], acc[ai][bj][m][n], 0, 0, 0); __builtin_amdgcn_s_setprio(0); } while (0)
; #define PG8_WAIT_V(n) asm volatile("s_waitcnt vmcnt(" #n ")" ::: "memory")
; #define PG8_WAIT_L(n) asm volatile("s_waitcnt lgkmcnt(" #n ")" ::: "memory")
; #define PG8_BAR __builtin_amdgcn_s_barrier()
; #define PG8_SCHED __builtin_amdgcn_sched_barrier(0)
; template <class Epi, class Sched>
; __device__ __forceinline__ void gemm_phase(PG8_LAS unsigned char* lds, const Gemm g, const Sched& S, const Epi& E) {
;     ...
;             PG8_BAR; PG8_WAIT_L(0); PG8_MMA(1, 0, At, B0); PG8_BAR; PG8_SCHED;
;             PG8_STAGE(PG8_SB(0, 1), b2 + hstep, voffB);
;             PG8_WAIT_V(6); PG8_BAR; PG8_MMA(1, 1, At, B1); PG8_BAR;
;             PG8_LDB(B0, 1, 0); PG8_SCHED; PG8_LDA(At, 1, 0); PG8_STAGE(PG8_SA(0, 1), a2 + hstep, voffA);
;             PG8_WAIT_L(8); PG8_BAR; PG8_WAIT_L(0); PG8_MMA(0, 0, At, B0); PG8_BAR; PG8_SCHED;
;             PG8_LDB(B1, 1, 1); PG8_STAGE(PG8_SB(1, 0), b3, voffB);
;             PG8_BAR; PG8_WAIT_L(0); PG8_MMA(0, 1, At, B1); PG8_BAR;
	v_mfma_f32_16x16x32_bf16 v[60:63], v[144:147], v[168:171], 0
	v_mfma_f32_16x16x32_bf16 v[56:59], v[160:163], v[168:171], 0
	v_mfma_f32_16x16x32_bf16 v[48:51], v[144:147], v[182:185], 0
	v_mfma_f32_16x16x32_bf16 v[40:43], v[160:163], v[182:185], 0
	v_mfma_f32_16x16x32_bf16 v[32:35], v[144:147], v[194:197], 0
	v_mfma_f32_16x16x32_bf16 v[24:27], v[160:163], v[194:197], 0
	v_mfma_f32_16x16x32_bf16 v[16:19], v[144:147], v[202:205], 0
	v_mfma_f32_16x16x32_bf16 v[8:11], v[160:163], v[202:205], 0
	v_mfma_f32_16x16x32_bf16 v[60:63], v[156:159], v[172:175], v[60:63]
	v_mfma_f32_16x16x32_bf16 v[56:59], v[164:167], v[172:175], v[56:59]
	v_mfma_f32_16x16x32_bf16 v[48:51], v[156:159], v[190:193], v[48:51]
	v_mfma_f32_16x16x32_bf16 v[40:43], v[164:167], v[190:193], v[40:43]
	v_mfma_f32_16x16x32_bf16 v[32:35], v[156:159], v[198:201], v[32:35]
	v_mfma_f32_16x16x32_bf16 v[24:27], v[164:167], v[198:201], v[24:27]
	v_mfma_f32_16x16x32_bf16 v[16:19], v[156:159], v[206:209], v[16:19]
	v_mfma_f32_16x16x32_bf16 v[8:11], v[164:167], v[206:209], v[8:11]
	v_mfma_f32_16x16x32_bf16 v[52:55], v[210:213], v[168:171], 0
	v_mfma_f32_16x16x32_bf16 v[44:47], v[218:221], v[168:171], 0
	v_mfma_f32_16x16x32_bf16 v[36:39], v[210:213], v[182:185], 0
	v_mfma_f32_16x16x32_bf16 v[28:31], v[218:221], v[182:185], 0
	v_mfma_f32_16x16x32_bf16 v[20:23], v[210:213], v[194:197], 0
	v_mfma_f32_16x16x32_bf16 v[12:15], v[218:221], v[194:197], 0
	v_mfma_f32_16x16x32_bf16 v[4:7], v[210:213], v[202:205], 0
	v_mfma_f32_16x16x32_bf16 v[0:3], v[218:221], v[202:205], 0
	v_mfma_f32_16x16x32_bf16 v[52:55], v[214:217], v[172:175], v[52:55]
	v_mfma_f32_16x16x32_bf16 v[44:47], v[222:225], v[172:175], v[44:47]
	v_mfma_f32_16x16x32_bf16 v[36:39], v[214:217], v[190:193], v[36:39]
	v_mfma_f32_16x16x32_bf16 v[28:31], v[222:225], v[190:193], v[28:31]
	v_mfma_f32_16x16x32_bf16 v[20:23], v[214:217], v[198:201], v[20:23]
	v_mfma_f32_16x16x32_bf16 v[12:15], v[222:225], v[198:201], v[12:15]
	v_mfma_f32_16x16x32_bf16 v[4:7], v[214:217], v[206:209], v[4:7]
	v_mfma_f32_16x16x32_bf16 v[0:3], v[222:225], v[206:209], v[0:3]
	s_barrier
	s_add_i32 s48, 0, 0x18000
	v_add_u32_e32 v164, s48, v151
	ds_read_b128 v[144:147], v164
	ds_read_b128 v[156:159], v164 offset:1024
	ds_read_b128 v[160:163], v164 offset:2048
	ds_read_b128 v[164:167], v164 offset:3072
	s_add_u32 s22, s22, 0x40000
	s_addc_u32 s23, s23, 0
	s_mov_b32 m0, s31
	v_lshl_add_u64 v[210:211], s[22:23], 0, v[128:129]
	ds_read_b128 v[168:171], v154 offset:32768
	ds_read_b128 v[172:175], v154 offset:33792
	ds_read_b128 v[182:185], v154 offset:34816
	ds_read_b128 v[190:193], v154 offset:35840
	ds_read_b128 v[194:197], v154 offset:36864
	ds_read_b128 v[198:201], v154 offset:37888
	ds_read_b128 v[202:205], v154 offset:38912
	ds_read_b128 v[206:209], v154 offset:39936
	global_load_lds_dwordx4 v[210:211], off
	v_lshl_add_u64 v[210:211], s[22:23], 0, v[132:133]
	s_mov_b32 m0, s34
	s_nop 0
	global_load_lds_dwordx4 v[210:211], off
	s_add_i32 s22, 0, 0x1c000
	v_add_u32_e32 v179, s22, v151
	s_waitcnt lgkmcnt(8)
	ds_read_b128 v[210:213], v179
	ds_read_b128 v[214:217], v179 offset:1024
	ds_read_b128 v[218:221], v179 offset:2048
	ds_read_b128 v[222:225], v179 offset:3072
	s_waitcnt vmcnt(8) lgkmcnt(0)
	s_barrier
	v_mfma_f32_16x16x32_bf16 v[124:127], v[144:147], v[168:171], v[124:127]
	v_mfma_f32_16x16x32_bf16 v[120:123], v[160:163], v[168:171], v[120:123]
	v_mfma_f32_16x16x32_bf16 v[112:115], v[144:147], v[182:185], v[112:115]
	v_mfma_f32_16x16x32_bf16 v[104:107], v[160:163], v[182:185], v[104:107]
	v_mfma_f32_16x16x32_bf16 v[96:99], v[144:147], v[194:197], v[96:99]
	v_mfma_f32_16x16x32_bf16 v[88:91], v[160:163], v[194:197], v[88:91]
	v_mfma_f32_16x16x32_bf16 v[80:83], v[144:147], v[202:205], v[80:83]
	v_mfma_f32_16x16x32_bf16 v[72:75], v[160:163], v[202:205], v[72:75]
	v_mfma_f32_16x16x32_bf16 v[124:127], v[156:159], v[172:175], v[124:127]
	v_mfma_f32_16x16x32_bf16 v[120:123], v[164:167], v[172:175], v[120:123]
	v_mfma_f32_16x16x32_bf16 v[112:115], v[156:159], v[190:193], v[112:115]
	v_mfma_f32_16x16x32_bf16 v[104:107], v[164:167], v[190:193], v[104:107]
	v_mfma_f32_16x16x32_bf16 v[96:99], v[156:159], v[198:201], v[96:99]
	v_mfma_f32_16x16x32_bf16 v[88:91], v[164:167], v[198:201], v[88:91]
	v_mfma_f32_16x16x32_bf16 v[80:83], v[156:159], v[206:209], v[80:83]
	v_mfma_f32_16x16x32_bf16 v[72:75], v[164:167], v[206:209], v[72:75]
	v_mfma_f32_16x16x32_bf16 v[116:119], v[210:213], v[168:171], v[116:119]
	v_mfma_f32_16x16x32_bf16 v[108:111], v[218:221], v[168:171], v[108:111]
	v_mfma_f32_16x16x32_bf16 v[100:103], v[210:213], v[182:185], v[100:103]
	v_mfma_f32_16x16x32_bf16 v[92:95], v[218:221], v[182:185], v[92:95]
	v_mfma_f32_16x16x32_bf16 v[84:87], v[210:213], v[194:197], v[84:87]
	v_mfma_f32_16x16x32_bf16 v[76:79], v[218:221], v[194:197], v[76:79]
	v_mfma_f32_16x16x32_bf16 v[68:71], v[210:213], v[202:205], v[68:71]
	v_mfma_f32_16x16x32_bf16 v[64:67], v[218:221], v[202:205], v[64:67]
	v_mfma_f32_16x16x32_bf16 v[116:119], v[214:217], v[172:175], v[116:119]
	v_mfma_f32_16x16x32_bf16 v[108:111], v[222:225], v[172:175], v[108:111]
	v_mfma_f32_16x16x32_bf16 v[100:103], v[214:217], v[190:193], v[100:103]
	v_mfma_f32_16x16x32_bf16 v[92:95], v[222:225], v[190:193], v[92:95]
	v_mfma_f32_16x16x32_bf16 v[84:87], v[214:217], v[198:201], v[84:87]
	v_mfma_f32_16x16x32_bf16 v[76:79], v[222:225], v[198:201], v[76:79]
	v_mfma_f32_16x16x32_bf16 v[68:71], v[214:217], v[206:209], v[68:71]
	v_mfma_f32_16x16x32_bf16 v[64:67], v[222:225], v[206:209], v[64:67]
	s_barrier
; #define PG8_STAGE(bufoff, gbase, voff) do { _Pragma("unroll") for (int _i = 0; _i < 2; ++_i) \
;         __builtin_amdgcn_global_load_lds((const unsigned*)((const char*)(gbase) + (voff)[_i]), (PG8_LAS unsigned*)(lds + (bufoff) + ldsw + _i * 8192), 16, 0, 0); } while (0)
; #define PG8_LDA(dst, b, h) do { _Pragma("unroll") for (int m = 0; m < 4; ++m) _Pragma("unroll") for (int k = 0; k < 2; ++k) dst[m][k] = *(const PG8_LAS bf16x8*)(lds + PG8_SA(b, h) + aoff + m * 2048 + k * 1024); } while (0)
; #define PG8_MMA(ai, bj, At, Bt) do { __builtin_amdgcn_s_setprio(1); _Pragma("unroll") for (int m = 0; m < 4; ++m) _Pragma("unroll") for (int n = 0; n < 2; ++n) _Pragma("unroll") for (int k = 0; k < 2; ++k) \
;         acc[ai][bj][m][n] = __builtin_amdgcn_mfma_f32_16x16x32_bf16(Bt[n][k], At[m][k], acc[ai][bj][m][n], 0, 0, 0); __builtin_amdgcn_s_setprio(0); } while (0)
; #define PG8_WAIT_V(n) asm volatile("s_waitcnt vmcnt(" #n ")" ::: "memory")
; #define PG8_WAIT_L(n) asm volatile("s_waitcnt lgkmcnt(" #n ")" ::: "memory")
; #define PG8_BAR __builtin_amdgcn_s_barrier()
; #define PG8_SCHED __builtin_amdgcn_sched_barrier(0)
; template <class Epi, class Sched>
; __device__ __forceinline__ void gemm_phase(PG8_LAS unsigned char* lds, const Gemm g, const Sched& S, const Epi& E) {
;     ...
;             PG8_LDA(At, 1, 1); PG8_STAGE(PG8_SA(1, 0), a3, voffA);
;             PG8_BAR; PG8_WAIT_L(0); PG8_MMA(1, 0, At, B0); PG8_BAR; PG8_SCHED;
;             PG8_STAGE(PG8_SB(1, 1), b3 + hstep, voffB);
;             PG8_WAIT_V(6); PG8_BAR; PG8_MMA(1, 1, At, B1); PG8_BAR;
;         }
	ds_read_b128 v[168:171], v154 offset:49152
	ds_read_b128 v[172:175], v154 offset:50176
	ds_read_b128 v[182:185], v154 offset:51200
	ds_read_b128 v[190:193], v154 offset:52224
	ds_read_b128 v[194:197], v154 offset:53248
	ds_read_b128 v[198:201], v154 offset:54272
	ds_read_b128 v[202:205], v154 offset:55296
	ds_read_b128 v[206:209], v154 offset:56320
	s_add_i32 s23, s48, s29
	v_lshl_add_u64 v[148:149], v[148:149], 0, s[6:7]
	s_mov_b32 m0, s23
	s_nop 0
	global_load_lds_dwordx4 v[148:149], off
	v_lshl_add_u64 v[148:149], v[186:187], 0, s[6:7]
	s_add_i32 m0, s23, 0x2000
	s_nop 0
	global_load_lds_dwordx4 v[148:149], off
	s_nop 1
	s_mov_b32 m0, s36
	v_lshl_add_u64 v[148:149], v[226:227], 0, s[6:7]
	global_load_lds_dwordx4 v[148:149], off
	v_lshl_add_u64 v[148:149], v[228:229], 0, s[6:7]
	s_mov_b32 m0, s37
	s_nop 0
	global_load_lds_dwordx4 v[148:149], off
	s_add_u32 s20, s20, 0x40080
	s_addc_u32 s21, s21, 0
	s_add_i32 s22, s22, s29
	v_lshl_add_u64 v[246:247], s[20:21], 0, v[130:131]
	s_mov_b32 m0, s22
	s_nop 0
	global_load_lds_dwordx4 v[246:247], off
	v_lshl_add_u64 v[246:247], s[20:21], 0, v[134:135]
	s_add_i32 m0, s22, 0x2000
	s_nop 0
	global_load_lds_dwordx4 v[246:247], off
	s_waitcnt vmcnt(8) lgkmcnt(0)
	s_barrier
	v_mfma_f32_16x16x32_bf16 v[60:63], v[144:147], v[168:171], v[60:63]
	v_mfma_f32_16x16x32_bf16 v[56:59], v[160:163], v[168:171], v[56:59]
	v_mfma_f32_16x16x32_bf16 v[48:51], v[144:147], v[182:185], v[48:51]
	v_mfma_f32_16x16x32_bf16 v[40:43], v[160:163], v[182:185], v[40:43]
	v_mfma_f32_16x16x32_bf16 v[32:35], v[144:147], v[194:197], v[32:35]
	v_mfma_f32_16x16x32_bf16 v[24:27], v[160:163], v[194:197], v[24:27]
	v_mfma_f32_16x16x32_bf16 v[16:19], v[144:147], v[202:205], v[16:19]
	v_mfma_f32_16x16x32_bf16 v[8:11], v[160:163], v[202:205], v[8:11]
	v_mfma_f32_16x16x32_bf16 v[60:63], v[156:159], v[172:175], v[60:63]
	v_mfma_f32_16x16x32_bf16 v[56:59], v[164:167], v[172:175], v[56:59]
	v_mfma_f32_16x16x32_bf16 v[48:51], v[156:159], v[190:193], v[48:51]
	v_mfma_f32_16x16x32_bf16 v[40:43], v[164:167], v[190:193], v[40:43]
	v_mfma_f32_16x16x32_bf16 v[32:35], v[156:159], v[198:201], v[32:35]
	v_mfma_f32_16x16x32_bf16 v[24:27], v[164:167], v[198:201], v[24:27]
	v_mfma_f32_16x16x32_bf16 v[16:19], v[156:159], v[206:209], v[16:19]
	v_mfma_f32_16x16x32_bf16 v[8:11], v[164:167], v[206:209], v[8:11]
	v_mfma_f32_16x16x32_bf16 v[52:55], v[210:213], v[168:171], v[52:55]
	v_mfma_f32_16x16x32_bf16 v[44:47], v[218:221], v[168:171], v[44:47]
	v_mfma_f32_16x16x32_bf16 v[36:39], v[210:213], v[182:185], v[36:39]
	v_mfma_f32_16x16x32_bf16 v[28:31], v[218:221], v[182:185], v[28:31]
	v_mfma_f32_16x16x32_bf16 v[20:23], v[210:213], v[194:197], v[20:23]
	v_mfma_f32_16x16x32_bf16 v[12:15], v[218:221], v[194:197], v[12:15]
	v_mfma_f32_16x16x32_bf16 v[4:7], v[210:213], v[202:205], v[4:7]
	v_mfma_f32_16x16x32_bf16 v[0:3], v[218:221], v[202:205], v[0:3]
	v_mfma_f32_16x16x32_bf16 v[52:55], v[214:217], v[172:175], v[52:55]
	v_mfma_f32_16x16x32_bf16 v[44:47], v[222:225], v[172:175], v[44:47]
	v_mfma_f32_16x16x32_bf16 v[36:39], v[214:217], v[190:193], v[36:39]
	v_mfma_f32_16x16x32_bf16 v[28:31], v[222:225], v[190:193], v[28:31]
	v_mfma_f32_16x16x32_bf16 v[20:23], v[214:217], v[198:201], v[20:23]
	v_mfma_f32_16x16x32_bf16 v[12:15], v[222:225], v[198:201], v[12:15]
	v_mfma_f32_16x16x32_bf16 v[4:7], v[214:217], v[206:209], v[4:7]
	v_mfma_f32_16x16x32_bf16 v[0:3], v[222:225], v[206:209], v[0:3]
	s_barrier
	s_add_i32 s47, s47, 2
	s_add_u32 s18, s18, 0x100
	s_addc_u32 s19, s19, 0
	s_add_u32 s45, s45, 0x100
	s_addc_u32 s46, s46, 0
	s_cmp_gt_u32 s47, 13

; #define PG8_STAGE(bufoff, gbase, voff) do { _Pragma("unroll") for (int _i = 0; _i < 2; ++_i) \
;         __builtin_amdgcn_global_load_lds((const unsigned*)((const char*)(gbase) + (voff)[_i]), (PG8_LAS unsigned*)(lds + (bufoff) + ldsw + _i * 8192), 16, 0, 0); } while (0)
; #define PG8_LDA(dst, b, h) do { _Pragma("unroll") for (int m = 0; m < 4; ++m) _Pragma("unroll") for (int k = 0; k < 2; ++k) dst[m][k] = *(const PG8_LAS bf16x8*)(lds + PG8_SA(b, h) + aoff + m * 2048 + k * 1024); } while (0)
; #define PG8_LDB(dst, b, h) do { _Pragma("unroll") for (int n = 0; n < 2; ++n) _Pragma("unroll") for (int k = 0; k < 2; ++k) dst[n][k] = *(const PG8_LAS bf16x8*)(lds + PG8_SB(b, h) + boff + n * 2048 + k * 1024); } while (0)
; template <class Epi, class Sched>
; __device__ __forceinline__ void gemm_phase(PG8_LAS unsigned char* lds, const Gemm g, const Sched& S, const Epi& E) {
;     ...
;         const bool has_next = S.next(ui + 1, nxt);
;         const char* nA = has_next ? (const char*)g.A + (size_t)nxt.pm * tstep : cA; const char* nB = has_next ? (const char*)g.Bt + (size_t)nxt.pn * tstep : cB;
;         for (int t = 0; t < nt; t += 2) {
;             const bool last = (t == nt - 2);
;             const char* a1 = cA + (size_t)(t + 1) * kstep;
;             const char* a2 = last ? nA : cA + (size_t)(t + 2) * kstep; const char* b2 = last ? nB : cB + (size_t)(t + 2) * kstep;
;             const char* a3 = a2 + kstep; const char* b3 = b2 + kstep;
;             if (last && has_next) S.a_ready(nxt);
;             PG8_LDB(B0, 0, 0); PG8_SCHED; PG8_LDA(At, 0, 0); PG8_STAGE(PG8_SA(1, 1), a1 + hstep, voffA);
;             PG8_WAIT_L(8); PG8_BAR; PG8_WAIT_L(0); PG8_MMA(0, 0, At, B0); PG8_BAR; PG8_SCHED;
;             PG8_LDB(B1, 0, 1); PG8_STAGE(PG8_SB(0, 0), b2, voffB);
;             PG8_BAR; PG8_WAIT_L(0); PG8_MMA(0, 1, At, B1); PG8_BAR;
;             PG8_LDA(At, 0, 1); PG8_STAGE(PG8_SA(0, 0), a2, voffA);
;             PG8_BAR; PG8_WAIT_L(0); PG8_MMA(1, 0, At, B0); PG8_BAR; PG8_SCHED;
;             PG8_STAGE(PG8_SB(0, 1), b2 + hstep, voffB);
;             PG8_WAIT_V(6); PG8_BAR; PG8_MMA(1, 1, At, B1); PG8_BAR;
;     ...
;         for (int a = 0; a < 2; ++a)
; #pragma unroll
;             for (int b = 0; b < 2; ++b)
; #pragma unroll
;                 for (int m = 0; m < 4; ++m)
; #pragma unroll
;                     for (int n = 0; n < 2; ++n) acc[a][b][m][n] = (f32x4){0.f, 0.f, 0.f, 0.f};
.LBB0_1010:
	s_ashr_i32 s11, s10, 31
	v_cmp_lt_i64_e32 vcc, s[12:13], v[140:141]
	s_lshl_b64 s[12:13], s[10:11], 19
	s_add_u32 s12, s27, s12
	s_addc_u32 s13, s28, s13
	s_and_b64 s[14:15], vcc, exec
	s_cselect_b32 s11, s13, s19
	s_cselect_b32 s43, s12, s18
	s_ashr_i32 s9, s8, 31
	s_lshl_b64 s[14:15], s[8:9], 19
	s_add_u32 s14, s94, s14
	s_addc_u32 s15, s95, s15
	s_and_b64 s[22:23], vcc, exec
	s_cselect_b32 s9, s15, s21
	s_cselect_b32 s44, s14, s20
	s_add_u32 s18, s18, 0x40080
	s_addc_u32 s19, s19, 0
	s_add_u32 s45, s20, 0x100
	s_addc_u32 s46, s21, 0
	s_mov_b32 s47, -2
	ds_read_b128 v[144:147], v153
	ds_read_b128 v[156:159], v153 offset:1024
	ds_read_b128 v[160:163], v153 offset:2048
	ds_read_b128 v[164:167], v153 offset:3072
	s_add_u32 s20, s18, 0xfffc0080
	s_addc_u32 s21, s19, -1
	s_cmp_eq_u32 s47, 12
	s_cselect_b32 s23, s11, s21
	s_cselect_b32 s22, s43, s20
	s_cselect_b32 s21, s9, s46
	s_cselect_b32 s20, s44, s45
	v_lshl_add_u64 v[148:149], s[18:19], 0, v[136:137]
	s_add_i32 m0, s17, 0xc000
	ds_read_b128 v[168:171], v154
	ds_read_b128 v[172:175], v154 offset:1024
	ds_read_b128 v[182:185], v154 offset:2048
	ds_read_b128 v[190:193], v154 offset:3072
	ds_read_b128 v[194:197], v154 offset:4096
	ds_read_b128 v[198:201], v154 offset:5120
	ds_read_b128 v[202:205], v154 offset:6144
	ds_read_b128 v[206:209], v154 offset:7168
	global_load_lds_dwordx4 v[148:149], off
	v_lshl_add_u64 v[148:149], s[18:19], 0, v[138:139]
	s_add_i32 m0, s17, 0xe000
	s_nop 0
	global_load_lds_dwordx4 v[148:149], off
	s_waitcnt lgkmcnt(8)
	ds_read_b128 v[210:213], v155
	ds_read_b128 v[214:217], v155 offset:1024
	ds_read_b128 v[218:221], v155 offset:2048
	ds_read_b128 v[222:225], v155 offset:3072
	s_waitcnt vmcnt(8) lgkmcnt(0)
	s_barrier
	v_mfma_f32_16x16x32_bf16 v[124:127], v[144:147], v[168:171], 0
	v_mfma_f32_16x16x32_bf16 v[120:123], v[160:163], v[168:171], 0
	v_mfma_f32_16x16x32_bf16 v[108:111], v[144:147], v[182:185], 0
	v_mfma_f32_16x16x32_bf16 v[104:107], v[160:163], v[182:185], 0
	v_mfma_f32_16x16x32_bf16 v[92:95], v[144:147], v[194:197], 0
	v_mfma_f32_16x16x32_bf16 v[88:91], v[160:163], v[194:197], 0
	v_mfma_f32_16x16x32_bf16 v[76:79], v[144:147], v[202:205], 0
	v_mfma_f32_16x16x32_bf16 v[72:75], v[160:163], v[202:205], 0
	v_mfma_f32_16x16x32_bf16 v[124:127], v[156:159], v[172:175], v[124:127]
	v_mfma_f32_16x16x32_bf16 v[120:123], v[164:167], v[172:175], v[120:123]
	v_mfma_f32_16x16x32_bf16 v[108:111], v[156:159], v[190:193], v[108:111]
	v_mfma_f32_16x16x32_bf16 v[104:107], v[164:167], v[190:193], v[104:107]
	v_mfma_f32_16x16x32_bf16 v[92:95], v[156:159], v[198:201], v[92:95]
	v_mfma_f32_16x16x32_bf16 v[88:91], v[164:167], v[198:201], v[88:91]
	v_mfma_f32_16x16x32_bf16 v[76:79], v[156:159], v[206:209], v[76:79]
	v_mfma_f32_16x16x32_bf16 v[72:75], v[164:167], v[206:209], v[72:75]
	v_mfma_f32_16x16x32_bf16 v[116:119], v[210:213], v[168:171], 0
	v_mfma_f32_16x16x32_bf16 v[112:115], v[218:221], v[168:171], 0
	v_mfma_f32_16x16x32_bf16 v[100:103], v[210:213], v[182:185], 0
	v_mfma_f32_16x16x32_bf16 v[96:99], v[218:221], v[182:185], 0
	v_mfma_f32_16x16x32_bf16 v[84:87], v[210:213], v[194:197], 0
	v_mfma_f32_16x16x32_bf16 v[80:83], v[218:221], v[194:197], 0
	v_mfma_f32_16x16x32_bf16 v[68:71], v[210:213], v[202:205], 0
	v_mfma_f32_16x16x32_bf16 v[64:67], v[218:221], v[202:205], 0
	v_mfma_f32_16x16x32_bf16 v[116:119], v[214:217], v[172:175], v[116:119]
	v_mfma_f32_16x16x32_bf16 v[112:115], v[222:225], v[172:175], v[112:115]
	v_mfma_f32_16x16x32_bf16 v[100:103], v[214:217], v[190:193], v[100:103]
	v_mfma_f32_16x16x32_bf16 v[96:99], v[222:225], v[190:193], v[96:99]
	v_mfma_f32_16x16x32_bf16 v[84:87], v[214:217], v[198:201], v[84:87]
	v_mfma_f32_16x16x32_bf16 v[80:83], v[222:225], v[198:201], v[80:83]
	v_mfma_f32_16x16x32_bf16 v[68:71], v[214:217], v[206:209], v[68:71]
	v_mfma_f32_16x16x32_bf16 v[64:67], v[222:225], v[206:209], v[64:67]
	s_barrier
	ds_read_b128 v[168:171], v154 offset:16384
	ds_read_b128 v[172:175], v154 offset:17408
	ds_read_b128 v[182:185], v154 offset:18432
	ds_read_b128 v[190:193], v154 offset:19456
	ds_read_b128 v[194:197], v154 offset:20480
	ds_read_b128 v[198:201], v154 offset:21504
	ds_read_b128 v[202:205], v154 offset:22528
	ds_read_b128 v[206:209], v154 offset:23552
	s_add_i32 s48, s39, s29
	v_lshl_add_u64 v[148:149], s[20:21], 0, v[130:131]
	s_mov_b32 m0, s48
	s_nop 0
	global_load_lds_dwordx4 v[148:149], off
	v_lshl_add_u64 v[186:187], s[20:21], 0, v[134:135]
	s_add_i32 m0, s48, 0x2000
	s_nop 0
	global_load_lds_dwordx4 v[186:187], off
	s_nop 1
	s_mov_b32 m0, s17
	v_lshl_add_u64 v[226:227], s[22:23], 0, v[128:129]
	global_load_lds_dwordx4 v[226:227], off
	v_lshl_add_u64 v[228:229], s[22:23], 0, v[132:133]
	s_mov_b32 m0, s30
	s_nop 0
	global_load_lds_dwordx4 v[228:229], off
	s_add_u32 s48, s20, 0x40000
	s_addc_u32 s49, s21, 0
	s_add_i32 s50, s40, s29
	v_lshl_add_u64 v[246:247], s[48:49], 0, v[130:131]
	s_mov_b32 m0, s50
	s_nop 0
	global_load_lds_dwordx4 v[246:247], off
	v_lshl_add_u64 v[246:247], s[48:49], 0, v[134:135]
	s_add_i32 m0, s50, 0x2000
	s_nop 0
	global_load_lds_dwordx4 v[246:247], off
	s_waitcnt vmcnt(8) lgkmcnt(0)
	s_barrier
; #define PG8_STAGE(bufoff, gbase, voff) do { _Pragma("unroll") for (int _i = 0; _i < 2; ++_i) \
;         __builtin_amdgcn_global_load_lds((const unsigned*)((const char*)(gbase) + (voff)[_i]), (PG8_LAS unsigned*)(lds + (bufoff) + ldsw + _i * 8192), 16, 0, 0); } while (0)
; #define PG8_LDA(dst, b, h) do { _Pragma("unroll") for (int m = 0; m < 4; ++m) _Pragma("unroll") for (int k = 0; k < 2; ++k) dst[m][k] = *(const PG8_LAS bf16x8*)(lds + PG8_SA(b, h) + aoff + m * 2048 + k * 1024); } while (0)
; #define PG8_LDB(dst, b, h) do { _Pragma("unroll") for (int n = 0; n < 2; ++n) _Pragma("unroll") for (int k = 0; k < 2; ++k) dst[n][k] = *(const PG8_LAS bf16x8*)(lds + PG8_SB(b, h) + boff + n * 2048 + k * 1024); } while (0)
; #define PG8_MMA(ai, bj, At, Bt) do { __builtin_amdgcn_s_setprio(1); _Pragma("unroll") for (int m = 0; m < 4; ++m) _Pragma("unroll") for (int n = 0; n < 2; ++n) _Pragma("unroll") for (int k = 0; k < 2; ++k) \
;         acc[ai][bj][m][n] = __builtin_amdgcn_mfma_f32_16x16x32_bf16(Bt[n][k], At[m][k], acc[ai][bj][m][n], 0, 0, 0); __builtin_amdgcn_s_setprio(0); } while (0)
; #define PG8_WAIT_V(n) asm volatile("s_waitcnt vmcnt(" #n ")" ::: "memory")
; #define PG8_WAIT_L(n) asm volatile("s_waitcnt lgkmcnt(" #n ")" ::: "memory")
; #define PG8_BAR __builtin_amdgcn_s_barrier()
; #define PG8_SCHED __builtin_amdgcn_sched_barrier(0)
; template <class Epi, class Sched>
; __device__ __forceinline__ void gemm_phase(PG8_LAS unsigned char* lds, const Gemm g, const Sched& S, const Epi& E) {
;     ...
;             PG8_BAR; PG8_WAIT_L(0); PG8_MMA(1, 0, At, B0); PG8_BAR; PG8_SCHED;
;             PG8_STAGE(PG8_SB(0, 1), b2 + hstep, voffB);
;             PG8_WAIT_V(6); PG8_BAR; PG8_MMA(1, 1, At, B1); PG8_BAR;
;             PG8_LDB(B0, 1, 0); PG8_SCHED; PG8_LDA(At, 1, 0); PG8_STAGE(PG8_SA(0, 1), a2 + hstep, voffA);
;             PG8_WAIT_L(8); PG8_BAR; PG8_WAIT_L(0); PG8_MMA(0, 0, At, B0); PG8_BAR; PG8_SCHED;
;             PG8_LDB(B1, 1, 1); PG8_STAGE(PG8_SB(1, 0), b3, voffB);
;             PG8_BAR; PG8_WAIT_L(0); PG8_MMA(0, 1, At, B1); PG8_BAR;
	v_mfma_f32_16x16x32_bf16 v[60:63], v[144:147], v[168:171], 0
	v_mfma_f32_16x16x32_bf16 v[56:59], v[160:163], v[168:171], 0
	v_mfma_f32_16x16x32_bf16 v[44:47], v[144:147], v[182:185], 0
	v_mfma_f32_16x16x32_bf16 v[40:43], v[160:163], v[182:185], 0
	v_mfma_f32_16x16x32_bf16 v[28:31], v[144:147], v[194:197], 0
	v_mfma_f32_16x16x32_bf16 v[24:27], v[160:163], v[194:197], 0
	v_mfma_f32_16x16x32_bf16 v[12:15], v[144:147], v[202:205], 0
	v_mfma_f32_16x16x32_bf16 v[8:11], v[160:163], v[202:205], 0
	v_mfma_f32_16x16x32_bf16 v[60:63], v[156:159], v[172:175], v[60:63]
	v_mfma_f32_16x16x32_bf16 v[56:59], v[164:167], v[172:175], v[56:59]
	v_mfma_f32_16x16x32_bf16 v[44:47], v[156:159], v[190:193], v[44:47]
	v_mfma_f32_16x16x32_bf16 v[40:43], v[164:167], v[190:193], v[40:43]
	v_mfma_f32_16x16x32_bf16 v[28:31], v[156:159], v[198:201], v[28:31]
	v_mfma_f32_16x16x32_bf16 v[24:27], v[164:167], v[198:201], v[24:27]
	v_mfma_f32_16x16x32_bf16 v[12:15], v[156:159], v[206:209], v[12:15]
	v_mfma_f32_16x16x32_bf16 v[8:11], v[164:167], v[206:209], v[8:11]
	v_mfma_f32_16x16x32_bf16 v[52:55], v[210:213], v[168:171], 0
	v_mfma_f32_16x16x32_bf16 v[48:51], v[218:221], v[168:171], 0
	v_mfma_f32_16x16x32_bf16 v[36:39], v[210:213], v[182:185], 0
	v_mfma_f32_16x16x32_bf16 v[32:35], v[218:221], v[182:185], 0
	v_mfma_f32_16x16x32_bf16 v[20:23], v[210:213], v[194:197], 0
	v_mfma_f32_16x16x32_bf16 v[16:19], v[218:221], v[194:197], 0
	v_mfma_f32_16x16x32_bf16 v[4:7], v[210:213], v[202:205], 0
	v_mfma_f32_16x16x32_bf16 v[0:3], v[218:221], v[202:205], 0
	v_mfma_f32_16x16x32_bf16 v[52:55], v[214:217], v[172:175], v[52:55]
	v_mfma_f32_16x16x32_bf16 v[48:51], v[222:225], v[172:175], v[48:51]
	v_mfma_f32_16x16x32_bf16 v[36:39], v[214:217], v[190:193], v[36:39]
	v_mfma_f32_16x16x32_bf16 v[32:35], v[222:225], v[190:193], v[32:35]
	v_mfma_f32_16x16x32_bf16 v[20:23], v[214:217], v[198:201], v[20:23]
	v_mfma_f32_16x16x32_bf16 v[16:19], v[222:225], v[198:201], v[16:19]
	v_mfma_f32_16x16x32_bf16 v[4:7], v[214:217], v[206:209], v[4:7]
	v_mfma_f32_16x16x32_bf16 v[0:3], v[222:225], v[206:209], v[0:3]
	s_barrier
	s_add_i32 s48, 0, 0x18000
	v_add_u32_e32 v164, s48, v151
	ds_read_b128 v[144:147], v164
	ds_read_b128 v[156:159], v164 offset:1024
	ds_read_b128 v[160:163], v164 offset:2048
	ds_read_b128 v[164:167], v164 offset:3072
	s_add_u32 s22, s22, 0x40000
	s_addc_u32 s23, s23, 0
	s_mov_b32 m0, s31
	v_lshl_add_u64 v[210:211], s[22:23], 0, v[128:129]
	ds_read_b128 v[168:171], v154 offset:32768
	ds_read_b128 v[172:175], v154 offset:33792
	ds_read_b128 v[182:185], v154 offset:34816
	ds_read_b128 v[190:193], v154 offset:35840
	ds_read_b128 v[194:197], v154 offset:36864
	ds_read_b128 v[198:201], v154 offset:37888
	ds_read_b128 v[202:205], v154 offset:38912
	ds_read_b128 v[206:209], v154 offset:39936
	global_load_lds_dwordx4 v[210:211], off
	v_lshl_add_u64 v[210:211], s[22:23], 0, v[132:133]
	s_mov_b32 m0, s34
	s_nop 0
	global_load_lds_dwordx4 v[210:211], off
	s_add_i32 s22, 0, 0x1c000
	v_add_u32_e32 v179, s22, v151
	s_waitcnt lgkmcnt(8)
	ds_read_b128 v[210:213], v179
	ds_read_b128 v[214:217], v179 offset:1024
	ds_read_b128 v[218:221], v179 offset:2048
	ds_read_b128 v[222:225], v179 offset:3072
	s_waitcnt vmcnt(8) lgkmcnt(0)
	s_barrier
	v_mfma_f32_16x16x32_bf16 v[124:127], v[144:147], v[168:171], v[124:127]
	v_mfma_f32_16x16x32_bf16 v[120:123], v[160:163], v[168:171], v[120:123]
	v_mfma_f32_16x16x32_bf16 v[108:111], v[144:147], v[182:185], v[108:111]
	v_mfma_f32_16x16x32_bf16 v[104:107], v[160:163], v[182:185], v[104:107]
	v_mfma_f32_16x16x32_bf16 v[92:95], v[144:147], v[194:197], v[92:95]
	v_mfma_f32_16x16x32_bf16 v[88:91], v[160:163], v[194:197], v[88:91]
	v_mfma_f32_16x16x32_bf16 v[76:79], v[144:147], v[202:205], v[76:79]
	v_mfma_f32_16x16x32_bf16 v[72:75], v[160:163], v[202:205], v[72:75]
	v_mfma_f32_16x16x32_bf16 v[124:127], v[156:159], v[172:175], v[124:127]
	v_mfma_f32_16x16x32_bf16 v[120:123], v[164:167], v[172:175], v[120:123]
	v_mfma_f32_16x16x32_bf16 v[108:111], v[156:159], v[190:193], v[108:111]
	v_mfma_f32_16x16x32_bf16 v[104:107], v[164:167], v[190:193], v[104:107]
	v_mfma_f32_16x16x32_bf16 v[92:95], v[156:159], v[198:201], v[92:95]
	v_mfma_f32_16x16x32_bf16 v[88:91], v[164:167], v[198:201], v[88:91]
	v_mfma_f32_16x16x32_bf16 v[76:79], v[156:159], v[206:209], v[76:79]
	v_mfma_f32_16x16x32_bf16 v[72:75], v[164:167], v[206:209], v[72:75]
	v_mfma_f32_16x16x32_bf16 v[116:119], v[210:213], v[168:171], v[116:119]
	v_mfma_f32_16x16x32_bf16 v[112:115], v[218:221], v[168:171], v[112:115]
	v_mfma_f32_16x16x32_bf16 v[100:103], v[210:213], v[182:185], v[100:103]
	v_mfma_f32_16x16x32_bf16 v[96:99], v[218:221], v[182:185], v[96:99]
	v_mfma_f32_16x16x32_bf16 v[84:87], v[210:213], v[194:197], v[84:87]
	v_mfma_f32_16x16x32_bf16 v[80:83], v[218:221], v[194:197], v[80:83]
	v_mfma_f32_16x16x32_bf16 v[68:71], v[210:213], v[202:205], v[68:71]
	v_mfma_f32_16x16x32_bf16 v[64:67], v[218:221], v[202:205], v[64:67]
	v_mfma_f32_16x16x32_bf16 v[116:119], v[214:217], v[172:175], v[116:119]
	v_mfma_f32_16x16x32_bf16 v[112:115], v[222:225], v[172:175], v[112:115]
	v_mfma_f32_16x16x32_bf16 v[100:103], v[214:217], v[190:193], v[100:103]
	v_mfma_f32_16x16x32_bf16 v[96:99], v[222:225], v[190:193], v[96:99]
	v_mfma_f32_16x16x32_bf16 v[84:87], v[214:217], v[198:201], v[84:87]
	v_mfma_f32_16x16x32_bf16 v[80:83], v[222:225], v[198:201], v[80:83]
	v_mfma_f32_16x16x32_bf16 v[68:71], v[214:217], v[206:209], v[68:71]
	v_mfma_f32_16x16x32_bf16 v[64:67], v[222:225], v[206:209], v[64:67]
	s_barrier
; #define PG8_STAGE(bufoff, gbase, voff) do { _Pragma("unroll") for (int _i = 0; _i < 2; ++_i) \
;         __builtin_amdgcn_global_load_lds((const unsigned*)((const char*)(gbase) + (voff)[_i]), (PG8_LAS unsigned*)(lds + (bufoff) + ldsw + _i * 8192), 16, 0, 0); } while (0)
; #define PG8_LDA(dst, b, h) do { _Pragma("unroll") for (int m = 0; m < 4; ++m) _Pragma("unroll") for (int k = 0; k < 2; ++k) dst[m][k] = *(const PG8_LAS bf16x8*)(lds + PG8_SA(b, h) + aoff + m * 2048 + k * 1024); } while (0)
; #define PG8_MMA(ai, bj, At, Bt) do { __builtin_amdgcn_s_setprio(1); _Pragma("unroll") for (int m = 0; m < 4; ++m) _Pragma("unroll") for (int n = 0; n < 2; ++n) _Pragma("unroll") for (int k = 0; k < 2; ++k) \
;         acc[ai][bj][m][n] = __builtin_amdgcn_mfma_f32_16x16x32_bf16(Bt[n][k], At[m][k], acc[ai][bj][m][n], 0, 0, 0); __builtin_amdgcn_s_setprio(0); } while (0)
; #define PG8_WAIT_V(n) asm volatile("s_waitcnt vmcnt(" #n ")" ::: "memory")
; #define PG8_WAIT_L(n) asm volatile("s_waitcnt lgkmcnt(" #n ")" ::: "memory")
; #define PG8_BAR __builtin_amdgcn_s_barrier()
; #define PG8_SCHED __builtin_amdgcn_sched_barrier(0)
; template <class Epi, class Sched>
; __device__ __forceinline__ void gemm_phase(PG8_LAS unsigned char* lds, const Gemm g, const Sched& S, const Epi& E) {
;     ...
;             PG8_LDA(At, 1, 1); PG8_STAGE(PG8_SA(1, 0), a3, voffA);
;             PG8_BAR; PG8_WAIT_L(0); PG8_MMA(1, 0, At, B0); PG8_BAR; PG8_SCHED;
;             PG8_STAGE(PG8_SB(1, 1), b3 + hstep, voffB);
;             PG8_WAIT_V(6); PG8_BAR; PG8_MMA(1, 1, At, B1); PG8_BAR;
;         }
	ds_read_b128 v[168:171], v154 offset:49152
	ds_read_b128 v[172:175], v154 offset:50176
	ds_read_b128 v[182:185], v154 offset:51200
	ds_read_b128 v[190:193], v154 offset:52224
	ds_read_b128 v[194:197], v154 offset:53248
	ds_read_b128 v[198:201], v154 offset:54272
	ds_read_b128 v[202:205], v154 offset:55296
	ds_read_b128 v[206:209], v154 offset:56320
	s_add_i32 s23, s48, s29
	v_lshl_add_u64 v[148:149], v[148:149], 0, s[6:7]
	s_mov_b32 m0, s23
	s_nop 0
	global_load_lds_dwordx4 v[148:149], off
	v_lshl_add_u64 v[148:149], v[186:187], 0, s[6:7]
	s_add_i32 m0, s23, 0x2000
	s_nop 0
	global_load_lds_dwordx4 v[148:149], off
	s_nop 1
	s_mov_b32 m0, s36
	v_lshl_add_u64 v[148:149], v[226:227], 0, s[6:7]
	global_load_lds_dwordx4 v[148:149], off
	v_lshl_add_u64 v[148:149], v[228:229], 0, s[6:7]
	s_mov_b32 m0, s37
	s_nop 0
	global_load_lds_dwordx4 v[148:149], off
	s_add_u32 s20, s20, 0x40080
	s_addc_u32 s21, s21, 0
	s_add_i32 s22, s22, s29
	v_lshl_add_u64 v[246:247], s[20:21], 0, v[130:131]
	s_mov_b32 m0, s22
	s_nop 0
	global_load_lds_dwordx4 v[246:247], off
	v_lshl_add_u64 v[246:247], s[20:21], 0, v[134:135]
	s_add_i32 m0, s22, 0x2000
	s_nop 0
	global_load_lds_dwordx4 v[246:247], off
	s_waitcnt vmcnt(8) lgkmcnt(0)
	s_barrier
	v_mfma_f32_16x16x32_bf16 v[60:63], v[144:147], v[168:171], v[60:63]
	v_mfma_f32_16x16x32_bf16 v[56:59], v[160:163], v[168:171], v[56:59]
	v_mfma_f32_16x16x32_bf16 v[44:47], v[144:147], v[182:185], v[44:47]
	v_mfma_f32_16x16x32_bf16 v[40:43], v[160:163], v[182:185], v[40:43]
	v_mfma_f32_16x16x32_bf16 v[28:31], v[144:147], v[194:197], v[28:31]
	v_mfma_f32_16x16x32_bf16 v[24:27], v[160:163], v[194:197], v[24:27]
	v_mfma_f32_16x16x32_bf16 v[12:15], v[144:147], v[202:205], v[12:15]
	v_mfma_f32_16x16x32_bf16 v[8:11], v[160:163], v[202:205], v[8:11]
	v_mfma_f32_16x16x32_bf16 v[60:63], v[156:159], v[172:175], v[60:63]
	v_mfma_f32_16x16x32_bf16 v[56:59], v[164:167], v[172:175], v[56:59]
	v_mfma_f32_16x16x32_bf16 v[44:47], v[156:159], v[190:193], v[44:47]
	v_mfma_f32_16x16x32_bf16 v[40:43], v[164:167], v[190:193], v[40:43]
	v_mfma_f32_16x16x32_bf16 v[28:31], v[156:159], v[198:201], v[28:31]
	v_mfma_f32_16x16x32_bf16 v[24:27], v[164:167], v[198:201], v[24:27]
	v_mfma_f32_16x16x32_bf16 v[12:15], v[156:159], v[206:209], v[12:15]
	v_mfma_f32_16x16x32_bf16 v[8:11], v[164:167], v[206:209], v[8:11]
	v_mfma_f32_16x16x32_bf16 v[52:55], v[210:213], v[168:171], v[52:55]
	v_mfma_f32_16x16x32_bf16 v[48:51], v[218:221], v[168:171], v[48:51]
	v_mfma_f32_16x16x32_bf16 v[36:39], v[210:213], v[182:185], v[36:39]
	v_mfma_f32_16x16x32_bf16 v[32:35], v[218:221], v[182:185], v[32:35]
	v_mfma_f32_16x16x32_bf16 v[20:23], v[210:213], v[194:197], v[20:23]
	v_mfma_f32_16x16x32_bf16 v[16:19], v[218:221], v[194:197], v[16:19]
	v_mfma_f32_16x16x32_bf16 v[4:7], v[210:213], v[202:205], v[4:7]
	v_mfma_f32_16x16x32_bf16 v[0:3], v[218:221], v[202:205], v[0:3]
	v_mfma_f32_16x16x32_bf16 v[52:55], v[214:217], v[172:175], v[52:55]
	v_mfma_f32_16x16x32_bf16 v[48:51], v[222:225], v[172:175], v[48:51]
	v_mfma_f32_16x16x32_bf16 v[36:39], v[214:217], v[190:193], v[36:39]
	v_mfma_f32_16x16x32_bf16 v[32:35], v[222:225], v[190:193], v[32:35]
	v_mfma_f32_16x16x32_bf16 v[20:23], v[214:217], v[198:201], v[20:23]
	v_mfma_f32_16x16x32_bf16 v[16:19], v[222:225], v[198:201], v[16:19]
	v_mfma_f32_16x16x32_bf16 v[4:7], v[214:217], v[206:209], v[4:7]
	v_mfma_f32_16x16x32_bf16 v[0:3], v[222:225], v[206:209], v[0:3]
	s_barrier
	s_add_i32 s47, s47, 2
	s_add_u32 s18, s18, 0x100
	s_addc_u32 s19, s19, 0
	s_add_u32 s45, s45, 0x100
	s_addc_u32 s46, s46, 0
	s_cmp_gt_u32 s47, 13

; #define PG8_STAGE(bufoff, gbase, voff) do { _Pragma("unroll") for (int _i = 0; _i < 2; ++_i) \
;         __builtin_amdgcn_global_load_lds((const unsigned*)((const char*)(gbase) + (voff)[_i]), (PG8_LAS unsigned*)(lds + (bufoff) + ldsw + _i * 8192), 16, 0, 0); } while (0)
; #define PG8_LDA(dst, b, h) do { _Pragma("unroll") for (int m = 0; m < 4; ++m) _Pragma("unroll") for (int k = 0; k < 2; ++k) dst[m][k] = *(const PG8_LAS bf16x8*)(lds + PG8_SA(b, h) + aoff + m * 2048 + k * 1024); } while (0)
; #define PG8_LDB(dst, b, h) do { _Pragma("unroll") for (int n = 0; n < 2; ++n) _Pragma("unroll") for (int k = 0; k < 2; ++k) dst[n][k] = *(const PG8_LAS bf16x8*)(lds + PG8_SB(b, h) + boff + n * 2048 + k * 1024); } while (0)
; template <class Epi, class Sched>
; __device__ __forceinline__ void gemm_phase(PG8_LAS unsigned char* lds, const Gemm g, const Sched& S, const Epi& E) {
;     ...
;         const bool has_next = S.next(ui + 1, nxt);
;         const char* nA = has_next ? (const char*)g.A + (size_t)nxt.pm * tstep : cA; const char* nB = has_next ? (const char*)g.Bt + (size_t)nxt.pn * tstep : cB;
;         for (int t = 0; t < nt; t += 2) {
;             const bool last = (t == nt - 2);
;             const char* a1 = cA + (size_t)(t + 1) * kstep;
;             const char* a2 = last ? nA : cA + (size_t)(t + 2) * kstep; const char* b2 = last ? nB : cB + (size_t)(t + 2) * kstep;
;             const char* a3 = a2 + kstep; const char* b3 = b2 + kstep;
;             if (last && has_next) S.a_ready(nxt);
;             PG8_LDB(B0, 0, 0); PG8_SCHED; PG8_LDA(At, 0, 0); PG8_STAGE(PG8_SA(1, 1), a1 + hstep, voffA);
;             PG8_WAIT_L(8); PG8_BAR; PG8_WAIT_L(0); PG8_MMA(0, 0, At, B0); PG8_BAR; PG8_SCHED;
;             PG8_LDB(B1, 0, 1); PG8_STAGE(PG8_SB(0, 0), b2, voffB);
;             PG8_BAR; PG8_WAIT_L(0); PG8_MMA(0, 1, At, B1); PG8_BAR;
;             PG8_LDA(At, 0, 1); PG8_STAGE(PG8_SA(0, 0), a2, voffA);
;             PG8_BAR; PG8_WAIT_L(0); PG8_MMA(1, 0, At, B0); PG8_BAR; PG8_SCHED;
;             PG8_STAGE(PG8_SB(0, 1), b2 + hstep, voffB);
;             PG8_WAIT_V(6); PG8_BAR; PG8_MMA(1, 1, At, B1); PG8_BAR;
;     ...
;         for (int a = 0; a < 2; ++a)
; #pragma unroll
;             for (int b = 0; b < 2; ++b)
; #pragma unroll
;                 for (int m = 0; m < 4; ++m)
; #pragma unroll
;                     for (int n = 0; n < 2; ++n) acc[a][b][m][n] = (f32x4){0.f, 0.f, 0.f, 0.f};
.LBB0_1082:
	s_ashr_i32 s17, s16, 31
	v_cmp_lt_i64_e32 vcc, s[18:19], v[140:141]
	s_lshl_b64 s[18:19], s[16:17], 19
	s_add_u32 s18, s35, s18
	s_addc_u32 s19, s36, s19
	s_and_b64 s[20:21], vcc, exec
	s_cselect_b32 s17, s19, s25
	s_cselect_b32 s52, s18, s24
	s_ashr_i32 s15, s14, 31
	s_lshl_b64 s[20:21], s[14:15], 19
	s_add_u32 s20, s72, s20
	s_addc_u32 s21, s73, s21
	s_and_b64 s[28:29], vcc, exec
	s_cselect_b32 s15, s21, s27
	s_cselect_b32 s53, s20, s26
	s_add_u32 s24, s24, 0x40080
	s_addc_u32 s25, s25, 0
	s_add_u32 s54, s26, 0x100
	s_addc_u32 s55, s27, 0
	s_mov_b32 s56, -2
	ds_read_b128 v[152:155], v149
	ds_read_b128 v[156:159], v149 offset:1024
	ds_read_b128 v[160:163], v149 offset:2048
	ds_read_b128 v[164:167], v149 offset:3072
	s_add_u32 s26, s24, 0xfffc0080
	s_addc_u32 s27, s25, -1
	s_cmp_eq_u32 s56, 12
	s_cselect_b32 s29, s17, s27
	s_cselect_b32 s28, s52, s26
	s_cselect_b32 s27, s15, s55
	s_cselect_b32 s26, s53, s54
	v_lshl_add_u64 v[144:145], s[24:25], 0, v[136:137]
	s_add_i32 m0, s23, 0xc000
	ds_read_b128 v[168:171], v150
	ds_read_b128 v[172:175], v150 offset:1024
	ds_read_b128 v[182:185], v150 offset:2048
	ds_read_b128 v[190:193], v150 offset:3072
	ds_read_b128 v[194:197], v150 offset:4096
	ds_read_b128 v[198:201], v150 offset:5120
	ds_read_b128 v[202:205], v150 offset:6144
	ds_read_b128 v[206:209], v150 offset:7168
	global_load_lds_dwordx4 v[144:145], off
	v_lshl_add_u64 v[144:145], s[24:25], 0, v[138:139]
	s_add_i32 m0, s23, 0xe000
	s_nop 0
	global_load_lds_dwordx4 v[144:145], off
	s_waitcnt lgkmcnt(8)
	ds_read_b128 v[210:213], v151
	ds_read_b128 v[214:217], v151 offset:1024
	ds_read_b128 v[218:221], v151 offset:2048
	ds_read_b128 v[222:225], v151 offset:3072
	s_waitcnt vmcnt(8) lgkmcnt(0)
	s_barrier
	v_mfma_f32_16x16x32_bf16 v[124:127], v[152:155], v[168:171], 0
	v_mfma_f32_16x16x32_bf16 v[120:123], v[160:163], v[168:171], 0
	v_mfma_f32_16x16x32_bf16 v[108:111], v[152:155], v[182:185], 0
	v_mfma_f32_16x16x32_bf16 v[104:107], v[160:163], v[182:185], 0
	v_mfma_f32_16x16x32_bf16 v[92:95], v[152:155], v[194:197], 0
	v_mfma_f32_16x16x32_bf16 v[88:91], v[160:163], v[194:197], 0
	v_mfma_f32_16x16x32_bf16 v[76:79], v[152:155], v[202:205], 0
	v_mfma_f32_16x16x32_bf16 v[72:75], v[160:163], v[202:205], 0
	v_mfma_f32_16x16x32_bf16 v[124:127], v[156:159], v[172:175], v[124:127]
	v_mfma_f32_16x16x32_bf16 v[120:123], v[164:167], v[172:175], v[120:123]
	v_mfma_f32_16x16x32_bf16 v[108:111], v[156:159], v[190:193], v[108:111]
	v_mfma_f32_16x16x32_bf16 v[104:107], v[164:167], v[190:193], v[104:107]
	v_mfma_f32_16x16x32_bf16 v[92:95], v[156:159], v[198:201], v[92:95]
	v_mfma_f32_16x16x32_bf16 v[88:91], v[164:167], v[198:201], v[88:91]
	v_mfma_f32_16x16x32_bf16 v[76:79], v[156:159], v[206:209], v[76:79]
	v_mfma_f32_16x16x32_bf16 v[72:75], v[164:167], v[206:209], v[72:75]
	v_mfma_f32_16x16x32_bf16 v[116:119], v[210:213], v[168:171], 0
	v_mfma_f32_16x16x32_bf16 v[112:115], v[218:221], v[168:171], 0
	v_mfma_f32_16x16x32_bf16 v[100:103], v[210:213], v[182:185], 0
	v_mfma_f32_16x16x32_bf16 v[96:99], v[218:221], v[182:185], 0
	v_mfma_f32_16x16x32_bf16 v[84:87], v[210:213], v[194:197], 0
	v_mfma_f32_16x16x32_bf16 v[80:83], v[218:221], v[194:197], 0
	v_mfma_f32_16x16x32_bf16 v[68:71], v[210:213], v[202:205], 0
	v_mfma_f32_16x16x32_bf16 v[64:67], v[218:221], v[202:205], 0
	v_mfma_f32_16x16x32_bf16 v[116:119], v[214:217], v[172:175], v[116:119]
	v_mfma_f32_16x16x32_bf16 v[112:115], v[222:225], v[172:175], v[112:115]
	v_mfma_f32_16x16x32_bf16 v[100:103], v[214:217], v[190:193], v[100:103]
	v_mfma_f32_16x16x32_bf16 v[96:99], v[222:225], v[190:193], v[96:99]
	v_mfma_f32_16x16x32_bf16 v[84:87], v[214:217], v[198:201], v[84:87]
	v_mfma_f32_16x16x32_bf16 v[80:83], v[222:225], v[198:201], v[80:83]
	v_mfma_f32_16x16x32_bf16 v[68:71], v[214:217], v[206:209], v[68:71]
	v_mfma_f32_16x16x32_bf16 v[64:67], v[222:225], v[206:209], v[64:67]
	s_barrier
	ds_read_b128 v[168:171], v150 offset:16384
	ds_read_b128 v[172:175], v150 offset:17408
	ds_read_b128 v[182:185], v150 offset:18432
	ds_read_b128 v[190:193], v150 offset:19456
	ds_read_b128 v[194:197], v150 offset:20480
	ds_read_b128 v[198:201], v150 offset:21504
	ds_read_b128 v[202:205], v150 offset:22528
	ds_read_b128 v[206:209], v150 offset:23552
	s_add_i32 s57, s45, s37
	v_lshl_add_u64 v[144:145], s[26:27], 0, v[130:131]
	s_mov_b32 m0, s57
	s_nop 0
	global_load_lds_dwordx4 v[144:145], off
	v_lshl_add_u64 v[186:187], s[26:27], 0, v[134:135]
	s_add_i32 m0, s57, 0x2000
	s_nop 0
	global_load_lds_dwordx4 v[186:187], off
	s_nop 1
	s_mov_b32 m0, s23
	v_lshl_add_u64 v[226:227], s[28:29], 0, v[128:129]
	global_load_lds_dwordx4 v[226:227], off
	v_lshl_add_u64 v[228:229], s[28:29], 0, v[132:133]
	s_mov_b32 m0, s38
	s_nop 0
	global_load_lds_dwordx4 v[228:229], off
	s_add_u32 s58, s26, 0x40000
	s_addc_u32 s59, s27, 0
	s_add_i32 s57, s46, s37
	v_lshl_add_u64 v[246:247], s[58:59], 0, v[130:131]
	s_mov_b32 m0, s57
	s_nop 0
	global_load_lds_dwordx4 v[246:247], off
	v_lshl_add_u64 v[246:247], s[58:59], 0, v[134:135]
	s_add_i32 m0, s57, 0x2000
	s_nop 0
	global_load_lds_dwordx4 v[246:247], off
	s_waitcnt vmcnt(8) lgkmcnt(0)
	s_barrier
; #define PG8_STAGE(bufoff, gbase, voff) do { _Pragma("unroll") for (int _i = 0; _i < 2; ++_i) \
;         __builtin_amdgcn_global_load_lds((const unsigned*)((const char*)(gbase) + (voff)[_i]), (PG8_LAS unsigned*)(lds + (bufoff) + ldsw + _i * 8192), 16, 0, 0); } while (0)
; #define PG8_LDA(dst, b, h) do { _Pragma("unroll") for (int m = 0; m < 4; ++m) _Pragma("unroll") for (int k = 0; k < 2; ++k) dst[m][k] = *(const PG8_LAS bf16x8*)(lds + PG8_SA(b, h) + aoff + m * 2048 + k * 1024); } while (0)
; #define PG8_LDB(dst, b, h) do { _Pragma("unroll") for (int n = 0; n < 2; ++n) _Pragma("unroll") for (int k = 0; k < 2; ++k) dst[n][k] = *(const PG8_LAS bf16x8*)(lds + PG8_SB(b, h) + boff + n * 2048 + k * 1024); } while (0)
; #define PG8_MMA(ai, bj, At, Bt) do { __builtin_amdgcn_s_setprio(1); _Pragma("unroll") for (int m = 0; m < 4; ++m) _Pragma("unroll") for (int n = 0; n < 2; ++n) _Pragma("unroll") for (int k = 0; k < 2; ++k) \
;         acc[ai][bj][m][n] = __builtin_amdgcn_mfma_f32_16x16x32_bf16(Bt[n][k], At[m][k], acc[ai][bj][m][n], 0, 0, 0); __builtin_amdgcn_s_setprio(0); } while (0)
; #define PG8_WAIT_V(n) asm volatile("s_waitcnt vmcnt(" #n ")" ::: "memory")
; #define PG8_WAIT_L(n) asm volatile("s_waitcnt lgkmcnt(" #n ")" ::: "memory")
; #define PG8_BAR __builtin_amdgcn_s_barrier()
; #define PG8_SCHED __builtin_amdgcn_sched_barrier(0)
; template <class Epi, class Sched>
; __device__ __forceinline__ void gemm_phase(PG8_LAS unsigned char* lds, const Gemm g, const Sched& S, const Epi& E) {
;     ...
;             PG8_BAR; PG8_WAIT_L(0); PG8_MMA(1, 0, At, B0); PG8_BAR; PG8_SCHED;
;             PG8_STAGE(PG8_SB(0, 1), b2 + hstep, voffB);
;             PG8_WAIT_V(6); PG8_BAR; PG8_MMA(1, 1, At, B1); PG8_BAR;
;             PG8_LDB(B0, 1, 0); PG8_SCHED; PG8_LDA(At, 1, 0); PG8_STAGE(PG8_SA(0, 1), a2 + hstep, voffA);
;             PG8_WAIT_L(8); PG8_BAR; PG8_WAIT_L(0); PG8_MMA(0, 0, At, B0); PG8_BAR; PG8_SCHED;
;             PG8_LDB(B1, 1, 1); PG8_STAGE(PG8_SB(1, 0), b3, voffB);
;             PG8_BAR; PG8_WAIT_L(0); PG8_MMA(0, 1, At, B1); PG8_BAR;
	v_mfma_f32_16x16x32_bf16 v[60:63], v[152:155], v[168:171], 0
	v_mfma_f32_16x16x32_bf16 v[56:59], v[160:163], v[168:171], 0
	v_mfma_f32_16x16x32_bf16 v[48:51], v[152:155], v[182:185], 0
	v_mfma_f32_16x16x32_bf16 v[40:43], v[160:163], v[182:185], 0
	v_mfma_f32_16x16x32_bf16 v[32:35], v[152:155], v[194:197], 0
	v_mfma_f32_16x16x32_bf16 v[24:27], v[160:163], v[194:197], 0
	v_mfma_f32_16x16x32_bf16 v[16:19], v[152:155], v[202:205], 0
	v_mfma_f32_16x16x32_bf16 v[8:11], v[160:163], v[202:205], 0
	v_mfma_f32_16x16x32_bf16 v[60:63], v[156:159], v[172:175], v[60:63]
	v_mfma_f32_16x16x32_bf16 v[56:59], v[164:167], v[172:175], v[56:59]
	v_mfma_f32_16x16x32_bf16 v[48:51], v[156:159], v[190:193], v[48:51]
	v_mfma_f32_16x16x32_bf16 v[40:43], v[164:167], v[190:193], v[40:43]
	v_mfma_f32_16x16x32_bf16 v[32:35], v[156:159], v[198:201], v[32:35]
	v_mfma_f32_16x16x32_bf16 v[24:27], v[164:167], v[198:201], v[24:27]
	v_mfma_f32_16x16x32_bf16 v[16:19], v[156:159], v[206:209], v[16:19]
	v_mfma_f32_16x16x32_bf16 v[8:11], v[164:167], v[206:209], v[8:11]
	v_mfma_f32_16x16x32_bf16 v[52:55], v[210:213], v[168:171], 0
	v_mfma_f32_16x16x32_bf16 v[44:47], v[218:221], v[168:171], 0
	v_mfma_f32_16x16x32_bf16 v[36:39], v[210:213], v[182:185], 0
	v_mfma_f32_16x16x32_bf16 v[28:31], v[218:221], v[182:185], 0
	v_mfma_f32_16x16x32_bf16 v[20:23], v[210:213], v[194:197], 0
	v_mfma_f32_16x16x32_bf16 v[12:15], v[218:221], v[194:197], 0
	v_mfma_f32_16x16x32_bf16 v[4:7], v[210:213], v[202:205], 0
	v_mfma_f32_16x16x32_bf16 v[0:3], v[218:221], v[202:205], 0
	v_mfma_f32_16x16x32_bf16 v[52:55], v[214:217], v[172:175], v[52:55]
	v_mfma_f32_16x16x32_bf16 v[44:47], v[222:225], v[172:175], v[44:47]
	v_mfma_f32_16x16x32_bf16 v[36:39], v[214:217], v[190:193], v[36:39]
	v_mfma_f32_16x16x32_bf16 v[28:31], v[222:225], v[190:193], v[28:31]
	v_mfma_f32_16x16x32_bf16 v[20:23], v[214:217], v[198:201], v[20:23]
	v_mfma_f32_16x16x32_bf16 v[12:15], v[222:225], v[198:201], v[12:15]
	v_mfma_f32_16x16x32_bf16 v[4:7], v[214:217], v[206:209], v[4:7]
	v_mfma_f32_16x16x32_bf16 v[0:3], v[222:225], v[206:209], v[0:3]
	s_barrier
	s_add_i32 s57, 0, 0x18000
	v_add_u32_e32 v164, s57, v147
	ds_read_b128 v[152:155], v164
	ds_read_b128 v[156:159], v164 offset:1024
	ds_read_b128 v[160:163], v164 offset:2048
	ds_read_b128 v[164:167], v164 offset:3072
	s_add_u32 s28, s28, 0x40000
	s_addc_u32 s29, s29, 0
	s_mov_b32 m0, s39
	v_lshl_add_u64 v[210:211], s[28:29], 0, v[128:129]
	ds_read_b128 v[168:171], v150 offset:32768
	ds_read_b128 v[172:175], v150 offset:33792
	ds_read_b128 v[182:185], v150 offset:34816
	ds_read_b128 v[190:193], v150 offset:35840
	ds_read_b128 v[194:197], v150 offset:36864
	ds_read_b128 v[198:201], v150 offset:37888
	ds_read_b128 v[202:205], v150 offset:38912
	ds_read_b128 v[206:209], v150 offset:39936
	global_load_lds_dwordx4 v[210:211], off
	v_lshl_add_u64 v[210:211], s[28:29], 0, v[132:133]
	s_mov_b32 m0, s40
	s_nop 0
	global_load_lds_dwordx4 v[210:211], off
	s_add_i32 s28, 0, 0x1c000
	v_add_u32_e32 v179, s28, v147
	s_waitcnt lgkmcnt(8)
	ds_read_b128 v[210:213], v179
	ds_read_b128 v[214:217], v179 offset:1024
	ds_read_b128 v[218:221], v179 offset:2048
	ds_read_b128 v[222:225], v179 offset:3072
	s_waitcnt vmcnt(8) lgkmcnt(0)
	s_barrier
	v_mfma_f32_16x16x32_bf16 v[124:127], v[152:155], v[168:171], v[124:127]
	v_mfma_f32_16x16x32_bf16 v[120:123], v[160:163], v[168:171], v[120:123]
	v_mfma_f32_16x16x32_bf16 v[108:111], v[152:155], v[182:185], v[108:111]
	v_mfma_f32_16x16x32_bf16 v[104:107], v[160:163], v[182:185], v[104:107]
	v_mfma_f32_16x16x32_bf16 v[92:95], v[152:155], v[194:197], v[92:95]
	v_mfma_f32_16x16x32_bf16 v[88:91], v[160:163], v[194:197], v[88:91]
	v_mfma_f32_16x16x32_bf16 v[76:79], v[152:155], v[202:205], v[76:79]
	v_mfma_f32_16x16x32_bf16 v[72:75], v[160:163], v[202:205], v[72:75]
	v_mfma_f32_16x16x32_bf16 v[124:127], v[156:159], v[172:175], v[124:127]
	v_mfma_f32_16x16x32_bf16 v[120:123], v[164:167], v[172:175], v[120:123]
	v_mfma_f32_16x16x32_bf16 v[108:111], v[156:159], v[190:193], v[108:111]
	v_mfma_f32_16x16x32_bf16 v[104:107], v[164:167], v[190:193], v[104:107]
	v_mfma_f32_16x16x32_bf16 v[92:95], v[156:159], v[198:201], v[92:95]
	v_mfma_f32_16x16x32_bf16 v[88:91], v[164:167], v[198:201], v[88:91]
	v_mfma_f32_16x16x32_bf16 v[76:79], v[156:159], v[206:209], v[76:79]
	v_mfma_f32_16x16x32_bf16 v[72:75], v[164:167], v[206:209], v[72:75]
	v_mfma_f32_16x16x32_bf16 v[116:119], v[210:213], v[168:171], v[116:119]
	v_mfma_f32_16x16x32_bf16 v[112:115], v[218:221], v[168:171], v[112:115]
	v_mfma_f32_16x16x32_bf16 v[100:103], v[210:213], v[182:185], v[100:103]
	v_mfma_f32_16x16x32_bf16 v[96:99], v[218:221], v[182:185], v[96:99]
	v_mfma_f32_16x16x32_bf16 v[84:87], v[210:213], v[194:197], v[84:87]
	v_mfma_f32_16x16x32_bf16 v[80:83], v[218:221], v[194:197], v[80:83]
	v_mfma_f32_16x16x32_bf16 v[68:71], v[210:213], v[202:205], v[68:71]
	v_mfma_f32_16x16x32_bf16 v[64:67], v[218:221], v[202:205], v[64:67]
	v_mfma_f32_16x16x32_bf16 v[116:119], v[214:217], v[172:175], v[116:119]
	v_mfma_f32_16x16x32_bf16 v[112:115], v[222:225], v[172:175], v[112:115]
	v_mfma_f32_16x16x32_bf16 v[100:103], v[214:217], v[190:193], v[100:103]
	v_mfma_f32_16x16x32_bf16 v[96:99], v[222:225], v[190:193], v[96:99]
	v_mfma_f32_16x16x32_bf16 v[84:87], v[214:217], v[198:201], v[84:87]
	v_mfma_f32_16x16x32_bf16 v[80:83], v[222:225], v[198:201], v[80:83]
	v_mfma_f32_16x16x32_bf16 v[68:71], v[214:217], v[206:209], v[68:71]
	v_mfma_f32_16x16x32_bf16 v[64:67], v[222:225], v[206:209], v[64:67]
	s_barrier
; #define PG8_STAGE(bufoff, gbase, voff) do { _Pragma("unroll") for (int _i = 0; _i < 2; ++_i) \
;         __builtin_amdgcn_global_load_lds((const unsigned*)((const char*)(gbase) + (voff)[_i]), (PG8_LAS unsigned*)(lds + (bufoff) + ldsw + _i * 8192), 16, 0, 0); } while (0)
; #define PG8_LDA(dst, b, h) do { _Pragma("unroll") for (int m = 0; m < 4; ++m) _Pragma("unroll") for (int k = 0; k < 2; ++k) dst[m][k] = *(const PG8_LAS bf16x8*)(lds + PG8_SA(b, h) + aoff + m * 2048 + k * 1024); } while (0)
; #define PG8_MMA(ai, bj, At, Bt) do { __builtin_amdgcn_s_setprio(1); _Pragma("unroll") for (int m = 0; m < 4; ++m) _Pragma("unroll") for (int n = 0; n < 2; ++n) _Pragma("unroll") for (int k = 0; k < 2; ++k) \
;         acc[ai][bj][m][n] = __builtin_amdgcn_mfma_f32_16x16x32_bf16(Bt[n][k], At[m][k], acc[ai][bj][m][n], 0, 0, 0); __builtin_amdgcn_s_setprio(0); } while (0)
; #define PG8_WAIT_V(n) asm volatile("s_waitcnt vmcnt(" #n ")" ::: "memory")
; #define PG8_WAIT_L(n) asm volatile("s_waitcnt lgkmcnt(" #n ")" ::: "memory")
; #define PG8_BAR __builtin_amdgcn_s_barrier()
; #define PG8_SCHED __builtin_amdgcn_sched_barrier(0)
; template <class Epi, class Sched>
; __device__ __forceinline__ void gemm_phase(PG8_LAS unsigned char* lds, const Gemm g, const Sched& S, const Epi& E) {
;     ...
;             PG8_LDA(At, 1, 1); PG8_STAGE(PG8_SA(1, 0), a3, voffA);
;             PG8_BAR; PG8_WAIT_L(0); PG8_MMA(1, 0, At, B0); PG8_BAR; PG8_SCHED;
;             PG8_STAGE(PG8_SB(1, 1), b3 + hstep, voffB);
;             PG8_WAIT_V(6); PG8_BAR; PG8_MMA(1, 1, At, B1); PG8_BAR;
;         }
	ds_read_b128 v[168:171], v150 offset:49152
	ds_read_b128 v[172:175], v150 offset:50176
	ds_read_b128 v[182:185], v150 offset:51200
	ds_read_b128 v[190:193], v150 offset:52224
	ds_read_b128 v[194:197], v150 offset:53248
	ds_read_b128 v[198:201], v150 offset:54272
	ds_read_b128 v[202:205], v150 offset:55296
	ds_read_b128 v[206:209], v150 offset:56320
	s_add_i32 s29, s57, s37
	v_lshl_add_u64 v[144:145], v[144:145], 0, s[6:7]
	s_mov_b32 m0, s29
	s_nop 0
	global_load_lds_dwordx4 v[144:145], off
	v_lshl_add_u64 v[144:145], v[186:187], 0, s[6:7]
	s_add_i32 m0, s29, 0x2000
	s_nop 0
	global_load_lds_dwordx4 v[144:145], off
	s_nop 1
	s_mov_b32 m0, s42
	v_lshl_add_u64 v[144:145], v[226:227], 0, s[6:7]
	global_load_lds_dwordx4 v[144:145], off
	v_lshl_add_u64 v[144:145], v[228:229], 0, s[6:7]
	s_mov_b32 m0, s43
	s_nop 0
	global_load_lds_dwordx4 v[144:145], off
	s_add_u32 s26, s26, 0x40080
	s_addc_u32 s27, s27, 0
	s_add_i32 s28, s28, s37
	v_lshl_add_u64 v[144:145], s[26:27], 0, v[130:131]
	s_mov_b32 m0, s28
	s_nop 0
	global_load_lds_dwordx4 v[144:145], off
	v_lshl_add_u64 v[144:145], s[26:27], 0, v[134:135]
	s_add_i32 m0, s28, 0x2000
	s_nop 0
	global_load_lds_dwordx4 v[144:145], off
	s_waitcnt vmcnt(8) lgkmcnt(0)
	s_barrier
	v_mfma_f32_16x16x32_bf16 v[60:63], v[152:155], v[168:171], v[60:63]
	v_mfma_f32_16x16x32_bf16 v[56:59], v[160:163], v[168:171], v[56:59]
	v_mfma_f32_16x16x32_bf16 v[48:51], v[152:155], v[182:185], v[48:51]
	v_mfma_f32_16x16x32_bf16 v[40:43], v[160:163], v[182:185], v[40:43]
	v_mfma_f32_16x16x32_bf16 v[32:35], v[152:155], v[194:197], v[32:35]
	v_mfma_f32_16x16x32_bf16 v[24:27], v[160:163], v[194:197], v[24:27]
	v_mfma_f32_16x16x32_bf16 v[16:19], v[152:155], v[202:205], v[16:19]
	v_mfma_f32_16x16x32_bf16 v[8:11], v[160:163], v[202:205], v[8:11]
	v_mfma_f32_16x16x32_bf16 v[60:63], v[156:159], v[172:175], v[60:63]
	v_mfma_f32_16x16x32_bf16 v[56:59], v[164:167], v[172:175], v[56:59]
	v_mfma_f32_16x16x32_bf16 v[48:51], v[156:159], v[190:193], v[48:51]
	v_mfma_f32_16x16x32_bf16 v[40:43], v[164:167], v[190:193], v[40:43]
	v_mfma_f32_16x16x32_bf16 v[32:35], v[156:159], v[198:201], v[32:35]
	v_mfma_f32_16x16x32_bf16 v[24:27], v[164:167], v[198:201], v[24:27]
	v_mfma_f32_16x16x32_bf16 v[16:19], v[156:159], v[206:209], v[16:19]
	v_mfma_f32_16x16x32_bf16 v[8:11], v[164:167], v[206:209], v[8:11]
	v_mfma_f32_16x16x32_bf16 v[52:55], v[210:213], v[168:171], v[52:55]
	v_mfma_f32_16x16x32_bf16 v[44:47], v[218:221], v[168:171], v[44:47]
	v_mfma_f32_16x16x32_bf16 v[36:39], v[210:213], v[182:185], v[36:39]
	v_mfma_f32_16x16x32_bf16 v[28:31], v[218:221], v[182:185], v[28:31]
	v_mfma_f32_16x16x32_bf16 v[20:23], v[210:213], v[194:197], v[20:23]
	v_mfma_f32_16x16x32_bf16 v[12:15], v[218:221], v[194:197], v[12:15]
	v_mfma_f32_16x16x32_bf16 v[4:7], v[210:213], v[202:205], v[4:7]
	v_mfma_f32_16x16x32_bf16 v[0:3], v[218:221], v[202:205], v[0:3]
	v_mfma_f32_16x16x32_bf16 v[52:55], v[214:217], v[172:175], v[52:55]
	v_mfma_f32_16x16x32_bf16 v[44:47], v[222:225], v[172:175], v[44:47]
	v_mfma_f32_16x16x32_bf16 v[36:39], v[214:217], v[190:193], v[36:39]
	v_mfma_f32_16x16x32_bf16 v[28:31], v[222:225], v[190:193], v[28:31]
	v_mfma_f32_16x16x32_bf16 v[20:23], v[214:217], v[198:201], v[20:23]
	v_mfma_f32_16x16x32_bf16 v[12:15], v[222:225], v[198:201], v[12:15]
	v_mfma_f32_16x16x32_bf16 v[4:7], v[214:217], v[206:209], v[4:7]
	v_mfma_f32_16x16x32_bf16 v[0:3], v[222:225], v[206:209], v[0:3]
	s_barrier
	s_add_i32 s56, s56, 2
	s_add_u32 s24, s24, 0x100
	s_addc_u32 s25, s25, 0
	s_add_u32 s54, s54, 0x100
	s_addc_u32 s55, s55, 0
	s_cmp_gt_u32 s56, 13

; #define PG8_STAGE(bufoff, gbase, voff) do { _Pragma("unroll") for (int _i = 0; _i < 2; ++_i) \
;         __builtin_amdgcn_global_load_lds((const unsigned*)((const char*)(gbase) + (voff)[_i]), (PG8_LAS unsigned*)(lds + (bufoff) + ldsw + _i * 8192), 16, 0, 0); } while (0)
; #define PG8_LDA(dst, b, h) do { _Pragma("unroll") for (int m = 0; m < 4; ++m) _Pragma("unroll") for (int k = 0; k < 2; ++k) dst[m][k] = *(const PG8_LAS bf16x8*)(lds + PG8_SA(b, h) + aoff + m * 2048 + k * 1024); } while (0)
; #define PG8_LDB(dst, b, h) do { _Pragma("unroll") for (int n = 0; n < 2; ++n) _Pragma("unroll") for (int k = 0; k < 2; ++k) dst[n][k] = *(const PG8_LAS bf16x8*)(lds + PG8_SB(b, h) + boff + n * 2048 + k * 1024); } while (0)
; template <class Epi, class Sched>
; __device__ __forceinline__ void gemm_phase(PG8_LAS unsigned char* lds, const Gemm g, const Sched& S, const Epi& E) {
;     ...
;         const bool has_next = S.next(ui + 1, nxt);
;         const char* nA = has_next ? (const char*)g.A + (size_t)nxt.pm * tstep : cA; const char* nB = has_next ? (const char*)g.Bt + (size_t)nxt.pn * tstep : cB;
;         for (int t = 0; t < nt; t += 2) {
;             const bool last = (t == nt - 2);
;             const char* a1 = cA + (size_t)(t + 1) * kstep;
;             const char* a2 = last ? nA : cA + (size_t)(t + 2) * kstep; const char* b2 = last ? nB : cB + (size_t)(t + 2) * kstep;
;             const char* a3 = a2 + kstep; const char* b3 = b2 + kstep;
;             if (last && has_next) S.a_ready(nxt);
;             PG8_LDB(B0, 0, 0); PG8_SCHED; PG8_LDA(At, 0, 0); PG8_STAGE(PG8_SA(1, 1), a1 + hstep, voffA);
;             PG8_WAIT_L(8); PG8_BAR; PG8_WAIT_L(0); PG8_MMA(0, 0, At, B0); PG8_BAR; PG8_SCHED;
;             PG8_LDB(B1, 0, 1); PG8_STAGE(PG8_SB(0, 0), b2, voffB);
;             PG8_BAR; PG8_WAIT_L(0); PG8_MMA(0, 1, At, B1); PG8_BAR;
;             PG8_LDA(At, 0, 1); PG8_STAGE(PG8_SA(0, 0), a2, voffA);
;             PG8_BAR; PG8_WAIT_L(0); PG8_MMA(1, 0, At, B0); PG8_BAR; PG8_SCHED;
;             PG8_STAGE(PG8_SB(0, 1), b2 + hstep, voffB);
;             PG8_WAIT_V(6); PG8_BAR; PG8_MMA(1, 1, At, B1); PG8_BAR;
;     ...
;         for (int a = 0; a < 2; ++a)
; #pragma unroll
;             for (int b = 0; b < 2; ++b)
; #pragma unroll
;                 for (int m = 0; m < 4; ++m)
; #pragma unroll
;                     for (int n = 0; n < 2; ++n) acc[a][b][m][n] = (f32x4){0.f, 0.f, 0.f, 0.f};
.LBB0_1201:
	s_ashr_i32 s9, s8, 31
	v_cmp_lt_i64_e32 vcc, s[10:11], v[140:141]
	s_lshl_b64 s[10:11], s[8:9], 19
	s_add_u32 s10, s24, s10
	s_addc_u32 s11, s25, s11
	s_and_b64 s[12:13], vcc, exec
	s_cselect_b32 s9, s11, s17
	s_cselect_b32 s42, s10, s16
	s_ashr_i32 s7, s6, 31
	s_lshl_b64 s[12:13], s[6:7], 19
	s_add_u32 s12, s84, s12
	s_addc_u32 s13, s85, s13
	s_and_b64 s[20:21], vcc, exec
	s_cselect_b32 s7, s13, s19
	s_cselect_b32 s43, s12, s18
	s_add_u32 s16, s16, 0x40080
	s_addc_u32 s17, s17, 0
	s_add_u32 s44, s18, 0x100
	s_addc_u32 s45, s19, 0
	s_mov_b32 s46, -2
	ds_read_b128 v[144:147], v151
	ds_read_b128 v[154:157], v151 offset:1024
	ds_read_b128 v[158:161], v151 offset:2048
	ds_read_b128 v[162:165], v151 offset:3072
	s_add_u32 s18, s16, 0xfffc0080
	s_addc_u32 s19, s17, -1
	s_cmp_eq_u32 s46, 12
	s_cselect_b32 s21, s9, s19
	s_cselect_b32 s20, s42, s18
	s_cselect_b32 s19, s7, s45
	s_cselect_b32 s18, s43, s44
	v_lshl_add_u64 v[174:175], s[16:17], 0, v[136:137]
	s_add_i32 m0, s15, 0xc000
	ds_read_b128 v[166:169], v152
	ds_read_b128 v[170:173], v152 offset:1024
	ds_read_b128 v[182:185], v152 offset:2048
	ds_read_b128 v[190:193], v152 offset:3072
	ds_read_b128 v[194:197], v152 offset:4096
	ds_read_b128 v[198:201], v152 offset:5120
	ds_read_b128 v[202:205], v152 offset:6144
	ds_read_b128 v[206:209], v152 offset:7168
	global_load_lds_dwordx4 v[174:175], off
	v_lshl_add_u64 v[174:175], s[16:17], 0, v[138:139]
	s_add_i32 m0, s15, 0xe000
	s_nop 0
	global_load_lds_dwordx4 v[174:175], off
	s_waitcnt lgkmcnt(8)
	ds_read_b128 v[210:213], v153
	ds_read_b128 v[214:217], v153 offset:1024
	ds_read_b128 v[218:221], v153 offset:2048
	ds_read_b128 v[222:225], v153 offset:3072
	s_waitcnt vmcnt(8) lgkmcnt(0)
	s_barrier
	v_mfma_f32_16x16x32_bf16 v[124:127], v[144:147], v[166:169], 0
	v_mfma_f32_16x16x32_bf16 v[120:123], v[158:161], v[166:169], 0
	v_mfma_f32_16x16x32_bf16 v[108:111], v[144:147], v[182:185], 0
	v_mfma_f32_16x16x32_bf16 v[104:107], v[158:161], v[182:185], 0
	v_mfma_f32_16x16x32_bf16 v[92:95], v[144:147], v[194:197], 0
	v_mfma_f32_16x16x32_bf16 v[88:91], v[158:161], v[194:197], 0
	v_mfma_f32_16x16x32_bf16 v[76:79], v[144:147], v[202:205], 0
	v_mfma_f32_16x16x32_bf16 v[72:75], v[158:161], v[202:205], 0
	v_mfma_f32_16x16x32_bf16 v[124:127], v[154:157], v[170:173], v[124:127]
	v_mfma_f32_16x16x32_bf16 v[120:123], v[162:165], v[170:173], v[120:123]
	v_mfma_f32_16x16x32_bf16 v[108:111], v[154:157], v[190:193], v[108:111]
	v_mfma_f32_16x16x32_bf16 v[104:107], v[162:165], v[190:193], v[104:107]
	v_mfma_f32_16x16x32_bf16 v[92:95], v[154:157], v[198:201], v[92:95]
	v_mfma_f32_16x16x32_bf16 v[88:91], v[162:165], v[198:201], v[88:91]
	v_mfma_f32_16x16x32_bf16 v[76:79], v[154:157], v[206:209], v[76:79]
	v_mfma_f32_16x16x32_bf16 v[72:75], v[162:165], v[206:209], v[72:75]
	v_mfma_f32_16x16x32_bf16 v[116:119], v[210:213], v[166:169], 0
	v_mfma_f32_16x16x32_bf16 v[112:115], v[218:221], v[166:169], 0
	v_mfma_f32_16x16x32_bf16 v[100:103], v[210:213], v[182:185], 0
	v_mfma_f32_16x16x32_bf16 v[96:99], v[218:221], v[182:185], 0
	v_mfma_f32_16x16x32_bf16 v[84:87], v[210:213], v[194:197], 0
	v_mfma_f32_16x16x32_bf16 v[80:83], v[218:221], v[194:197], 0
	v_mfma_f32_16x16x32_bf16 v[68:71], v[210:213], v[202:205], 0
	v_mfma_f32_16x16x32_bf16 v[64:67], v[218:221], v[202:205], 0
	v_mfma_f32_16x16x32_bf16 v[116:119], v[214:217], v[170:173], v[116:119]
	v_mfma_f32_16x16x32_bf16 v[112:115], v[222:225], v[170:173], v[112:115]
	v_mfma_f32_16x16x32_bf16 v[100:103], v[214:217], v[190:193], v[100:103]
	v_mfma_f32_16x16x32_bf16 v[96:99], v[222:225], v[190:193], v[96:99]
	v_mfma_f32_16x16x32_bf16 v[84:87], v[214:217], v[198:201], v[84:87]
	v_mfma_f32_16x16x32_bf16 v[80:83], v[222:225], v[198:201], v[80:83]
	v_mfma_f32_16x16x32_bf16 v[68:71], v[214:217], v[206:209], v[68:71]
	v_mfma_f32_16x16x32_bf16 v[64:67], v[222:225], v[206:209], v[64:67]
	s_barrier
	ds_read_b128 v[166:169], v152 offset:16384
	ds_read_b128 v[170:173], v152 offset:17408
	ds_read_b128 v[182:185], v152 offset:18432
	ds_read_b128 v[190:193], v152 offset:19456
	ds_read_b128 v[194:197], v152 offset:20480
	ds_read_b128 v[198:201], v152 offset:21504
	ds_read_b128 v[202:205], v152 offset:22528
	ds_read_b128 v[206:209], v152 offset:23552
	s_add_i32 s47, s38, s26
	v_lshl_add_u64 v[174:175], s[18:19], 0, v[132:133]
	s_mov_b32 m0, s47
	s_nop 0
	global_load_lds_dwordx4 v[174:175], off
	v_lshl_add_u64 v[186:187], s[18:19], 0, v[128:129]
	s_add_i32 m0, s47, 0x2000
	s_nop 0
	global_load_lds_dwordx4 v[186:187], off
	s_nop 1
	s_mov_b32 m0, s15
	v_lshl_add_u64 v[226:227], s[20:21], 0, v[134:135]
	global_load_lds_dwordx4 v[226:227], off
	v_lshl_add_u64 v[228:229], s[20:21], 0, v[130:131]
	s_mov_b32 m0, s29
	s_nop 0
	global_load_lds_dwordx4 v[228:229], off
	s_add_u32 s48, s18, 0x40000
	s_addc_u32 s49, s19, 0
	s_add_i32 s47, s39, s26
	v_lshl_add_u64 v[246:247], s[48:49], 0, v[132:133]
	s_mov_b32 m0, s47
	s_nop 0
	global_load_lds_dwordx4 v[246:247], off
	v_lshl_add_u64 v[246:247], s[48:49], 0, v[128:129]
	s_add_i32 m0, s47, 0x2000
	s_nop 0
	global_load_lds_dwordx4 v[246:247], off
	s_waitcnt vmcnt(8) lgkmcnt(0)
	s_barrier
; #define PG8_STAGE(bufoff, gbase, voff) do { _Pragma("unroll") for (int _i = 0; _i < 2; ++_i) \
;         __builtin_amdgcn_global_load_lds((const unsigned*)((const char*)(gbase) + (voff)[_i]), (PG8_LAS unsigned*)(lds + (bufoff) + ldsw + _i * 8192), 16, 0, 0); } while (0)
; #define PG8_LDA(dst, b, h) do { _Pragma("unroll") for (int m = 0; m < 4; ++m) _Pragma("unroll") for (int k = 0; k < 2; ++k) dst[m][k] = *(const PG8_LAS bf16x8*)(lds + PG8_SA(b, h) + aoff + m * 2048 + k * 1024); } while (0)
; #define PG8_LDB(dst, b, h) do { _Pragma("unroll") for (int n = 0; n < 2; ++n) _Pragma("unroll") for (int k = 0; k < 2; ++k) dst[n][k] = *(const PG8_LAS bf16x8*)(lds + PG8_SB(b, h) + boff + n * 2048 + k * 1024); } while (0)
; #define PG8_MMA(ai, bj, At, Bt) do { __builtin_amdgcn_s_setprio(1); _Pragma("unroll") for (int m = 0; m < 4; ++m) _Pragma("unroll") for (int n = 0; n < 2; ++n) _Pragma("unroll") for (int k = 0; k < 2; ++k) \
;         acc[ai][bj][m][n] = __builtin_amdgcn_mfma_f32_16x16x32_bf16(Bt[n][k], At[m][k], acc[ai][bj][m][n], 0, 0, 0); __builtin_amdgcn_s_setprio(0); } while (0)
; #define PG8_WAIT_V(n) asm volatile("s_waitcnt vmcnt(" #n ")" ::: "memory")
; #define PG8_WAIT_L(n) asm volatile("s_waitcnt lgkmcnt(" #n ")" ::: "memory")
; #define PG8_BAR __builtin_amdgcn_s_barrier()
; #define PG8_SCHED __builtin_amdgcn_sched_barrier(0)
; template <class Epi, class Sched>
; __device__ __forceinline__ void gemm_phase(PG8_LAS unsigned char* lds, const Gemm g, const Sched& S, const Epi& E) {
;     ...
;             PG8_BAR; PG8_WAIT_L(0); PG8_MMA(1, 0, At, B0); PG8_BAR; PG8_SCHED;
;             PG8_STAGE(PG8_SB(0, 1), b2 + hstep, voffB);
;             PG8_WAIT_V(6); PG8_BAR; PG8_MMA(1, 1, At, B1); PG8_BAR;
;             PG8_LDB(B0, 1, 0); PG8_SCHED; PG8_LDA(At, 1, 0); PG8_STAGE(PG8_SA(0, 1), a2 + hstep, voffA);
;             PG8_WAIT_L(8); PG8_BAR; PG8_WAIT_L(0); PG8_MMA(0, 0, At, B0); PG8_BAR; PG8_SCHED;
;             PG8_LDB(B1, 1, 1); PG8_STAGE(PG8_SB(1, 0), b3, voffB);
;             PG8_BAR; PG8_WAIT_L(0); PG8_MMA(0, 1, At, B1); PG8_BAR;
	v_mfma_f32_16x16x32_bf16 v[60:63], v[144:147], v[166:169], 0
	v_mfma_f32_16x16x32_bf16 v[56:59], v[158:161], v[166:169], 0
	v_mfma_f32_16x16x32_bf16 v[44:47], v[144:147], v[182:185], 0
	v_mfma_f32_16x16x32_bf16 v[40:43], v[158:161], v[182:185], 0
	v_mfma_f32_16x16x32_bf16 v[28:31], v[144:147], v[194:197], 0
	v_mfma_f32_16x16x32_bf16 v[24:27], v[158:161], v[194:197], 0
	v_mfma_f32_16x16x32_bf16 v[12:15], v[144:147], v[202:205], 0
	v_mfma_f32_16x16x32_bf16 v[8:11], v[158:161], v[202:205], 0
	v_mfma_f32_16x16x32_bf16 v[60:63], v[154:157], v[170:173], v[60:63]
	v_mfma_f32_16x16x32_bf16 v[56:59], v[162:165], v[170:173], v[56:59]
	v_mfma_f32_16x16x32_bf16 v[44:47], v[154:157], v[190:193], v[44:47]
	v_mfma_f32_16x16x32_bf16 v[40:43], v[162:165], v[190:193], v[40:43]
	v_mfma_f32_16x16x32_bf16 v[28:31], v[154:157], v[198:201], v[28:31]
	v_mfma_f32_16x16x32_bf16 v[24:27], v[162:165], v[198:201], v[24:27]
	v_mfma_f32_16x16x32_bf16 v[12:15], v[154:157], v[206:209], v[12:15]
	v_mfma_f32_16x16x32_bf16 v[8:11], v[162:165], v[206:209], v[8:11]
	v_mfma_f32_16x16x32_bf16 v[52:55], v[210:213], v[166:169], 0
	v_mfma_f32_16x16x32_bf16 v[48:51], v[218:221], v[166:169], 0
	v_mfma_f32_16x16x32_bf16 v[36:39], v[210:213], v[182:185], 0
	v_mfma_f32_16x16x32_bf16 v[32:35], v[218:221], v[182:185], 0
	v_mfma_f32_16x16x32_bf16 v[20:23], v[210:213], v[194:197], 0
	v_mfma_f32_16x16x32_bf16 v[16:19], v[218:221], v[194:197], 0
	v_mfma_f32_16x16x32_bf16 v[4:7], v[210:213], v[202:205], 0
	v_mfma_f32_16x16x32_bf16 v[0:3], v[218:221], v[202:205], 0
	v_mfma_f32_16x16x32_bf16 v[52:55], v[214:217], v[170:173], v[52:55]
	v_mfma_f32_16x16x32_bf16 v[48:51], v[222:225], v[170:173], v[48:51]
	v_mfma_f32_16x16x32_bf16 v[36:39], v[214:217], v[190:193], v[36:39]
	v_mfma_f32_16x16x32_bf16 v[32:35], v[222:225], v[190:193], v[32:35]
	v_mfma_f32_16x16x32_bf16 v[20:23], v[214:217], v[198:201], v[20:23]
	v_mfma_f32_16x16x32_bf16 v[16:19], v[222:225], v[198:201], v[16:19]
	v_mfma_f32_16x16x32_bf16 v[4:7], v[214:217], v[206:209], v[4:7]
	v_mfma_f32_16x16x32_bf16 v[0:3], v[222:225], v[206:209], v[0:3]
	s_barrier
	s_add_i32 s47, 0, 0x18000
	v_add_u32_e32 v162, s47, v149
	ds_read_b128 v[144:147], v162
	ds_read_b128 v[154:157], v162 offset:1024
	ds_read_b128 v[158:161], v162 offset:2048
	ds_read_b128 v[162:165], v162 offset:3072
	s_add_u32 s20, s20, 0x40000
	s_addc_u32 s21, s21, 0
	s_mov_b32 m0, s30
	v_lshl_add_u64 v[210:211], s[20:21], 0, v[134:135]
	ds_read_b128 v[166:169], v152 offset:32768
	ds_read_b128 v[170:173], v152 offset:33792
	ds_read_b128 v[182:185], v152 offset:34816
	ds_read_b128 v[190:193], v152 offset:35840
	ds_read_b128 v[194:197], v152 offset:36864
	ds_read_b128 v[198:201], v152 offset:37888
	ds_read_b128 v[202:205], v152 offset:38912
	ds_read_b128 v[206:209], v152 offset:39936
	global_load_lds_dwordx4 v[210:211], off
	v_lshl_add_u64 v[210:211], s[20:21], 0, v[130:131]
	s_mov_b32 m0, s31
	s_nop 0
	global_load_lds_dwordx4 v[210:211], off
	s_add_i32 s20, 0, 0x1c000
	v_add_u32_e32 v179, s20, v149
	s_waitcnt lgkmcnt(8)
	ds_read_b128 v[210:213], v179
	ds_read_b128 v[214:217], v179 offset:1024
	ds_read_b128 v[218:221], v179 offset:2048
	ds_read_b128 v[222:225], v179 offset:3072
	s_waitcnt vmcnt(8) lgkmcnt(0)
	s_barrier
	v_mfma_f32_16x16x32_bf16 v[124:127], v[144:147], v[166:169], v[124:127]
	v_mfma_f32_16x16x32_bf16 v[120:123], v[158:161], v[166:169], v[120:123]
	v_mfma_f32_16x16x32_bf16 v[108:111], v[144:147], v[182:185], v[108:111]
	v_mfma_f32_16x16x32_bf16 v[104:107], v[158:161], v[182:185], v[104:107]
	v_mfma_f32_16x16x32_bf16 v[92:95], v[144:147], v[194:197], v[92:95]
	v_mfma_f32_16x16x32_bf16 v[88:91], v[158:161], v[194:197], v[88:91]
	v_mfma_f32_16x16x32_bf16 v[76:79], v[144:147], v[202:205], v[76:79]
	v_mfma_f32_16x16x32_bf16 v[72:75], v[158:161], v[202:205], v[72:75]
	v_mfma_f32_16x16x32_bf16 v[124:127], v[154:157], v[170:173], v[124:127]
	v_mfma_f32_16x16x32_bf16 v[120:123], v[162:165], v[170:173], v[120:123]
	v_mfma_f32_16x16x32_bf16 v[108:111], v[154:157], v[190:193], v[108:111]
	v_mfma_f32_16x16x32_bf16 v[104:107], v[162:165], v[190:193], v[104:107]
	v_mfma_f32_16x16x32_bf16 v[92:95], v[154:157], v[198:201], v[92:95]
	v_mfma_f32_16x16x32_bf16 v[88:91], v[162:165], v[198:201], v[88:91]
	v_mfma_f32_16x16x32_bf16 v[76:79], v[154:157], v[206:209], v[76:79]
	v_mfma_f32_16x16x32_bf16 v[72:75], v[162:165], v[206:209], v[72:75]
	v_mfma_f32_16x16x32_bf16 v[116:119], v[210:213], v[166:169], v[116:119]
	v_mfma_f32_16x16x32_bf16 v[112:115], v[218:221], v[166:169], v[112:115]
	v_mfma_f32_16x16x32_bf16 v[100:103], v[210:213], v[182:185], v[100:103]
	v_mfma_f32_16x16x32_bf16 v[96:99], v[218:221], v[182:185], v[96:99]
	v_mfma_f32_16x16x32_bf16 v[84:87], v[210:213], v[194:197], v[84:87]
	v_mfma_f32_16x16x32_bf16 v[80:83], v[218:221], v[194:197], v[80:83]
	v_mfma_f32_16x16x32_bf16 v[68:71], v[210:213], v[202:205], v[68:71]
	v_mfma_f32_16x16x32_bf16 v[64:67], v[218:221], v[202:205], v[64:67]
	v_mfma_f32_16x16x32_bf16 v[116:119], v[214:217], v[170:173], v[116:119]
	v_mfma_f32_16x16x32_bf16 v[112:115], v[222:225], v[170:173], v[112:115]
	v_mfma_f32_16x16x32_bf16 v[100:103], v[214:217], v[190:193], v[100:103]
	v_mfma_f32_16x16x32_bf16 v[96:99], v[222:225], v[190:193], v[96:99]
	v_mfma_f32_16x16x32_bf16 v[84:87], v[214:217], v[198:201], v[84:87]
	v_mfma_f32_16x16x32_bf16 v[80:83], v[222:225], v[198:201], v[80:83]
	v_mfma_f32_16x16x32_bf16 v[68:71], v[214:217], v[206:209], v[68:71]
	v_mfma_f32_16x16x32_bf16 v[64:67], v[222:225], v[206:209], v[64:67]
	s_barrier
; #define PG8_STAGE(bufoff, gbase, voff) do { _Pragma("unroll") for (int _i = 0; _i < 2; ++_i) \
;         __builtin_amdgcn_global_load_lds((const unsigned*)((const char*)(gbase) + (voff)[_i]), (PG8_LAS unsigned*)(lds + (bufoff) + ldsw + _i * 8192), 16, 0, 0); } while (0)
; #define PG8_LDA(dst, b, h) do { _Pragma("unroll") for (int m = 0; m < 4; ++m) _Pragma("unroll") for (int k = 0; k < 2; ++k) dst[m][k] = *(const PG8_LAS bf16x8*)(lds + PG8_SA(b, h) + aoff + m * 2048 + k * 1024); } while (0)
; #define PG8_MMA(ai, bj, At, Bt) do { __builtin_amdgcn_s_setprio(1); _Pragma("unroll") for (int m = 0; m < 4; ++m) _Pragma("unroll") for (int n = 0; n < 2; ++n) _Pragma("unroll") for (int k = 0; k < 2; ++k) \
;         acc[ai][bj][m][n] = __builtin_amdgcn_mfma_f32_16x16x32_bf16(Bt[n][k], At[m][k], acc[ai][bj][m][n], 0, 0, 0); __builtin_amdgcn_s_setprio(0); } while (0)
; #define PG8_WAIT_V(n) asm volatile("s_waitcnt vmcnt(" #n ")" ::: "memory")
; #define PG8_WAIT_L(n) asm volatile("s_waitcnt lgkmcnt(" #n ")" ::: "memory")
; #define PG8_BAR __builtin_amdgcn_s_barrier()
; #define PG8_SCHED __builtin_amdgcn_sched_barrier(0)
; template <class Epi, class Sched>
; __device__ __forceinline__ void gemm_phase(PG8_LAS unsigned char* lds, const Gemm g, const Sched& S, const Epi& E) {
;     ...
;             PG8_LDA(At, 1, 1); PG8_STAGE(PG8_SA(1, 0), a3, voffA);
;             PG8_BAR; PG8_WAIT_L(0); PG8_MMA(1, 0, At, B0); PG8_BAR; PG8_SCHED;
;             PG8_STAGE(PG8_SB(1, 1), b3 + hstep, voffB);
;             PG8_WAIT_V(6); PG8_BAR; PG8_MMA(1, 1, At, B1); PG8_BAR;
;         }
	ds_read_b128 v[166:169], v152 offset:49152
	ds_read_b128 v[170:173], v152 offset:50176
	ds_read_b128 v[182:185], v152 offset:51200
	ds_read_b128 v[190:193], v152 offset:52224
	ds_read_b128 v[194:197], v152 offset:53248
	ds_read_b128 v[198:201], v152 offset:54272
	ds_read_b128 v[202:205], v152 offset:55296
	ds_read_b128 v[206:209], v152 offset:56320
	s_add_i32 s21, s47, s26
	v_lshl_add_u64 v[174:175], v[174:175], 0, s[4:5]
	s_mov_b32 m0, s21
	s_nop 0
	global_load_lds_dwordx4 v[174:175], off
	v_lshl_add_u64 v[174:175], v[186:187], 0, s[4:5]
	s_add_i32 m0, s21, 0x2000
	s_nop 0
	global_load_lds_dwordx4 v[174:175], off
	s_nop 1
	s_mov_b32 m0, s35
	v_lshl_add_u64 v[174:175], v[226:227], 0, s[4:5]
	global_load_lds_dwordx4 v[174:175], off
	v_lshl_add_u64 v[174:175], v[228:229], 0, s[4:5]
	s_mov_b32 m0, s36
	s_nop 0
	global_load_lds_dwordx4 v[174:175], off
	s_add_u32 s18, s18, 0x40080
	s_addc_u32 s19, s19, 0
	s_add_i32 s20, s20, s26
	v_lshl_add_u64 v[246:247], s[18:19], 0, v[132:133]
	s_mov_b32 m0, s20
	s_nop 0
	global_load_lds_dwordx4 v[246:247], off
	v_lshl_add_u64 v[246:247], s[18:19], 0, v[128:129]
	s_add_i32 m0, s20, 0x2000
	s_nop 0
	global_load_lds_dwordx4 v[246:247], off
	s_waitcnt vmcnt(8) lgkmcnt(0)
	s_barrier
	v_mfma_f32_16x16x32_bf16 v[60:63], v[144:147], v[166:169], v[60:63]
	v_mfma_f32_16x16x32_bf16 v[56:59], v[158:161], v[166:169], v[56:59]
	v_mfma_f32_16x16x32_bf16 v[44:47], v[144:147], v[182:185], v[44:47]
	v_mfma_f32_16x16x32_bf16 v[40:43], v[158:161], v[182:185], v[40:43]
	v_mfma_f32_16x16x32_bf16 v[28:31], v[144:147], v[194:197], v[28:31]
	v_mfma_f32_16x16x32_bf16 v[24:27], v[158:161], v[194:197], v[24:27]
	v_mfma_f32_16x16x32_bf16 v[12:15], v[144:147], v[202:205], v[12:15]
	v_mfma_f32_16x16x32_bf16 v[8:11], v[158:161], v[202:205], v[8:11]
	v_mfma_f32_16x16x32_bf16 v[60:63], v[154:157], v[170:173], v[60:63]
	v_mfma_f32_16x16x32_bf16 v[56:59], v[162:165], v[170:173], v[56:59]
	v_mfma_f32_16x16x32_bf16 v[44:47], v[154:157], v[190:193], v[44:47]
	v_mfma_f32_16x16x32_bf16 v[40:43], v[162:165], v[190:193], v[40:43]
	v_mfma_f32_16x16x32_bf16 v[28:31], v[154:157], v[198:201], v[28:31]
	v_mfma_f32_16x16x32_bf16 v[24:27], v[162:165], v[198:201], v[24:27]
	v_mfma_f32_16x16x32_bf16 v[12:15], v[154:157], v[206:209], v[12:15]
	v_mfma_f32_16x16x32_bf16 v[8:11], v[162:165], v[206:209], v[8:11]
	v_mfma_f32_16x16x32_bf16 v[52:55], v[210:213], v[166:169], v[52:55]
	v_mfma_f32_16x16x32_bf16 v[48:51], v[218:221], v[166:169], v[48:51]
	v_mfma_f32_16x16x32_bf16 v[36:39], v[210:213], v[182:185], v[36:39]
	v_mfma_f32_16x16x32_bf16 v[32:35], v[218:221], v[182:185], v[32:35]
	v_mfma_f32_16x16x32_bf16 v[20:23], v[210:213], v[194:197], v[20:23]
	v_mfma_f32_16x16x32_bf16 v[16:19], v[218:221], v[194:197], v[16:19]
	v_mfma_f32_16x16x32_bf16 v[4:7], v[210:213], v[202:205], v[4:7]
	v_mfma_f32_16x16x32_bf16 v[0:3], v[218:221], v[202:205], v[0:3]
	v_mfma_f32_16x16x32_bf16 v[52:55], v[214:217], v[170:173], v[52:55]
	v_mfma_f32_16x16x32_bf16 v[48:51], v[222:225], v[170:173], v[48:51]
	v_mfma_f32_16x16x32_bf16 v[36:39], v[214:217], v[190:193], v[36:39]
	v_mfma_f32_16x16x32_bf16 v[32:35], v[222:225], v[190:193], v[32:35]
	v_mfma_f32_16x16x32_bf16 v[20:23], v[214:217], v[198:201], v[20:23]
	v_mfma_f32_16x16x32_bf16 v[16:19], v[222:225], v[198:201], v[16:19]
	v_mfma_f32_16x16x32_bf16 v[4:7], v[214:217], v[206:209], v[4:7]
	v_mfma_f32_16x16x32_bf16 v[0:3], v[222:225], v[206:209], v[0:3]
	s_barrier
	s_add_i32 s46, s46, 2
	s_add_u32 s16, s16, 0x100
	s_addc_u32 s17, s17, 0
	s_add_u32 s44, s44, 0x100
	s_addc_u32 s45, s45, 0
	s_cmp_gt_u32 s46, 13

; #define PG8_STAGE(bufoff, gbase, voff) do { _Pragma("unroll") for (int _i = 0; _i < 2; ++_i) \
;         __builtin_amdgcn_global_load_lds((const unsigned*)((const char*)(gbase) + (voff)[_i]), (PG8_LAS unsigned*)(lds + (bufoff) + ldsw + _i * 8192), 16, 0, 0); } while (0)
; #define PG8_LDA(dst, b, h) do { _Pragma("unroll") for (int m = 0; m < 4; ++m) _Pragma("unroll") for (int k = 0; k < 2; ++k) dst[m][k] = *(const PG8_LAS bf16x8*)(lds + PG8_SA(b, h) + aoff + m * 2048 + k * 1024); } while (0)
; #define PG8_LDB(dst, b, h) do { _Pragma("unroll") for (int n = 0; n < 2; ++n) _Pragma("unroll") for (int k = 0; k < 2; ++k) dst[n][k] = *(const PG8_LAS bf16x8*)(lds + PG8_SB(b, h) + boff + n * 2048 + k * 1024); } while (0)
; #define PG8_WAIT_V(n) asm volatile("s_waitcnt vmcnt(" #n ")" ::: "memory")
; #define PG8_WAIT_L(n) asm volatile("s_waitcnt lgkmcnt(" #n ")" ::: "memory")
; #define PG8_BAR __builtin_amdgcn_s_barrier()
; #define PG8_SCHED __builtin_amdgcn_sched_barrier(0)
; template <class Epi, class Sched>
; __device__ __forceinline__ void gemm_phase(PG8_LAS unsigned char* lds, const Gemm g, const Sched& S, const Epi& E) {
;     ...
;             const bool last = (t == nt - 2);
;             const char* a1 = cA + (size_t)(t + 1) * kstep;
;             const char* a2 = last ? nA : cA + (size_t)(t + 2) * kstep; const char* b2 = last ? nB : cB + (size_t)(t + 2) * kstep;
;             const char* a3 = a2 + kstep; const char* b3 = b2 + kstep;
;             if (last && has_next) S.a_ready(nxt);
;             PG8_LDB(B0, 0, 0); PG8_SCHED; PG8_LDA(At, 0, 0); PG8_STAGE(PG8_SA(1, 1), a1 + hstep, voffA);
;             PG8_WAIT_L(8); PG8_BAR; PG8_WAIT_L(0); PG8_MMA(0, 0, At, B0); PG8_BAR; PG8_SCHED;
;             PG8_LDB(B1, 0, 1); PG8_STAGE(PG8_SB(0, 0), b2, voffB);
;             PG8_BAR; PG8_WAIT_L(0); PG8_MMA(0, 1, At, B1); PG8_BAR;
;             PG8_LDA(At, 0, 1); PG8_STAGE(PG8_SA(0, 0), a2, voffA);
;             PG8_BAR; PG8_WAIT_L(0); PG8_MMA(1, 0, At, B0); PG8_BAR; PG8_SCHED;
;             PG8_STAGE(PG8_SB(0, 1), b2 + hstep, voffB);
;             PG8_WAIT_V(6); PG8_BAR; PG8_MMA(1, 1, At, B1); PG8_BAR;
;     ...
;         for (int a = 0; a < 2; ++a)
; #pragma unroll
;             for (int b = 0; b < 2; ++b)
; #pragma unroll
;                 for (int m = 0; m < 4; ++m)
; #pragma unroll
;                     for (int n = 0; n < 2; ++n) acc[a][b][m][n] = (f32x4){0.f, 0.f, 0.f, 0.f};
.LBB0_1277:
	s_add_u32 s52, s20, 0x100
	s_addc_u32 s53, s21, 0
	s_mov_b32 s54, -2
	ds_read_b128 v[152:155], v149
	ds_read_b128 v[156:159], v149 offset:1024
	ds_read_b128 v[160:163], v149 offset:2048
	ds_read_b128 v[164:167], v149 offset:3072
	s_add_u32 s20, s18, 0x100
	s_addc_u32 s21, s19, 0
	s_cmp_eq_u32 s54, 40
	s_cselect_b32 s25, s1, s21
	s_cselect_b32 s24, s0, s20
	s_cselect_b32 s23, s5, s53
	s_cselect_b32 s22, s4, s52
	v_lshl_add_u64 v[144:145], s[18:19], 0, v[136:137]
	s_add_i32 m0, s34, 0xc000
	ds_read_b128 v[168:171], v150
	ds_read_b128 v[172:175], v150 offset:1024
	ds_read_b128 v[182:185], v150 offset:2048
	ds_read_b128 v[190:193], v150 offset:3072
	ds_read_b128 v[194:197], v150 offset:4096
	ds_read_b128 v[198:201], v150 offset:5120
	ds_read_b128 v[202:205], v150 offset:6144
	ds_read_b128 v[206:209], v150 offset:7168
	global_load_lds_dwordx4 v[144:145], off
	v_lshl_add_u64 v[144:145], s[18:19], 0, v[138:139]
	s_add_i32 m0, s34, 0xe000
	s_nop 0
	global_load_lds_dwordx4 v[144:145], off
	s_waitcnt lgkmcnt(8)
	ds_read_b128 v[210:213], v151
	ds_read_b128 v[214:217], v151 offset:1024
	ds_read_b128 v[218:221], v151 offset:2048
	ds_read_b128 v[222:225], v151 offset:3072
	s_waitcnt vmcnt(8) lgkmcnt(0)
	s_barrier
	v_mfma_f32_16x16x32_bf16 v[124:127], v[152:155], v[168:171], 0
	v_mfma_f32_16x16x32_bf16 v[120:123], v[160:163], v[168:171], 0
	v_mfma_f32_16x16x32_bf16 v[108:111], v[152:155], v[182:185], 0
	v_mfma_f32_16x16x32_bf16 v[104:107], v[160:163], v[182:185], 0
	v_mfma_f32_16x16x32_bf16 v[92:95], v[152:155], v[194:197], 0
	v_mfma_f32_16x16x32_bf16 v[88:91], v[160:163], v[194:197], 0
	v_mfma_f32_16x16x32_bf16 v[76:79], v[152:155], v[202:205], 0
	v_mfma_f32_16x16x32_bf16 v[72:75], v[160:163], v[202:205], 0
	v_mfma_f32_16x16x32_bf16 v[124:127], v[156:159], v[172:175], v[124:127]
	v_mfma_f32_16x16x32_bf16 v[120:123], v[164:167], v[172:175], v[120:123]
	v_mfma_f32_16x16x32_bf16 v[108:111], v[156:159], v[190:193], v[108:111]
	v_mfma_f32_16x16x32_bf16 v[104:107], v[164:167], v[190:193], v[104:107]
	v_mfma_f32_16x16x32_bf16 v[92:95], v[156:159], v[198:201], v[92:95]
	v_mfma_f32_16x16x32_bf16 v[88:91], v[164:167], v[198:201], v[88:91]
	v_mfma_f32_16x16x32_bf16 v[76:79], v[156:159], v[206:209], v[76:79]
	v_mfma_f32_16x16x32_bf16 v[72:75], v[164:167], v[206:209], v[72:75]
	v_mfma_f32_16x16x32_bf16 v[116:119], v[210:213], v[168:171], 0
	v_mfma_f32_16x16x32_bf16 v[112:115], v[218:221], v[168:171], 0
	v_mfma_f32_16x16x32_bf16 v[100:103], v[210:213], v[182:185], 0
	v_mfma_f32_16x16x32_bf16 v[96:99], v[218:221], v[182:185], 0
	v_mfma_f32_16x16x32_bf16 v[84:87], v[210:213], v[194:197], 0
	v_mfma_f32_16x16x32_bf16 v[80:83], v[218:221], v[194:197], 0
	v_mfma_f32_16x16x32_bf16 v[68:71], v[210:213], v[202:205], 0
	v_mfma_f32_16x16x32_bf16 v[64:67], v[218:221], v[202:205], 0
	v_mfma_f32_16x16x32_bf16 v[116:119], v[214:217], v[172:175], v[116:119]
	v_mfma_f32_16x16x32_bf16 v[112:115], v[222:225], v[172:175], v[112:115]
	v_mfma_f32_16x16x32_bf16 v[100:103], v[214:217], v[190:193], v[100:103]
	v_mfma_f32_16x16x32_bf16 v[96:99], v[222:225], v[190:193], v[96:99]
	v_mfma_f32_16x16x32_bf16 v[84:87], v[214:217], v[198:201], v[84:87]
	v_mfma_f32_16x16x32_bf16 v[80:83], v[222:225], v[198:201], v[80:83]
	v_mfma_f32_16x16x32_bf16 v[68:71], v[214:217], v[206:209], v[68:71]
	v_mfma_f32_16x16x32_bf16 v[64:67], v[222:225], v[206:209], v[64:67]
	s_barrier
	ds_read_b128 v[168:171], v150 offset:16384
	ds_read_b128 v[172:175], v150 offset:17408
	ds_read_b128 v[182:185], v150 offset:18432
	ds_read_b128 v[190:193], v150 offset:19456
	ds_read_b128 v[194:197], v150 offset:20480
	ds_read_b128 v[198:201], v150 offset:21504
	ds_read_b128 v[202:205], v150 offset:22528
	ds_read_b128 v[206:209], v150 offset:23552
	s_add_i32 s18, s42, s31
	v_lshl_add_u64 v[144:145], s[22:23], 0, v[130:131]
	s_mov_b32 m0, s18
	s_nop 0
	global_load_lds_dwordx4 v[144:145], off
	v_lshl_add_u64 v[186:187], s[22:23], 0, v[134:135]
	s_add_i32 m0, s18, 0x2000
	s_nop 0
	global_load_lds_dwordx4 v[186:187], off
	s_nop 1
	s_mov_b32 m0, s34
	v_lshl_add_u64 v[226:227], s[24:25], 0, v[128:129]
	global_load_lds_dwordx4 v[226:227], off
	v_lshl_add_u64 v[228:229], s[24:25], 0, v[132:133]
	s_mov_b32 m0, s35
	s_nop 0
	global_load_lds_dwordx4 v[228:229], off
	s_add_u32 s18, s22, 0xb0000
	s_addc_u32 s19, s23, 0
	s_add_i32 s55, s43, s31
	v_lshl_add_u64 v[246:247], s[18:19], 0, v[130:131]
	s_mov_b32 m0, s55
	s_nop 0
	global_load_lds_dwordx4 v[246:247], off
	v_lshl_add_u64 v[246:247], s[18:19], 0, v[134:135]
	s_add_i32 m0, s55, 0x2000
	s_nop 0
	global_load_lds_dwordx4 v[246:247], off
	s_waitcnt vmcnt(8) lgkmcnt(0)
	s_barrier
; #define PG8_STAGE(bufoff, gbase, voff) do { _Pragma("unroll") for (int _i = 0; _i < 2; ++_i) \
;         __builtin_amdgcn_global_load_lds((const unsigned*)((const char*)(gbase) + (voff)[_i]), (PG8_LAS unsigned*)(lds + (bufoff) + ldsw + _i * 8192), 16, 0, 0); } while (0)
; #define PG8_LDA(dst, b, h) do { _Pragma("unroll") for (int m = 0; m < 4; ++m) _Pragma("unroll") for (int k = 0; k < 2; ++k) dst[m][k] = *(const PG8_LAS bf16x8*)(lds + PG8_SA(b, h) + aoff + m * 2048 + k * 1024); } while (0)
; #define PG8_LDB(dst, b, h) do { _Pragma("unroll") for (int n = 0; n < 2; ++n) _Pragma("unroll") for (int k = 0; k < 2; ++k) dst[n][k] = *(const PG8_LAS bf16x8*)(lds + PG8_SB(b, h) + boff + n * 2048 + k * 1024); } while (0)
; #define PG8_MMA(ai, bj, At, Bt) do { __builtin_amdgcn_s_setprio(1); _Pragma("unroll") for (int m = 0; m < 4; ++m) _Pragma("unroll") for (int n = 0; n < 2; ++n) _Pragma("unroll") for (int k = 0; k < 2; ++k) \
;         acc[ai][bj][m][n] = __builtin_amdgcn_mfma_f32_16x16x32_bf16(Bt[n][k], At[m][k], acc[ai][bj][m][n], 0, 0, 0); __builtin_amdgcn_s_setprio(0); } while (0)
; #define PG8_WAIT_V(n) asm volatile("s_waitcnt vmcnt(" #n ")" ::: "memory")
; #define PG8_WAIT_L(n) asm volatile("s_waitcnt lgkmcnt(" #n ")" ::: "memory")
; #define PG8_BAR __builtin_amdgcn_s_barrier()
; #define PG8_SCHED __builtin_amdgcn_sched_barrier(0)
; template <class Epi, class Sched>
; __device__ __forceinline__ void gemm_phase(PG8_LAS unsigned char* lds, const Gemm g, const Sched& S, const Epi& E) {
;     ...
;             PG8_BAR; PG8_WAIT_L(0); PG8_MMA(1, 0, At, B0); PG8_BAR; PG8_SCHED;
;             PG8_STAGE(PG8_SB(0, 1), b2 + hstep, voffB);
;             PG8_WAIT_V(6); PG8_BAR; PG8_MMA(1, 1, At, B1); PG8_BAR;
;             PG8_LDB(B0, 1, 0); PG8_SCHED; PG8_LDA(At, 1, 0); PG8_STAGE(PG8_SA(0, 1), a2 + hstep, voffA);
;             PG8_WAIT_L(8); PG8_BAR; PG8_WAIT_L(0); PG8_MMA(0, 0, At, B0); PG8_BAR; PG8_SCHED;
;             PG8_LDB(B1, 1, 1); PG8_STAGE(PG8_SB(1, 0), b3, voffB);
;             PG8_BAR; PG8_WAIT_L(0); PG8_MMA(0, 1, At, B1); PG8_BAR;
	v_mfma_f32_16x16x32_bf16 v[60:63], v[152:155], v[168:171], 0
	v_mfma_f32_16x16x32_bf16 v[56:59], v[160:163], v[168:171], 0
	v_mfma_f32_16x16x32_bf16 v[48:51], v[152:155], v[182:185], 0
	v_mfma_f32_16x16x32_bf16 v[40:43], v[160:163], v[182:185], 0
	v_mfma_f32_16x16x32_bf16 v[32:35], v[152:155], v[194:197], 0
	v_mfma_f32_16x16x32_bf16 v[24:27], v[160:163], v[194:197], 0
	v_mfma_f32_16x16x32_bf16 v[16:19], v[152:155], v[202:205], 0
	v_mfma_f32_16x16x32_bf16 v[8:11], v[160:163], v[202:205], 0
	v_mfma_f32_16x16x32_bf16 v[60:63], v[156:159], v[172:175], v[60:63]
	v_mfma_f32_16x16x32_bf16 v[56:59], v[164:167], v[172:175], v[56:59]
	v_mfma_f32_16x16x32_bf16 v[48:51], v[156:159], v[190:193], v[48:51]
	v_mfma_f32_16x16x32_bf16 v[40:43], v[164:167], v[190:193], v[40:43]
	v_mfma_f32_16x16x32_bf16 v[32:35], v[156:159], v[198:201], v[32:35]
	v_mfma_f32_16x16x32_bf16 v[24:27], v[164:167], v[198:201], v[24:27]
	v_mfma_f32_16x16x32_bf16 v[16:19], v[156:159], v[206:209], v[16:19]
	v_mfma_f32_16x16x32_bf16 v[8:11], v[164:167], v[206:209], v[8:11]
	v_mfma_f32_16x16x32_bf16 v[52:55], v[210:213], v[168:171], 0
	v_mfma_f32_16x16x32_bf16 v[44:47], v[218:221], v[168:171], 0
	v_mfma_f32_16x16x32_bf16 v[36:39], v[210:213], v[182:185], 0
	v_mfma_f32_16x16x32_bf16 v[28:31], v[218:221], v[182:185], 0
	v_mfma_f32_16x16x32_bf16 v[20:23], v[210:213], v[194:197], 0
	v_mfma_f32_16x16x32_bf16 v[12:15], v[218:221], v[194:197], 0
	v_mfma_f32_16x16x32_bf16 v[4:7], v[210:213], v[202:205], 0
	v_mfma_f32_16x16x32_bf16 v[0:3], v[218:221], v[202:205], 0
	v_mfma_f32_16x16x32_bf16 v[52:55], v[214:217], v[172:175], v[52:55]
	v_mfma_f32_16x16x32_bf16 v[44:47], v[222:225], v[172:175], v[44:47]
	v_mfma_f32_16x16x32_bf16 v[36:39], v[214:217], v[190:193], v[36:39]
	v_mfma_f32_16x16x32_bf16 v[28:31], v[222:225], v[190:193], v[28:31]
	v_mfma_f32_16x16x32_bf16 v[20:23], v[214:217], v[198:201], v[20:23]
	v_mfma_f32_16x16x32_bf16 v[12:15], v[222:225], v[198:201], v[12:15]
	v_mfma_f32_16x16x32_bf16 v[4:7], v[214:217], v[206:209], v[4:7]
	v_mfma_f32_16x16x32_bf16 v[0:3], v[222:225], v[206:209], v[0:3]
	s_barrier
	s_add_i32 s55, 0, 0x18000
	v_add_u32_e32 v164, s55, v147
	ds_read_b128 v[152:155], v164
	ds_read_b128 v[156:159], v164 offset:1024
	ds_read_b128 v[160:163], v164 offset:2048
	ds_read_b128 v[164:167], v164 offset:3072
	s_add_u32 s18, s24, 0xb0000
	s_addc_u32 s19, s25, 0
	s_mov_b32 m0, s36
	v_lshl_add_u64 v[210:211], s[18:19], 0, v[128:129]
	ds_read_b128 v[168:171], v150 offset:32768
	ds_read_b128 v[172:175], v150 offset:33792
	ds_read_b128 v[182:185], v150 offset:34816
	ds_read_b128 v[190:193], v150 offset:35840
	ds_read_b128 v[194:197], v150 offset:36864
	ds_read_b128 v[198:201], v150 offset:37888
	ds_read_b128 v[202:205], v150 offset:38912
	ds_read_b128 v[206:209], v150 offset:39936
	global_load_lds_dwordx4 v[210:211], off
	v_lshl_add_u64 v[210:211], s[18:19], 0, v[132:133]
	s_mov_b32 m0, s37
	s_nop 0
	global_load_lds_dwordx4 v[210:211], off
	s_add_i32 s24, 0, 0x1c000
	v_add_u32_e32 v179, s24, v147
	s_waitcnt lgkmcnt(8)
	ds_read_b128 v[210:213], v179
	ds_read_b128 v[214:217], v179 offset:1024
	ds_read_b128 v[218:221], v179 offset:2048
	ds_read_b128 v[222:225], v179 offset:3072
	s_waitcnt vmcnt(8) lgkmcnt(0)
	s_barrier
	v_mfma_f32_16x16x32_bf16 v[124:127], v[152:155], v[168:171], v[124:127]
	v_mfma_f32_16x16x32_bf16 v[120:123], v[160:163], v[168:171], v[120:123]
	v_mfma_f32_16x16x32_bf16 v[108:111], v[152:155], v[182:185], v[108:111]
	v_mfma_f32_16x16x32_bf16 v[104:107], v[160:163], v[182:185], v[104:107]
	v_mfma_f32_16x16x32_bf16 v[92:95], v[152:155], v[194:197], v[92:95]
	v_mfma_f32_16x16x32_bf16 v[88:91], v[160:163], v[194:197], v[88:91]
	v_mfma_f32_16x16x32_bf16 v[76:79], v[152:155], v[202:205], v[76:79]
	v_mfma_f32_16x16x32_bf16 v[72:75], v[160:163], v[202:205], v[72:75]
	v_mfma_f32_16x16x32_bf16 v[124:127], v[156:159], v[172:175], v[124:127]
	v_mfma_f32_16x16x32_bf16 v[120:123], v[164:167], v[172:175], v[120:123]
	v_mfma_f32_16x16x32_bf16 v[108:111], v[156:159], v[190:193], v[108:111]
	v_mfma_f32_16x16x32_bf16 v[104:107], v[164:167], v[190:193], v[104:107]
	v_mfma_f32_16x16x32_bf16 v[92:95], v[156:159], v[198:201], v[92:95]
	v_mfma_f32_16x16x32_bf16 v[88:91], v[164:167], v[198:201], v[88:91]
	v_mfma_f32_16x16x32_bf16 v[76:79], v[156:159], v[206:209], v[76:79]
	v_mfma_f32_16x16x32_bf16 v[72:75], v[164:167], v[206:209], v[72:75]
	v_mfma_f32_16x16x32_bf16 v[116:119], v[210:213], v[168:171], v[116:119]
	v_mfma_f32_16x16x32_bf16 v[112:115], v[218:221], v[168:171], v[112:115]
	v_mfma_f32_16x16x32_bf16 v[100:103], v[210:213], v[182:185], v[100:103]
	v_mfma_f32_16x16x32_bf16 v[96:99], v[218:221], v[182:185], v[96:99]
	v_mfma_f32_16x16x32_bf16 v[84:87], v[210:213], v[194:197], v[84:87]
	v_mfma_f32_16x16x32_bf16 v[80:83], v[218:221], v[194:197], v[80:83]
	v_mfma_f32_16x16x32_bf16 v[68:71], v[210:213], v[202:205], v[68:71]
	v_mfma_f32_16x16x32_bf16 v[64:67], v[218:221], v[202:205], v[64:67]
	v_mfma_f32_16x16x32_bf16 v[116:119], v[214:217], v[172:175], v[116:119]
	v_mfma_f32_16x16x32_bf16 v[112:115], v[222:225], v[172:175], v[112:115]
	v_mfma_f32_16x16x32_bf16 v[100:103], v[214:217], v[190:193], v[100:103]
	v_mfma_f32_16x16x32_bf16 v[96:99], v[222:225], v[190:193], v[96:99]
	v_mfma_f32_16x16x32_bf16 v[84:87], v[214:217], v[198:201], v[84:87]
	v_mfma_f32_16x16x32_bf16 v[80:83], v[222:225], v[198:201], v[80:83]
	v_mfma_f32_16x16x32_bf16 v[68:71], v[214:217], v[206:209], v[68:71]
	v_mfma_f32_16x16x32_bf16 v[64:67], v[222:225], v[206:209], v[64:67]
	s_barrier
; #define PG8_STAGE(bufoff, gbase, voff) do { _Pragma("unroll") for (int _i = 0; _i < 2; ++_i) \
;         __builtin_amdgcn_global_load_lds((const unsigned*)((const char*)(gbase) + (voff)[_i]), (PG8_LAS unsigned*)(lds + (bufoff) + ldsw + _i * 8192), 16, 0, 0); } while (0)
; #define PG8_LDA(dst, b, h) do { _Pragma("unroll") for (int m = 0; m < 4; ++m) _Pragma("unroll") for (int k = 0; k < 2; ++k) dst[m][k] = *(const PG8_LAS bf16x8*)(lds + PG8_SA(b, h) + aoff + m * 2048 + k * 1024); } while (0)
; #define PG8_MMA(ai, bj, At, Bt) do { __builtin_amdgcn_s_setprio(1); _Pragma("unroll") for (int m = 0; m < 4; ++m) _Pragma("unroll") for (int n = 0; n < 2; ++n) _Pragma("unroll") for (int k = 0; k < 2; ++k) \
;         acc[ai][bj][m][n] = __builtin_amdgcn_mfma_f32_16x16x32_bf16(Bt[n][k], At[m][k], acc[ai][bj][m][n], 0, 0, 0); __builtin_amdgcn_s_setprio(0); } while (0)
; #define PG8_WAIT_V(n) asm volatile("s_waitcnt vmcnt(" #n ")" ::: "memory")
; #define PG8_WAIT_L(n) asm volatile("s_waitcnt lgkmcnt(" #n ")" ::: "memory")
; #define PG8_BAR __builtin_amdgcn_s_barrier()
; #define PG8_SCHED __builtin_amdgcn_sched_barrier(0)
; template <class Epi, class Sched>
; __device__ __forceinline__ void gemm_phase(PG8_LAS unsigned char* lds, const Gemm g, const Sched& S, const Epi& E) {
;     ...
;             PG8_LDA(At, 1, 1); PG8_STAGE(PG8_SA(1, 0), a3, voffA);
;             PG8_BAR; PG8_WAIT_L(0); PG8_MMA(1, 0, At, B0); PG8_BAR; PG8_SCHED;
;             PG8_STAGE(PG8_SB(1, 1), b3 + hstep, voffB);
;             PG8_WAIT_V(6); PG8_BAR; PG8_MMA(1, 1, At, B1); PG8_BAR;
;         }
	ds_read_b128 v[168:171], v150 offset:49152
	ds_read_b128 v[172:175], v150 offset:50176
	ds_read_b128 v[182:185], v150 offset:51200
	ds_read_b128 v[190:193], v150 offset:52224
	ds_read_b128 v[194:197], v150 offset:53248
	ds_read_b128 v[198:201], v150 offset:54272
	ds_read_b128 v[202:205], v150 offset:55296
	ds_read_b128 v[206:209], v150 offset:56320
	s_add_i32 s18, s55, s31
	v_lshl_add_u64 v[144:145], v[144:145], 0, s[8:9]
	s_mov_b32 m0, s18
	s_nop 0
	global_load_lds_dwordx4 v[144:145], off
	v_lshl_add_u64 v[144:145], v[186:187], 0, s[8:9]
	s_add_i32 m0, s18, 0x2000
	s_nop 0
	global_load_lds_dwordx4 v[144:145], off
	s_nop 1
	s_mov_b32 m0, s39
	v_lshl_add_u64 v[144:145], v[226:227], 0, s[8:9]
	global_load_lds_dwordx4 v[144:145], off
	v_lshl_add_u64 v[144:145], v[228:229], 0, s[8:9]
	s_mov_b32 m0, s40
	s_nop 0
	global_load_lds_dwordx4 v[144:145], off
	s_add_u32 s18, s22, 0xb0080
	s_addc_u32 s19, s23, 0
	s_add_i32 s22, s24, s31
	v_lshl_add_u64 v[144:145], s[18:19], 0, v[130:131]
	s_mov_b32 m0, s22
	s_nop 0
	global_load_lds_dwordx4 v[144:145], off
	v_lshl_add_u64 v[144:145], s[18:19], 0, v[134:135]
	s_add_i32 m0, s22, 0x2000
	s_nop 0
	global_load_lds_dwordx4 v[144:145], off
	s_waitcnt vmcnt(8) lgkmcnt(0)
	s_barrier
	v_mfma_f32_16x16x32_bf16 v[60:63], v[152:155], v[168:171], v[60:63]
	v_mfma_f32_16x16x32_bf16 v[56:59], v[160:163], v[168:171], v[56:59]
	v_mfma_f32_16x16x32_bf16 v[48:51], v[152:155], v[182:185], v[48:51]
	v_mfma_f32_16x16x32_bf16 v[40:43], v[160:163], v[182:185], v[40:43]
	v_mfma_f32_16x16x32_bf16 v[32:35], v[152:155], v[194:197], v[32:35]
	v_mfma_f32_16x16x32_bf16 v[24:27], v[160:163], v[194:197], v[24:27]
	v_mfma_f32_16x16x32_bf16 v[16:19], v[152:155], v[202:205], v[16:19]
	v_mfma_f32_16x16x32_bf16 v[8:11], v[160:163], v[202:205], v[8:11]
	v_mfma_f32_16x16x32_bf16 v[60:63], v[156:159], v[172:175], v[60:63]
	v_mfma_f32_16x16x32_bf16 v[56:59], v[164:167], v[172:175], v[56:59]
	v_mfma_f32_16x16x32_bf16 v[48:51], v[156:159], v[190:193], v[48:51]
	v_mfma_f32_16x16x32_bf16 v[40:43], v[164:167], v[190:193], v[40:43]
	v_mfma_f32_16x16x32_bf16 v[32:35], v[156:159], v[198:201], v[32:35]
	v_mfma_f32_16x16x32_bf16 v[24:27], v[164:167], v[198:201], v[24:27]
	v_mfma_f32_16x16x32_bf16 v[16:19], v[156:159], v[206:209], v[16:19]
	v_mfma_f32_16x16x32_bf16 v[8:11], v[164:167], v[206:209], v[8:11]
	v_mfma_f32_16x16x32_bf16 v[52:55], v[210:213], v[168:171], v[52:55]
	v_mfma_f32_16x16x32_bf16 v[44:47], v[218:221], v[168:171], v[44:47]
	v_mfma_f32_16x16x32_bf16 v[36:39], v[210:213], v[182:185], v[36:39]
	v_mfma_f32_16x16x32_bf16 v[28:31], v[218:221], v[182:185], v[28:31]
	v_mfma_f32_16x16x32_bf16 v[20:23], v[210:213], v[194:197], v[20:23]
	v_mfma_f32_16x16x32_bf16 v[12:15], v[218:221], v[194:197], v[12:15]
	v_mfma_f32_16x16x32_bf16 v[4:7], v[210:213], v[202:205], v[4:7]
	v_mfma_f32_16x16x32_bf16 v[0:3], v[218:221], v[202:205], v[0:3]
	v_mfma_f32_16x16x32_bf16 v[52:55], v[214:217], v[172:175], v[52:55]
	v_mfma_f32_16x16x32_bf16 v[44:47], v[222:225], v[172:175], v[44:47]
	v_mfma_f32_16x16x32_bf16 v[36:39], v[214:217], v[190:193], v[36:39]
	v_mfma_f32_16x16x32_bf16 v[28:31], v[222:225], v[190:193], v[28:31]
	v_mfma_f32_16x16x32_bf16 v[20:23], v[214:217], v[198:201], v[20:23]
	v_mfma_f32_16x16x32_bf16 v[12:15], v[222:225], v[198:201], v[12:15]
	v_mfma_f32_16x16x32_bf16 v[4:7], v[214:217], v[206:209], v[4:7]
	v_mfma_f32_16x16x32_bf16 v[0:3], v[222:225], v[206:209], v[0:3]
	s_barrier
	s_add_i32 s54, s54, 2
	s_add_u32 s52, s52, 0x100
	s_addc_u32 s53, s53, 0
	s_cmp_gt_u32 s54, 41
	s_mov_b64 s[18:19], s[20:21]
